# attention loops: workgroup barrier moved from before the PV block to after it (ds_write completion and V-fragment LDS reads now overlap the PV MFMAs)
# speedup vs baseline: 1.0305x; 1.0073x over previous
.LBB0_641:
	v_lshl_add_u64 v[178:179], v[174:175], 0, v[170:171]
	s_mov_b32 s24, 0x1894a000
	v_add_co_u32_e32 v52, vcc, s24, v178
	v_lshl_add_u64 v[56:57], v[172:173], 0, v[170:171]
	s_nop 0
	v_addc_co_u32_e32 v53, vcc, 0, v179, vcc
	s_mov_b32 s24, 0x19980000
	v_add_co_u32_e32 v176, vcc, s24, v56
	s_nop 0
	v_addc_co_u32_e32 v177, vcc, 0, v57, vcc
	global_load_dwordx4 v[52:55], v[52:53], off
	s_mul_i32 s26, s25, 0x2400
	global_load_dwordx4 v[56:59], v[176:177], off offset:512
	s_add_i32 s24, s23, -7
	s_add_i32 s27, s26, 0xffffdc00
	s_cmp_lg_u32 s25, 0
	s_cselect_b32 s27, s27, 0x9000
	v_add_u32_e32 v1, s27, v163
	ds_read_b128 v[60:63], v1 offset:36864
	ds_read_b128 v[114:117], v1 offset:36896
	ds_read_b128 v[118:121], v1 offset:41472
	ds_read_b128 v[134:137], v1 offset:41504
	ds_read_b128 v[146:149], v1 offset:36928
	ds_read_b128 v[150:153], v1 offset:36960
	ds_read_b128 v[196:199], v1 offset:41536
	ds_read_b128 v[200:203], v1 offset:41568
	s_setprio 3
	v_mov_b32_e32 v1, 0
	v_cvt_pk_bf16_f32 v204, v102, v103
	v_cvt_pk_bf16_f32 v205, v104, v105
	v_cvt_pk_bf16_f32 v206, v98, v99
	v_cvt_pk_bf16_f32 v207, v100, v101
	s_waitcnt lgkmcnt(7)
	s_nop 0
	v_mfma_f32_32x32x16_bf16 v[18:33], v[60:63], v[204:207], v[18:33]
	v_add_f32_e32 v1, v1, v102
	v_add_f32_e32 v1, v1, v103
	v_add_f32_e32 v1, v1, v104
	v_add_f32_e32 v1, v1, v105
	s_waitcnt lgkmcnt(5)
	v_mfma_f32_32x32x16_bf16 v[2:17], v[118:121], v[204:207], v[2:17]
	v_cvt_pk_bf16_f32 v60, v194, v187
	v_cvt_pk_bf16_f32 v61, v186, v185
	v_cvt_pk_bf16_f32 v62, v133, v132
	v_cvt_pk_bf16_f32 v63, v131, v130
	v_add_f32_e32 v1, v1, v98
	v_add_f32_e32 v1, v1, v99
	v_add_f32_e32 v1, v1, v100
	v_add_f32_e32 v1, v1, v101
	s_nop 0
	v_mfma_f32_32x32x16_bf16 v[18:33], v[114:117], v[60:63], v[18:33]
	v_add_f32_e32 v1, v1, v194
	v_add_f32_e32 v1, v1, v187
	v_add_f32_e32 v1, v1, v186
	v_add_f32_e32 v1, v1, v185
	s_waitcnt lgkmcnt(4)
	v_mfma_f32_32x32x16_bf16 v[2:17], v[134:137], v[60:63], v[2:17]
	v_cvt_pk_bf16_f32 v98, v129, v128
	v_cvt_pk_bf16_f32 v99, v127, v126
	v_cvt_pk_bf16_f32 v100, v125, v124
	v_cvt_pk_bf16_f32 v101, v123, v122
	v_add_f32_e32 v1, v1, v133
	v_add_f32_e32 v1, v1, v132
	v_add_f32_e32 v1, v1, v131
	v_add_f32_e32 v1, v1, v130
	s_waitcnt lgkmcnt(3)
	v_mfma_f32_32x32x16_bf16 v[18:33], v[146:149], v[98:101], v[18:33]
	v_add_f32_e32 v1, v1, v129
	v_add_f32_e32 v1, v1, v128
	v_add_f32_e32 v1, v1, v127
	v_add_f32_e32 v1, v1, v126
	s_waitcnt lgkmcnt(1)
	v_mfma_f32_32x32x16_bf16 v[2:17], v[196:199], v[98:101], v[2:17]
	v_cvt_pk_bf16_f32 v60, v109, v108
	v_cvt_pk_bf16_f32 v61, v107, v106
	v_cvt_pk_bf16_f32 v62, v113, v112
	v_cvt_pk_bf16_f32 v63, v111, v110
	v_add_f32_e32 v1, v1, v125
	v_add_f32_e32 v1, v1, v124
	v_add_f32_e32 v1, v1, v123
	v_add_f32_e32 v1, v1, v122
	s_nop 0
	v_mfma_f32_32x32x16_bf16 v[18:33], v[150:153], v[60:63], v[18:33]
	v_add_f32_e32 v1, v1, v109
	v_add_f32_e32 v1, v1, v108
	v_add_f32_e32 v1, v1, v107
	v_add_f32_e32 v1, v1, v106
	s_waitcnt lgkmcnt(0)
	v_mfma_f32_32x32x16_bf16 v[2:17], v[200:203], v[60:63], v[2:17]
	v_add_f32_e32 v1, v1, v113
	v_add_f32_e32 v1, v1, v112
	v_add_f32_e32 v1, v1, v111
	v_add_f32_e32 v1, v1, v110
	s_setprio 2
	s_waitcnt lgkmcnt(0)
	s_barrier
	ds_read_b128 v[240:243], v165 offset:18432
	ds_read_b128 v[244:247], v165 offset:23040
	ds_read_b128 v[130:133], v165 offset:18464
	ds_read_b128 v[146:149], v165 offset:23072
	s_waitcnt lgkmcnt(2)
	v_mfma_f32_32x32x16_bf16 v[114:129], v[240:243], v[158:161], v[34:49]
	v_exp_f32_e32 v185, v82
	v_exp_f32_e32 v186, v83
	v_exp_f32_e32 v187, v84
	v_exp_f32_e32 v194, v85
	v_exp_f32_e32 v195, v86
	v_exp_f32_e32 v196, v87
	v_exp_f32_e32 v197, v88
	v_exp_f32_e32 v198, v89
	s_waitcnt lgkmcnt(1)
	v_mfma_f32_32x32x16_bf16 v[98:113], v[244:247], v[158:161], v[34:49]
	v_exp_f32_e32 v199, v90
	v_exp_f32_e32 v200, v91
	v_exp_f32_e32 v201, v92
	v_exp_f32_e32 v202, v93
	v_exp_f32_e32 v134, v94
	v_exp_f32_e32 v135, v95
	v_exp_f32_e32 v136, v96
	v_exp_f32_e32 v137, v97
	v_mfma_f32_32x32x16_bf16 v[114:129], v[130:133], v[154:157], v[114:129]
	v_exp_f32_e32 v96, v66
	v_exp_f32_e32 v97, v67
	v_exp_f32_e32 v203, v68
	v_exp_f32_e32 v204, v69
	v_exp_f32_e32 v130, v70
	v_exp_f32_e32 v131, v71
	v_exp_f32_e32 v132, v72
	v_exp_f32_e32 v133, v73
	s_waitcnt lgkmcnt(0)
	v_mfma_f32_32x32x16_bf16 v[98:113], v[146:149], v[154:157], v[98:113]
	v_exp_f32_e32 v205, v74
	v_exp_f32_e32 v206, v75
	v_exp_f32_e32 v207, v76
	v_exp_f32_e32 v208, v77
	v_exp_f32_e32 v209, v78
	v_exp_f32_e32 v210, v79
	v_exp_f32_e32 v211, v80
	v_exp_f32_e32 v212, v81
	s_cmp_gt_i32 s25, 2
	s_cselect_b32 s27, -3, 2
	s_add_i32 s27, s27, s25
	v_add_u32_e32 v88, s26, v163
	s_add_i32 s26, s23, -6
	s_mulk_i32 s27, 0x2400
	s_min_u32 s26, s26, s13
	v_add_u32_e32 v51, s27, v182
	s_min_u32 s24, s24, s13
	s_lshl_b32 s92, s26, 13
	s_waitcnt vmcnt(3)
	ds_write_b128 v182, v[138:141]
	s_waitcnt vmcnt(2)
	ds_write_b128 v51, v[142:145] offset:36864
	v_add_f32_e32 v1, v50, v1
	v_lshl_add_u64 v[50:51], v[168:169], 0, s[92:93]
	s_lshl_b32 s92, s24, 7
	global_load_dwordx4 v[146:149], v[50:51], off
	v_lshl_add_u64 v[50:51], v[166:167], 0, s[92:93]
	global_load_dwordx4 v[150:153], v[50:51], off
	ds_read_b128 v[240:243], v165 offset:27648
	ds_read_b128 v[244:247], v165 offset:32256
	ds_read_b128 v[60:63], v88 offset:41472
	ds_read_b128 v[64:67], v88 offset:36864
	ds_read_b128 v[68:71], v88 offset:36896
	ds_read_b128 v[72:75], v88 offset:41504
	ds_read_b128 v[76:79], v88 offset:36928
	ds_read_b128 v[80:83], v88 offset:41536
	ds_read_b128 v[84:87], v88 offset:36960
	ds_read_b128 v[88:91], v88 offset:41568
	s_add_i32 s27, s25, 1
	s_setprio 1
	v_mov_b32_e32 v213, 0
	v_cvt_pk_bf16_f32 v92, v185, v186
	v_cvt_pk_bf16_f32 v93, v187, v194
	v_cvt_pk_bf16_f32 v94, v195, v196
	v_cvt_pk_bf16_f32 v95, v197, v198
	s_waitcnt lgkmcnt(6)
	s_nop 0
	v_mfma_f32_32x32x16_bf16 v[18:33], v[64:67], v[92:95], v[18:33]
	v_add_f32_e32 v213, v213, v185
	v_add_f32_e32 v213, v213, v186
	v_add_f32_e32 v213, v213, v187
	v_add_f32_e32 v213, v213, v194
	s_nop 0
	v_mfma_f32_32x32x16_bf16 v[2:17], v[60:63], v[92:95], v[2:17]
	v_cvt_pk_bf16_f32 v64, v199, v200
	v_cvt_pk_bf16_f32 v65, v201, v202
	v_cvt_pk_bf16_f32 v66, v134, v135
	v_cvt_pk_bf16_f32 v67, v136, v137
	v_add_f32_e32 v213, v213, v195
	v_add_f32_e32 v213, v213, v196
	v_add_f32_e32 v213, v213, v197
	v_add_f32_e32 v213, v213, v198
	s_waitcnt lgkmcnt(5)
	v_mfma_f32_32x32x16_bf16 v[18:33], v[68:71], v[64:67], v[18:33]
	v_add_f32_e32 v213, v213, v199
	v_add_f32_e32 v213, v213, v200
	v_add_f32_e32 v213, v213, v201
	v_add_f32_e32 v213, v213, v202
	s_waitcnt lgkmcnt(4)
	v_mfma_f32_32x32x16_bf16 v[2:17], v[72:75], v[64:67], v[2:17]
	v_cvt_pk_bf16_f32 v60, v96, v97
	v_cvt_pk_bf16_f32 v61, v203, v204
	v_cvt_pk_bf16_f32 v62, v130, v131
	v_cvt_pk_bf16_f32 v63, v132, v133
	v_add_f32_e32 v213, v213, v134
	v_add_f32_e32 v213, v213, v135
	v_add_f32_e32 v213, v213, v136
	v_add_f32_e32 v213, v213, v137
	s_waitcnt lgkmcnt(3)
	v_mfma_f32_32x32x16_bf16 v[18:33], v[76:79], v[60:63], v[18:33]
	v_add_f32_e32 v213, v213, v96
	v_add_f32_e32 v213, v213, v97
	v_add_f32_e32 v213, v213, v203
	v_add_f32_e32 v213, v213, v204
	s_waitcnt lgkmcnt(2)
	v_mfma_f32_32x32x16_bf16 v[2:17], v[80:83], v[60:63], v[2:17]
	v_cvt_pk_bf16_f32 v64, v205, v206
	v_cvt_pk_bf16_f32 v65, v207, v208
	v_cvt_pk_bf16_f32 v66, v209, v210
	v_cvt_pk_bf16_f32 v67, v211, v212
	v_add_f32_e32 v213, v213, v130
	v_add_f32_e32 v213, v213, v131
	v_add_f32_e32 v213, v213, v132
	v_add_f32_e32 v213, v213, v133
	s_waitcnt lgkmcnt(1)
	v_mfma_f32_32x32x16_bf16 v[18:33], v[84:87], v[64:67], v[18:33]
	v_add_f32_e32 v213, v213, v205
	v_add_f32_e32 v213, v213, v206
	v_add_f32_e32 v213, v213, v207
	v_add_f32_e32 v213, v213, v208
	s_waitcnt lgkmcnt(0)
	v_mfma_f32_32x32x16_bf16 v[2:17], v[88:91], v[64:67], v[2:17]
	v_add_f32_e32 v213, v213, v209
	v_add_f32_e32 v213, v213, v210
	v_add_f32_e32 v213, v213, v211
	v_add_f32_e32 v213, v213, v212
	s_setprio 0
	ds_read_b128 v[64:67], v165 offset:27680
	ds_read_b128 v[72:75], v165 offset:32288
	s_cmp_lg_u32 s25, 4
	s_cselect_b32 s24, s27, 0
	s_waitcnt lgkmcnt(2)
	v_mfma_f32_32x32x16_bf16 v[130:145], v[240:243], v[158:161], v[34:49]
	v_exp_f32_e32 v185, v114
	v_exp_f32_e32 v186, v115
	v_exp_f32_e32 v187, v116
	v_exp_f32_e32 v194, v117
	v_exp_f32_e32 v195, v118
	v_exp_f32_e32 v196, v119
	v_exp_f32_e32 v197, v120
	v_exp_f32_e32 v198, v121
	s_waitcnt lgkmcnt(1)
	v_mfma_f32_32x32x16_bf16 v[82:97], v[244:247], v[158:161], v[34:49]
	v_exp_f32_e32 v199, v122
	v_exp_f32_e32 v200, v123
	v_exp_f32_e32 v201, v124
	v_exp_f32_e32 v202, v125
	v_exp_f32_e32 v122, v126
	v_exp_f32_e32 v123, v127
	v_exp_f32_e32 v124, v128
	v_exp_f32_e32 v125, v129
	v_mfma_f32_32x32x16_bf16 v[130:145], v[64:67], v[154:157], v[130:145]
	v_exp_f32_e32 v126, v98
	v_exp_f32_e32 v127, v99
	v_exp_f32_e32 v128, v100
	v_exp_f32_e32 v129, v101
	v_exp_f32_e32 v203, v102
	v_exp_f32_e32 v204, v103
	v_exp_f32_e32 v205, v104
	v_exp_f32_e32 v206, v105
	s_waitcnt lgkmcnt(0)
	v_mfma_f32_32x32x16_bf16 v[82:97], v[72:75], v[154:157], v[82:97]
	v_exp_f32_e32 v102, v106
	v_exp_f32_e32 v103, v107
	v_exp_f32_e32 v104, v108
	v_exp_f32_e32 v105, v109
	v_exp_f32_e32 v106, v110
	v_exp_f32_e32 v107, v111
	v_exp_f32_e32 v108, v112
	v_exp_f32_e32 v109, v113
	s_cmp_gt_i32 s24, 2
	s_cselect_b32 s25, -3, 2
	s_add_i32 s25, s25, s24
	s_mulk_i32 s25, 0x2400
	v_add_u32_e32 v50, s25, v182
	s_add_i32 s25, s24, 1
	s_cmp_lg_u32 s24, 4
	s_cselect_b32 s24, s25, 0
	s_add_i32 s25, s23, -5
	s_min_u32 s25, s25, s13
	s_lshl_b32 s92, s25, 13
	s_waitcnt vmcnt(3)
	ds_write_b128 v182, v[52:55] offset:9216
	s_waitcnt vmcnt(2)
	ds_write_b128 v50, v[56:59] offset:36864
	v_lshl_add_u64 v[50:51], v[168:169], 0, s[92:93]
	s_lshl_b32 s92, s26, 7
	v_lshl_add_u64 v[52:53], v[166:167], 0, s[92:93]
	global_load_dwordx4 v[118:121], v[50:51], off
	global_load_dwordx4 v[114:117], v[52:53], off
	s_mul_i32 s26, s24, 0x2400
	s_add_i32 s27, s26, 0xffffdc00
	s_cmp_lg_u32 s24, 0
	s_cselect_b32 s27, s27, 0x9000
	v_add_u32_e32 v78, s27, v163
	ds_read_b128 v[50:53], v78 offset:36864
	ds_read_b128 v[54:57], v78 offset:36896
	ds_read_b128 v[58:61], v78 offset:41472
	ds_read_b128 v[62:65], v78 offset:41504
	ds_read_b128 v[66:69], v78 offset:36928
	ds_read_b128 v[70:73], v78 offset:36960
	ds_read_b128 v[74:77], v78 offset:41536
	ds_read_b128 v[78:81], v78 offset:41568
	s_setprio 3
	v_mov_b32_e32 v110, 0
	v_cvt_pk_bf16_f32 v98, v185, v186
	v_cvt_pk_bf16_f32 v99, v187, v194
	v_cvt_pk_bf16_f32 v100, v195, v196
	v_cvt_pk_bf16_f32 v101, v197, v198
	s_waitcnt lgkmcnt(7)
	s_nop 0
	v_mfma_f32_32x32x16_bf16 v[18:33], v[50:53], v[98:101], v[18:33]
	v_add_f32_e32 v110, v110, v185
	v_add_f32_e32 v110, v110, v186
	v_add_f32_e32 v110, v110, v187
	v_add_f32_e32 v110, v110, v194
	s_waitcnt lgkmcnt(5)
	v_mfma_f32_32x32x16_bf16 v[2:17], v[58:61], v[98:101], v[2:17]
	v_cvt_pk_bf16_f32 v50, v199, v200
	v_cvt_pk_bf16_f32 v51, v201, v202
	v_cvt_pk_bf16_f32 v52, v122, v123
	v_cvt_pk_bf16_f32 v53, v124, v125
	v_add_f32_e32 v110, v110, v195
	v_add_f32_e32 v110, v110, v196
	v_add_f32_e32 v110, v110, v197
	v_add_f32_e32 v110, v110, v198
	s_nop 0
	v_mfma_f32_32x32x16_bf16 v[18:33], v[54:57], v[50:53], v[18:33]
	v_add_f32_e32 v110, v110, v199
	v_add_f32_e32 v110, v110, v200
	v_add_f32_e32 v110, v110, v201
	v_add_f32_e32 v110, v110, v202
	s_waitcnt lgkmcnt(4)
	v_mfma_f32_32x32x16_bf16 v[2:17], v[62:65], v[50:53], v[2:17]
	v_cvt_pk_bf16_f32 v54, v126, v127
	v_cvt_pk_bf16_f32 v55, v128, v129
	v_cvt_pk_bf16_f32 v56, v203, v204
	v_cvt_pk_bf16_f32 v57, v205, v206
	v_add_f32_e32 v110, v110, v122
	v_add_f32_e32 v110, v110, v123
	v_add_f32_e32 v110, v110, v124
	v_add_f32_e32 v110, v110, v125
	s_waitcnt lgkmcnt(3)
	v_mfma_f32_32x32x16_bf16 v[18:33], v[66:69], v[54:57], v[18:33]
	v_add_f32_e32 v110, v110, v126
	v_add_f32_e32 v110, v110, v127
	v_add_f32_e32 v110, v110, v128
	v_add_f32_e32 v110, v110, v129
	s_waitcnt lgkmcnt(1)
	v_mfma_f32_32x32x16_bf16 v[2:17], v[74:77], v[54:57], v[2:17]
	v_cvt_pk_bf16_f32 v50, v102, v103
	v_cvt_pk_bf16_f32 v51, v104, v105
	v_cvt_pk_bf16_f32 v52, v106, v107
	v_cvt_pk_bf16_f32 v53, v108, v109
	v_add_f32_e32 v110, v110, v203
	v_add_f32_e32 v110, v110, v204
	v_add_f32_e32 v110, v110, v205
	v_add_f32_e32 v110, v110, v206
	s_nop 0
	v_mfma_f32_32x32x16_bf16 v[18:33], v[70:73], v[50:53], v[18:33]
	v_add_f32_e32 v110, v110, v102
	v_add_f32_e32 v110, v110, v103
	v_add_f32_e32 v110, v110, v104
	v_add_f32_e32 v110, v110, v105
	s_waitcnt lgkmcnt(0)
	v_mfma_f32_32x32x16_bf16 v[2:17], v[78:81], v[50:53], v[2:17]
	v_add_f32_e32 v110, v110, v106
	v_add_f32_e32 v110, v110, v107
	v_add_f32_e32 v110, v110, v108
	v_add_f32_e32 v110, v110, v109
	s_setprio 2
	s_waitcnt lgkmcnt(0)
	s_barrier
	ds_read_b128 v[240:243], v165
	ds_read_b128 v[244:247], v165 offset:4608
	ds_read_b128 v[102:105], v165 offset:32
	ds_read_b128 v[106:109], v165 offset:4640
	v_add_f32_e32 v1, v1, v213
	s_waitcnt lgkmcnt(2)
	v_mfma_f32_32x32x16_bf16 v[66:81], v[240:243], v[158:161], v[34:49]
	v_exp_f32_e32 v185, v130
	v_exp_f32_e32 v186, v131
	v_exp_f32_e32 v187, v132
	v_exp_f32_e32 v194, v133
	v_exp_f32_e32 v195, v134
	v_exp_f32_e32 v196, v135
	v_exp_f32_e32 v197, v136
	v_exp_f32_e32 v198, v137
	v_mfma_f32_32x32x16_bf16 v[50:65], v[244:247], v[158:161], v[34:49]
	v_exp_f32_e32 v134, v138
	v_exp_f32_e32 v135, v139
	v_exp_f32_e32 v136, v140
	v_exp_f32_e32 v137, v141
	v_exp_f32_e32 v138, v142
	v_exp_f32_e32 v139, v143
	v_exp_f32_e32 v140, v144
	v_exp_f32_e32 v141, v145
	s_waitcnt lgkmcnt(1)
	v_mfma_f32_32x32x16_bf16 v[66:81], v[102:105], v[154:157], v[66:81]
	v_exp_f32_e32 v142, v82
	v_exp_f32_e32 v143, v83
	v_exp_f32_e32 v144, v84
	v_exp_f32_e32 v145, v85
	v_exp_f32_e32 v199, v86
	v_exp_f32_e32 v200, v87
	v_exp_f32_e32 v201, v88
	v_exp_f32_e32 v202, v89
	s_waitcnt lgkmcnt(0)
	v_mfma_f32_32x32x16_bf16 v[50:65], v[106:109], v[154:157], v[50:65]
	v_exp_f32_e32 v203, v90
	v_exp_f32_e32 v204, v91
	v_exp_f32_e32 v205, v92
	v_exp_f32_e32 v206, v93
	v_exp_f32_e32 v207, v94
	v_exp_f32_e32 v208, v95
	v_exp_f32_e32 v209, v96
	v_exp_f32_e32 v210, v97
	s_cmp_gt_i32 s24, 2
	s_cselect_b32 s27, -3, 2
	s_add_i32 s27, s27, s24
	s_mulk_i32 s27, 0x2400
	v_add_u32_e32 v82, s27, v182
	s_mov_b32 s27, 0x18950000
	s_waitcnt vmcnt(3)
	ds_write_b128 v182, v[146:149] offset:18432
	s_waitcnt vmcnt(2)
	ds_write_b128 v82, v[150:153] offset:36864
	v_add_co_u32_e32 v82, vcc, s27, v178
	s_lshl_b32 s92, s25, 7
	s_nop 0
	v_addc_co_u32_e32 v83, vcc, 0, v179, vcc
	global_load_dwordx4 v[126:129], v[82:83], off
	v_lshl_add_u64 v[82:83], v[166:167], 0, s[92:93]
	global_load_dwordx4 v[122:125], v[82:83], off
	v_add_u32_e32 v111, s26, v163
	v_add_f32_e32 v1, v1, v110
	ds_read_b128 v[240:243], v165 offset:9216
	ds_read_b128 v[244:247], v165 offset:13824
	ds_read_b128 v[82:85], v111 offset:41472
	ds_read_b128 v[86:89], v111 offset:36864
	ds_read_b128 v[90:93], v111 offset:36896
	ds_read_b128 v[94:97], v111 offset:41504
	ds_read_b128 v[98:101], v111 offset:36928
	ds_read_b128 v[102:105], v111 offset:41536
	ds_read_b128 v[106:109], v111 offset:36960
	ds_read_b128 v[110:113], v111 offset:41568
	s_add_i32 s26, s24, 1
	s_setprio 1
	v_mov_b32_e32 v146, 0
	v_cvt_pk_bf16_f32 v130, v185, v186
	v_cvt_pk_bf16_f32 v131, v187, v194
	v_cvt_pk_bf16_f32 v132, v195, v196
	v_cvt_pk_bf16_f32 v133, v197, v198
	s_waitcnt lgkmcnt(6)
	s_nop 0
	v_mfma_f32_32x32x16_bf16 v[18:33], v[86:89], v[130:133], v[18:33]
	v_add_f32_e32 v146, v146, v185
	v_add_f32_e32 v146, v146, v186
	v_add_f32_e32 v146, v146, v187
	v_add_f32_e32 v146, v146, v194
	s_nop 0
	v_mfma_f32_32x32x16_bf16 v[2:17], v[82:85], v[130:133], v[2:17]
	v_cvt_pk_bf16_f32 v86, v134, v135
	v_cvt_pk_bf16_f32 v87, v136, v137
	v_cvt_pk_bf16_f32 v88, v138, v139
	v_cvt_pk_bf16_f32 v89, v140, v141
	v_add_f32_e32 v146, v146, v195
	v_add_f32_e32 v146, v146, v196
	v_add_f32_e32 v146, v146, v197
	v_add_f32_e32 v146, v146, v198
	s_waitcnt lgkmcnt(5)
	v_mfma_f32_32x32x16_bf16 v[18:33], v[90:93], v[86:89], v[18:33]
	v_add_f32_e32 v146, v146, v134
	v_add_f32_e32 v146, v146, v135
	v_add_f32_e32 v146, v146, v136
	v_add_f32_e32 v146, v146, v137
	s_waitcnt lgkmcnt(4)
	v_mfma_f32_32x32x16_bf16 v[2:17], v[94:97], v[86:89], v[2:17]
	v_cvt_pk_bf16_f32 v82, v142, v143
	v_cvt_pk_bf16_f32 v83, v144, v145
	v_cvt_pk_bf16_f32 v84, v199, v200
	v_cvt_pk_bf16_f32 v85, v201, v202
	v_add_f32_e32 v146, v146, v138
	v_add_f32_e32 v146, v146, v139
	v_add_f32_e32 v146, v146, v140
	v_add_f32_e32 v146, v146, v141
	s_waitcnt lgkmcnt(3)
	v_mfma_f32_32x32x16_bf16 v[18:33], v[98:101], v[82:85], v[18:33]
	v_add_f32_e32 v146, v146, v142
	v_add_f32_e32 v146, v146, v143
	v_add_f32_e32 v146, v146, v144
	v_add_f32_e32 v146, v146, v145
	s_waitcnt lgkmcnt(2)
	v_mfma_f32_32x32x16_bf16 v[2:17], v[102:105], v[82:85], v[2:17]
	v_cvt_pk_bf16_f32 v86, v203, v204
	v_cvt_pk_bf16_f32 v87, v205, v206
	v_cvt_pk_bf16_f32 v88, v207, v208
	v_cvt_pk_bf16_f32 v89, v209, v210
	v_add_f32_e32 v146, v146, v199
	v_add_f32_e32 v146, v146, v200
	v_add_f32_e32 v146, v146, v201
	v_add_f32_e32 v146, v146, v202
	s_waitcnt lgkmcnt(1)
	v_mfma_f32_32x32x16_bf16 v[18:33], v[106:109], v[86:89], v[18:33]
	v_add_f32_e32 v146, v146, v203
	v_add_f32_e32 v146, v146, v204
	v_add_f32_e32 v146, v146, v205
	v_add_f32_e32 v146, v146, v206
	s_waitcnt lgkmcnt(0)
	v_mfma_f32_32x32x16_bf16 v[2:17], v[110:113], v[86:89], v[2:17]
	v_add_f32_e32 v146, v146, v207
	v_add_f32_e32 v146, v146, v208
	v_add_f32_e32 v146, v146, v209
	v_add_f32_e32 v146, v146, v210
	s_setprio 0
	ds_read_b128 v[130:133], v165 offset:9248
	ds_read_b128 v[138:141], v165 offset:13856
	s_cmp_lg_u32 s24, 4
	s_cselect_b32 s24, s26, 0
	s_waitcnt lgkmcnt(2)
	v_mfma_f32_32x32x16_bf16 v[98:113], v[240:243], v[158:161], v[34:49]
	v_exp_f32_e32 v142, v66
	v_exp_f32_e32 v143, v67
	v_exp_f32_e32 v144, v68
	v_exp_f32_e32 v145, v69
	v_exp_f32_e32 v147, v70
	v_exp_f32_e32 v148, v71
	v_exp_f32_e32 v149, v72
	v_exp_f32_e32 v150, v73
	s_waitcnt lgkmcnt(1)
	v_mfma_f32_32x32x16_bf16 v[82:97], v[244:247], v[158:161], v[34:49]
	v_exp_f32_e32 v151, v74
	v_exp_f32_e32 v152, v75
	v_exp_f32_e32 v153, v76
	v_exp_f32_e32 v178, v77
	v_exp_f32_e32 v134, v78
	v_exp_f32_e32 v135, v79
	v_exp_f32_e32 v136, v80
	v_exp_f32_e32 v137, v81
	v_mfma_f32_32x32x16_bf16 v[98:113], v[130:133], v[154:157], v[98:113]
	v_exp_f32_e32 v179, v50
	v_exp_f32_e32 v185, v51
	v_exp_f32_e32 v186, v52
	v_exp_f32_e32 v187, v53
	v_exp_f32_e32 v194, v54
	v_exp_f32_e32 v195, v55
	v_exp_f32_e32 v196, v56
	v_exp_f32_e32 v197, v57
	s_waitcnt lgkmcnt(0)
	v_mfma_f32_32x32x16_bf16 v[82:97], v[138:141], v[154:157], v[82:97]
	v_exp_f32_e32 v198, v58
	v_exp_f32_e32 v199, v59
	v_exp_f32_e32 v200, v60
	v_exp_f32_e32 v201, v61
	v_exp_f32_e32 v138, v62
	v_exp_f32_e32 v139, v63
	v_exp_f32_e32 v140, v64
	v_exp_f32_e32 v141, v65
	s_cmp_gt_i32 s24, 2
	s_cselect_b32 s25, -3, 2
	s_add_i32 s25, s25, s24
	s_mulk_i32 s25, 0x2400
	v_add_u32_e32 v50, s25, v182
	s_add_i32 s25, s24, 1
	s_cmp_lg_u32 s24, 4
	s_cselect_b32 s25, s25, 0
	s_add_i32 s24, s23, -3
	s_min_u32 s26, s24, s13
	s_lshl_b32 s92, s26, 13
	s_waitcnt vmcnt(3)
	ds_write_b128 v182, v[118:121] offset:27648
	s_waitcnt vmcnt(2)
	ds_write_b128 v50, v[114:117] offset:36864
	v_lshl_add_u64 v[50:51], v[168:169], 0, s[92:93]
	global_load_dwordx4 v[118:121], v[50:51], off
	global_load_dwordx4 v[114:117], v[176:177], off offset:1024
	s_mul_i32 s27, s25, 0x2400
	s_add_i32 s28, s27, 0xffffdc00
	s_cmp_lg_u32 s25, 0
	s_cselect_b32 s28, s28, 0x9000
	v_add_u32_e32 v78, s28, v163
	ds_read_b128 v[50:53], v78 offset:36864
	ds_read_b128 v[54:57], v78 offset:36896
	ds_read_b128 v[58:61], v78 offset:41472
	ds_read_b128 v[62:65], v78 offset:41504
	ds_read_b128 v[66:69], v78 offset:36928
	ds_read_b128 v[70:73], v78 offset:36960
	ds_read_b128 v[74:77], v78 offset:41536
	ds_read_b128 v[78:81], v78 offset:41568
	s_setprio 3
	v_mov_b32_e32 v176, 0
	v_cvt_pk_bf16_f32 v130, v142, v143
	v_cvt_pk_bf16_f32 v131, v144, v145
	v_cvt_pk_bf16_f32 v132, v147, v148
	v_cvt_pk_bf16_f32 v133, v149, v150
	s_waitcnt lgkmcnt(7)
	s_nop 0
	v_mfma_f32_32x32x16_bf16 v[18:33], v[50:53], v[130:133], v[18:33]
	v_add_f32_e32 v176, v176, v142
	v_add_f32_e32 v176, v176, v143
	v_add_f32_e32 v176, v176, v144
	v_add_f32_e32 v176, v176, v145
	s_waitcnt lgkmcnt(5)
	v_mfma_f32_32x32x16_bf16 v[2:17], v[58:61], v[130:133], v[2:17]
	v_cvt_pk_bf16_f32 v50, v151, v152
	v_cvt_pk_bf16_f32 v51, v153, v178
	v_cvt_pk_bf16_f32 v52, v134, v135
	v_cvt_pk_bf16_f32 v53, v136, v137
	v_add_f32_e32 v176, v176, v147
	v_add_f32_e32 v176, v176, v148
	v_add_f32_e32 v176, v176, v149
	v_add_f32_e32 v176, v176, v150
	s_nop 0
	v_mfma_f32_32x32x16_bf16 v[18:33], v[54:57], v[50:53], v[18:33]
	v_add_f32_e32 v176, v176, v151
	v_add_f32_e32 v176, v176, v152
	v_add_f32_e32 v176, v176, v153
	v_add_f32_e32 v176, v176, v178
	s_waitcnt lgkmcnt(4)
	v_mfma_f32_32x32x16_bf16 v[2:17], v[62:65], v[50:53], v[2:17]
	v_cvt_pk_bf16_f32 v54, v179, v185
	v_cvt_pk_bf16_f32 v55, v186, v187
	v_cvt_pk_bf16_f32 v56, v194, v195
	v_cvt_pk_bf16_f32 v57, v196, v197
	v_add_f32_e32 v176, v176, v134
	v_add_f32_e32 v176, v176, v135
	v_add_f32_e32 v176, v176, v136
	v_add_f32_e32 v176, v176, v137
	s_waitcnt lgkmcnt(3)
	v_mfma_f32_32x32x16_bf16 v[18:33], v[66:69], v[54:57], v[18:33]
	v_add_f32_e32 v176, v176, v179
	v_add_f32_e32 v176, v176, v185
	v_add_f32_e32 v176, v176, v186
	v_add_f32_e32 v176, v176, v187
	s_waitcnt lgkmcnt(1)
	v_mfma_f32_32x32x16_bf16 v[2:17], v[74:77], v[54:57], v[2:17]
	v_cvt_pk_bf16_f32 v50, v198, v199
	v_cvt_pk_bf16_f32 v51, v200, v201
	v_cvt_pk_bf16_f32 v52, v138, v139
	v_cvt_pk_bf16_f32 v53, v140, v141
	v_add_f32_e32 v176, v176, v194
	v_add_f32_e32 v176, v176, v195
	v_add_f32_e32 v176, v176, v196
	v_add_f32_e32 v176, v176, v197
	s_nop 0
	v_mfma_f32_32x32x16_bf16 v[18:33], v[70:73], v[50:53], v[18:33]
	v_add_f32_e32 v176, v176, v198
	v_add_f32_e32 v176, v176, v199
	v_add_f32_e32 v176, v176, v200
	v_add_f32_e32 v176, v176, v201
	s_waitcnt lgkmcnt(0)
	v_mfma_f32_32x32x16_bf16 v[2:17], v[78:81], v[50:53], v[2:17]
	v_add_f32_e32 v176, v176, v138
	v_add_f32_e32 v176, v176, v139
	v_add_f32_e32 v176, v176, v140
	v_add_f32_e32 v176, v176, v141
	s_setprio 2
	s_waitcnt lgkmcnt(0)
	s_barrier
	ds_read_b128 v[240:243], v165 offset:18432
	ds_read_b128 v[244:247], v165 offset:23040
	ds_read_b128 v[134:137], v165 offset:18464
	ds_read_b128 v[138:141], v165 offset:23072
	v_add_f32_e32 v1, v1, v146
	s_waitcnt lgkmcnt(2)
	v_mfma_f32_32x32x16_bf16 v[66:81], v[240:243], v[158:161], v[34:49]
	v_exp_f32_e32 v142, v98
	v_exp_f32_e32 v143, v99
	v_exp_f32_e32 v144, v100
	v_exp_f32_e32 v145, v101
	v_exp_f32_e32 v146, v102
	v_exp_f32_e32 v147, v103
	v_exp_f32_e32 v148, v104
	v_exp_f32_e32 v149, v105
	v_mfma_f32_32x32x16_bf16 v[50:65], v[244:247], v[158:161], v[34:49]
	v_exp_f32_e32 v150, v106
	v_exp_f32_e32 v151, v107
	v_exp_f32_e32 v152, v108
	v_exp_f32_e32 v153, v109
	v_exp_f32_e32 v177, v110
	v_exp_f32_e32 v178, v111
	v_exp_f32_e32 v179, v112
	v_exp_f32_e32 v185, v113
	s_waitcnt lgkmcnt(1)
	v_mfma_f32_32x32x16_bf16 v[66:81], v[134:137], v[154:157], v[66:81]
	v_exp_f32_e32 v186, v82
	v_exp_f32_e32 v187, v83
	v_exp_f32_e32 v194, v84
	v_exp_f32_e32 v195, v85
	v_exp_f32_e32 v134, v86
	v_exp_f32_e32 v135, v87
	v_exp_f32_e32 v136, v88
	v_exp_f32_e32 v137, v89
	s_waitcnt lgkmcnt(0)
	v_mfma_f32_32x32x16_bf16 v[50:65], v[138:141], v[154:157], v[50:65]
	v_exp_f32_e32 v196, v90
	v_exp_f32_e32 v197, v91
	v_exp_f32_e32 v198, v92
	v_exp_f32_e32 v199, v93
	v_exp_f32_e32 v138, v94
	v_exp_f32_e32 v139, v95
	v_exp_f32_e32 v140, v96
	v_exp_f32_e32 v141, v97
	s_cmp_gt_i32 s25, 2
	s_cselect_b32 s28, -3, 2
	s_waitcnt vmcnt(3)
	ds_write_b128 v182, v[126:129]
	s_add_i32 s28, s28, s25
	v_add_u32_e32 v126, s27, v163
	s_add_i32 s27, s23, -2
	s_mulk_i32 s28, 0x2400
	s_min_u32 s27, s27, s13
	v_add_u32_e32 v82, s28, v182
	s_lshl_b32 s92, s27, 13
	s_waitcnt vmcnt(2)
	ds_write_b128 v82, v[122:125] offset:36864
	v_lshl_add_u64 v[82:83], v[168:169], 0, s[92:93]
	s_lshl_b32 s92, s26, 7
	global_load_dwordx4 v[98:101], v[82:83], off
	v_lshl_add_u64 v[82:83], v[166:167], 0, s[92:93]
	global_load_dwordx4 v[102:105], v[82:83], off
	ds_read_b128 v[240:243], v165 offset:27648
	ds_read_b128 v[244:247], v165 offset:32256
	ds_read_b128 v[82:85], v126 offset:41472
	ds_read_b128 v[86:89], v126 offset:36864
	ds_read_b128 v[90:93], v126 offset:36896
	ds_read_b128 v[94:97], v126 offset:41504
	ds_read_b128 v[106:109], v126 offset:36928
	ds_read_b128 v[110:113], v126 offset:41536
	ds_read_b128 v[122:125], v126 offset:36960
	ds_read_b128 v[126:129], v126 offset:41568
	v_add_f32_e32 v1, v1, v176
	s_add_i32 s28, s25, 1
	s_setprio 1
	v_mov_b32_e32 v176, 0
	v_cvt_pk_bf16_f32 v130, v142, v143
	v_cvt_pk_bf16_f32 v131, v144, v145
	v_cvt_pk_bf16_f32 v132, v146, v147
	v_cvt_pk_bf16_f32 v133, v148, v149
	s_waitcnt lgkmcnt(6)
	s_nop 0
	v_mfma_f32_32x32x16_bf16 v[18:33], v[86:89], v[130:133], v[18:33]
	v_add_f32_e32 v176, v176, v142
	v_add_f32_e32 v176, v176, v143
	v_add_f32_e32 v176, v176, v144
	v_add_f32_e32 v176, v176, v145
	s_nop 0
	v_mfma_f32_32x32x16_bf16 v[2:17], v[82:85], v[130:133], v[2:17]
	v_cvt_pk_bf16_f32 v86, v150, v151
	v_cvt_pk_bf16_f32 v87, v152, v153
	v_cvt_pk_bf16_f32 v88, v177, v178
	v_cvt_pk_bf16_f32 v89, v179, v185
	v_add_f32_e32 v176, v176, v146
	v_add_f32_e32 v176, v176, v147
	v_add_f32_e32 v176, v176, v148
	v_add_f32_e32 v176, v176, v149
	s_waitcnt lgkmcnt(5)
	v_mfma_f32_32x32x16_bf16 v[18:33], v[90:93], v[86:89], v[18:33]
	v_add_f32_e32 v176, v176, v150
	v_add_f32_e32 v176, v176, v151
	v_add_f32_e32 v176, v176, v152
	v_add_f32_e32 v176, v176, v153
	s_waitcnt lgkmcnt(4)
	v_mfma_f32_32x32x16_bf16 v[2:17], v[94:97], v[86:89], v[2:17]
	v_cvt_pk_bf16_f32 v82, v186, v187
	v_cvt_pk_bf16_f32 v83, v194, v195
	v_cvt_pk_bf16_f32 v84, v134, v135
	v_cvt_pk_bf16_f32 v85, v136, v137
	v_add_f32_e32 v176, v176, v177
	v_add_f32_e32 v176, v176, v178
	v_add_f32_e32 v176, v176, v179
	v_add_f32_e32 v176, v176, v185
	s_waitcnt lgkmcnt(3)
	v_mfma_f32_32x32x16_bf16 v[18:33], v[106:109], v[82:85], v[18:33]
	v_add_f32_e32 v176, v176, v186
	v_add_f32_e32 v176, v176, v187
	v_add_f32_e32 v176, v176, v194
	v_add_f32_e32 v176, v176, v195
	s_waitcnt lgkmcnt(2)
	v_mfma_f32_32x32x16_bf16 v[2:17], v[110:113], v[82:85], v[2:17]
	v_cvt_pk_bf16_f32 v86, v196, v197
	v_cvt_pk_bf16_f32 v87, v198, v199
	v_cvt_pk_bf16_f32 v88, v138, v139
	v_cvt_pk_bf16_f32 v89, v140, v141
	v_add_f32_e32 v176, v176, v134
	v_add_f32_e32 v176, v176, v135
	v_add_f32_e32 v176, v176, v136
	v_add_f32_e32 v176, v176, v137
	s_waitcnt lgkmcnt(1)
	v_mfma_f32_32x32x16_bf16 v[18:33], v[122:125], v[86:89], v[18:33]
	v_add_f32_e32 v176, v176, v196
	v_add_f32_e32 v176, v176, v197
	v_add_f32_e32 v176, v176, v198
	v_add_f32_e32 v176, v176, v199
	s_waitcnt lgkmcnt(0)
	v_mfma_f32_32x32x16_bf16 v[2:17], v[126:129], v[86:89], v[2:17]
	v_add_f32_e32 v176, v176, v138
	v_add_f32_e32 v176, v176, v139
	v_add_f32_e32 v176, v176, v140
	v_add_f32_e32 v176, v176, v141
	s_setprio 0
	ds_read_b128 v[106:109], v165 offset:27680
	ds_read_b128 v[122:125], v165 offset:32288
	s_cmp_lg_u32 s25, 4
	s_cselect_b32 s25, s28, 0
	s_waitcnt lgkmcnt(2)
	v_mfma_f32_32x32x16_bf16 v[138:153], v[240:243], v[158:161], v[34:49]
	v_exp_f32_e32 v126, v66
	v_exp_f32_e32 v127, v67
	v_exp_f32_e32 v128, v68
	v_exp_f32_e32 v129, v69
	v_exp_f32_e32 v130, v70
	v_exp_f32_e32 v131, v71
	v_exp_f32_e32 v132, v72
	v_exp_f32_e32 v133, v73
	s_waitcnt lgkmcnt(1)
	v_mfma_f32_32x32x16_bf16 v[82:97], v[244:247], v[158:161], v[34:49]
	v_exp_f32_e32 v134, v74
	v_exp_f32_e32 v135, v75
	v_exp_f32_e32 v136, v76
	v_exp_f32_e32 v137, v77
	v_exp_f32_e32 v177, v78
	v_exp_f32_e32 v178, v79
	v_exp_f32_e32 v179, v80
	v_exp_f32_e32 v185, v81
	v_mfma_f32_32x32x16_bf16 v[138:153], v[106:109], v[154:157], v[138:153]
	v_exp_f32_e32 v80, v50
	v_exp_f32_e32 v81, v51
	v_exp_f32_e32 v186, v52
	v_exp_f32_e32 v187, v53
	v_exp_f32_e32 v194, v54
	v_exp_f32_e32 v195, v55
	v_exp_f32_e32 v196, v56
	v_exp_f32_e32 v197, v57
	s_waitcnt lgkmcnt(0)
	v_mfma_f32_32x32x16_bf16 v[82:97], v[122:125], v[154:157], v[82:97]
	v_exp_f32_e32 v198, v58
	v_exp_f32_e32 v199, v59
	v_exp_f32_e32 v200, v60
	v_exp_f32_e32 v201, v61
	v_exp_f32_e32 v122, v62
	v_exp_f32_e32 v123, v63
	v_exp_f32_e32 v124, v64
	v_exp_f32_e32 v125, v65
	s_cmp_gt_i32 s25, 2
	s_cselect_b32 s26, -3, 2
	s_add_i32 s26, s26, s25
	s_mulk_i32 s26, 0x2400
	v_add_u32_e32 v50, s26, v182
	s_add_i32 s26, s25, 1
	s_cmp_lg_u32 s25, 4
	s_cselect_b32 s25, s26, 0
	s_add_i32 s26, s23, -1
	s_min_u32 s26, s26, s13
	s_lshl_b32 s92, s26, 13
	s_waitcnt vmcnt(3)
	ds_write_b128 v182, v[118:121] offset:9216
	s_waitcnt vmcnt(2)
	ds_write_b128 v50, v[114:117] offset:36864
	v_lshl_add_u64 v[50:51], v[168:169], 0, s[92:93]
	s_lshl_b32 s92, s27, 7
	v_lshl_add_u64 v[52:53], v[166:167], 0, s[92:93]
	global_load_dwordx4 v[56:59], v[50:51], off
	s_nop 0
	global_load_dwordx4 v[52:55], v[52:53], off
	s_mul_i32 s27, s25, 0x2400
	s_add_i32 s28, s27, 0xffffdc00
	s_cmp_lg_u32 s25, 0
	s_cselect_b32 s28, s28, 0x9000
	v_add_u32_e32 v50, s28, v163
	ds_read_b128 v[60:63], v50 offset:36864
	ds_read_b128 v[64:67], v50 offset:36896
	ds_read_b128 v[68:71], v50 offset:41472
	ds_read_b128 v[72:75], v50 offset:41504
	ds_read_b128 v[76:79], v50 offset:36928
	ds_read_b128 v[106:109], v50 offset:36960
	ds_read_b128 v[110:113], v50 offset:41536
	ds_read_b128 v[114:117], v50 offset:41568
	s_setprio 3
	v_mov_b32_e32 v50, 0
	v_cvt_pk_bf16_f32 v118, v126, v127
	v_cvt_pk_bf16_f32 v119, v128, v129
	v_cvt_pk_bf16_f32 v120, v130, v131
	v_cvt_pk_bf16_f32 v121, v132, v133
	s_waitcnt lgkmcnt(7)
	s_nop 0
	v_mfma_f32_32x32x16_bf16 v[18:33], v[60:63], v[118:121], v[18:33]
	v_add_f32_e32 v50, v50, v126
	v_add_f32_e32 v50, v50, v127
	v_add_f32_e32 v50, v50, v128
	v_add_f32_e32 v50, v50, v129
	s_waitcnt lgkmcnt(5)
	v_mfma_f32_32x32x16_bf16 v[2:17], v[68:71], v[118:121], v[2:17]
	v_cvt_pk_bf16_f32 v60, v134, v135
	v_cvt_pk_bf16_f32 v61, v136, v137
	v_cvt_pk_bf16_f32 v62, v177, v178
	v_cvt_pk_bf16_f32 v63, v179, v185
	v_add_f32_e32 v50, v50, v130
	v_add_f32_e32 v50, v50, v131
	v_add_f32_e32 v50, v50, v132
	v_add_f32_e32 v50, v50, v133
	s_nop 0
	v_mfma_f32_32x32x16_bf16 v[18:33], v[64:67], v[60:63], v[18:33]
	v_add_f32_e32 v50, v50, v134
	v_add_f32_e32 v50, v50, v135
	v_add_f32_e32 v50, v50, v136
	v_add_f32_e32 v50, v50, v137
	s_waitcnt lgkmcnt(4)
	v_mfma_f32_32x32x16_bf16 v[2:17], v[72:75], v[60:63], v[2:17]
	v_cvt_pk_bf16_f32 v64, v80, v81
	v_cvt_pk_bf16_f32 v65, v186, v187
	v_cvt_pk_bf16_f32 v66, v194, v195
	v_cvt_pk_bf16_f32 v67, v196, v197
	v_add_f32_e32 v50, v50, v177
	v_add_f32_e32 v50, v50, v178
	v_add_f32_e32 v50, v50, v179
	v_add_f32_e32 v50, v50, v185
	s_waitcnt lgkmcnt(3)
	v_mfma_f32_32x32x16_bf16 v[18:33], v[76:79], v[64:67], v[18:33]
	v_add_f32_e32 v50, v50, v80
	v_add_f32_e32 v50, v50, v81
	v_add_f32_e32 v50, v50, v186
	v_add_f32_e32 v50, v50, v187
	s_waitcnt lgkmcnt(1)
	v_mfma_f32_32x32x16_bf16 v[2:17], v[110:113], v[64:67], v[2:17]
	v_cvt_pk_bf16_f32 v60, v198, v199
	v_cvt_pk_bf16_f32 v61, v200, v201
	v_cvt_pk_bf16_f32 v62, v122, v123
	v_cvt_pk_bf16_f32 v63, v124, v125
	v_add_f32_e32 v50, v50, v194
	v_add_f32_e32 v50, v50, v195
	v_add_f32_e32 v50, v50, v196
	v_add_f32_e32 v50, v50, v197
	s_nop 0
	v_mfma_f32_32x32x16_bf16 v[18:33], v[106:109], v[60:63], v[18:33]
	v_add_f32_e32 v50, v50, v198
	v_add_f32_e32 v50, v50, v199
	v_add_f32_e32 v50, v50, v200
	v_add_f32_e32 v50, v50, v201
	s_waitcnt lgkmcnt(0)
	v_mfma_f32_32x32x16_bf16 v[2:17], v[114:117], v[60:63], v[2:17]
	v_add_f32_e32 v50, v50, v122
	v_add_f32_e32 v50, v50, v123
	v_add_f32_e32 v50, v50, v124
	v_add_f32_e32 v50, v50, v125
	s_setprio 2
	s_waitcnt lgkmcnt(0)
	s_barrier
	ds_read_b128 v[240:243], v165
	ds_read_b128 v[244:247], v165 offset:4608
	ds_read_b128 v[68:71], v165 offset:32
	ds_read_b128 v[72:75], v165 offset:4640
	v_add_f32_e32 v1, v1, v176
	s_waitcnt lgkmcnt(2)
	v_mfma_f32_32x32x16_bf16 v[122:137], v[240:243], v[158:161], v[34:49]
	v_exp_f32_e32 v176, v138
	v_exp_f32_e32 v177, v139
	v_exp_f32_e32 v178, v140
	v_exp_f32_e32 v179, v141
	v_exp_f32_e32 v185, v142
	v_exp_f32_e32 v186, v143
	v_exp_f32_e32 v187, v144
	v_exp_f32_e32 v194, v145
	v_mfma_f32_32x32x16_bf16 v[106:121], v[244:247], v[158:161], v[34:49]
	v_exp_f32_e32 v195, v146
	v_exp_f32_e32 v196, v147
	v_exp_f32_e32 v197, v148
	v_exp_f32_e32 v198, v149
	v_exp_f32_e32 v146, v150
	v_exp_f32_e32 v147, v151
	v_exp_f32_e32 v148, v152
	v_exp_f32_e32 v149, v153
	s_waitcnt lgkmcnt(1)
	v_mfma_f32_32x32x16_bf16 v[122:137], v[68:71], v[154:157], v[122:137]
	v_exp_f32_e32 v150, v82
	v_exp_f32_e32 v151, v83
	v_exp_f32_e32 v152, v84
	v_exp_f32_e32 v153, v85
	v_exp_f32_e32 v199, v86
	v_exp_f32_e32 v200, v87
	v_exp_f32_e32 v201, v88
	v_exp_f32_e32 v202, v89
	s_waitcnt lgkmcnt(0)
	v_mfma_f32_32x32x16_bf16 v[106:121], v[72:75], v[154:157], v[106:121]
	v_exp_f32_e32 v203, v90
	v_exp_f32_e32 v204, v91
	v_exp_f32_e32 v205, v92
	v_exp_f32_e32 v206, v93
	v_exp_f32_e32 v207, v94
	v_exp_f32_e32 v208, v95
	v_exp_f32_e32 v209, v96
	v_exp_f32_e32 v210, v97
	s_cmp_gt_i32 s25, 2
	s_cselect_b32 s28, -3, 2
	s_add_i32 s28, s28, s25
	s_mulk_i32 s28, 0x2400
	v_add_u32_e32 v88, s27, v163
	s_min_u32 s27, s23, s13
	v_add_u32_e32 v51, s28, v182
	s_lshl_b32 s92, s27, 13
	s_waitcnt vmcnt(3)
	ds_write_b128 v182, v[98:101] offset:18432
	s_waitcnt vmcnt(2)
	ds_write_b128 v51, v[102:105] offset:36864
	v_add_f32_e32 v1, v1, v50
	v_lshl_add_u64 v[50:51], v[168:169], 0, s[92:93]
	s_lshl_b32 s92, s26, 7
	global_load_dwordx4 v[138:141], v[50:51], off
	v_lshl_add_u64 v[50:51], v[166:167], 0, s[92:93]
	global_load_dwordx4 v[142:145], v[50:51], off
	ds_read_b128 v[240:243], v165 offset:9216
	ds_read_b128 v[244:247], v165 offset:13824
	ds_read_b128 v[60:63], v88 offset:41472
	ds_read_b128 v[64:67], v88 offset:36864
	ds_read_b128 v[68:71], v88 offset:36896
	ds_read_b128 v[72:75], v88 offset:41504
	ds_read_b128 v[76:79], v88 offset:36928
	ds_read_b128 v[80:83], v88 offset:41536
	ds_read_b128 v[84:87], v88 offset:36960
	ds_read_b128 v[88:91], v88 offset:41568
	s_setprio 1
	v_mov_b32_e32 v50, 0
	v_mov_b32_e32 v51, v122
	v_cvt_pk_bf16_f32 v92, v176, v177
	v_cvt_pk_bf16_f32 v93, v178, v179
	v_cvt_pk_bf16_f32 v94, v185, v186
	v_cvt_pk_bf16_f32 v95, v187, v194
	s_waitcnt lgkmcnt(6)
	s_nop 0
	v_mfma_f32_32x32x16_bf16 v[18:33], v[64:67], v[92:95], v[18:33]
	v_max3_f32 v51, v51, v123, v124
	v_max3_f32 v51, v51, v125, v126
	v_add_f32_e32 v50, v50, v176
	v_add_f32_e32 v50, v50, v177
	v_add_f32_e32 v50, v50, v178
	v_add_f32_e32 v50, v50, v179
	s_nop 0
	v_mfma_f32_32x32x16_bf16 v[2:17], v[60:63], v[92:95], v[2:17]
	v_cvt_pk_bf16_f32 v64, v195, v196
	v_cvt_pk_bf16_f32 v65, v197, v198
	v_cvt_pk_bf16_f32 v66, v146, v147
	v_cvt_pk_bf16_f32 v67, v148, v149
	v_max3_f32 v51, v51, v127, v128
	v_max3_f32 v51, v51, v129, v130
	v_add_f32_e32 v50, v50, v185
	v_add_f32_e32 v50, v50, v186
	v_add_f32_e32 v50, v50, v187
	v_add_f32_e32 v50, v50, v194
	s_waitcnt lgkmcnt(5)
	v_mfma_f32_32x32x16_bf16 v[18:33], v[68:71], v[64:67], v[18:33]
	v_max3_f32 v51, v51, v131, v132
	v_max3_f32 v51, v51, v133, v134
	v_add_f32_e32 v50, v50, v195
	v_add_f32_e32 v50, v50, v196
	v_add_f32_e32 v50, v50, v197
	v_add_f32_e32 v50, v50, v198
	s_waitcnt lgkmcnt(4)
	v_mfma_f32_32x32x16_bf16 v[2:17], v[72:75], v[64:67], v[2:17]
	v_cvt_pk_bf16_f32 v60, v150, v151
	v_cvt_pk_bf16_f32 v61, v152, v153
	v_cvt_pk_bf16_f32 v62, v199, v200
	v_cvt_pk_bf16_f32 v63, v201, v202
	v_max3_f32 v51, v51, v135, v136
	v_max3_f32 v51, v51, v137, v106
	v_add_f32_e32 v50, v50, v146
	v_add_f32_e32 v50, v50, v147
	v_add_f32_e32 v50, v50, v148
	v_add_f32_e32 v50, v50, v149
	s_waitcnt lgkmcnt(3)
	v_mfma_f32_32x32x16_bf16 v[18:33], v[76:79], v[60:63], v[18:33]
	v_max3_f32 v51, v51, v107, v108
	v_max3_f32 v51, v51, v109, v110
	v_add_f32_e32 v50, v50, v150
	v_add_f32_e32 v50, v50, v151
	v_add_f32_e32 v50, v50, v152
	v_add_f32_e32 v50, v50, v153
	s_waitcnt lgkmcnt(2)
	v_mfma_f32_32x32x16_bf16 v[2:17], v[80:83], v[60:63], v[2:17]
	v_cvt_pk_bf16_f32 v64, v203, v204
	v_cvt_pk_bf16_f32 v65, v205, v206
	v_cvt_pk_bf16_f32 v66, v207, v208
	v_cvt_pk_bf16_f32 v67, v209, v210
	v_max3_f32 v51, v51, v111, v112
	v_max3_f32 v51, v51, v113, v114
	v_add_f32_e32 v50, v50, v199
	v_add_f32_e32 v50, v50, v200
	v_add_f32_e32 v50, v50, v201
	v_add_f32_e32 v50, v50, v202
	s_waitcnt lgkmcnt(1)
	v_mfma_f32_32x32x16_bf16 v[18:33], v[84:87], v[64:67], v[18:33]
	v_max3_f32 v51, v51, v115, v116
	v_max3_f32 v51, v51, v117, v118
	v_add_f32_e32 v50, v50, v203
	v_add_f32_e32 v50, v50, v204
	v_add_f32_e32 v50, v50, v205
	v_add_f32_e32 v50, v50, v206
	s_waitcnt lgkmcnt(0)
	v_mfma_f32_32x32x16_bf16 v[2:17], v[88:91], v[64:67], v[2:17]
	v_max3_f32 v51, v51, v119, v120
	v_max3_f32 v51, v51, v121, v121
	v_add_f32_e32 v50, v50, v207
	v_add_f32_e32 v50, v50, v208
	v_add_f32_e32 v50, v50, v209
	v_add_f32_e32 v50, v50, v210
	s_setprio 0
	ds_read_b128 v[146:149], v165 offset:9248
	ds_read_b128 v[60:63], v165 offset:13856
	v_add_f32_e32 v50, v1, v50
	v_mov_b32_e32 v1, v51
	s_nop 1
	v_permlane32_swap_b32_e32 v51, v1
	v_max_f32_e32 v1, v1, v1
	v_max_f32_e32 v51, v51, v51
	v_max_f32_e32 v1, v51, v1
	v_cmp_lt_f32_e32 vcc, s52, v1
	s_cbranch_vccz .LBB0_643
	v_max_f32_e32 v1, v1, v1
	v_max_f32_e32 v68, 0, v1
	v_add_f32_e32 v183, v183, v68
	v_xor_b32_e32 v34, 0x80000000, v183
	v_pk_add_f32 v[122:123], v[122:123], v[68:69] op_sel_hi:[1,0] neg_lo:[0,1] neg_hi:[0,1]
	v_pk_add_f32 v[106:107], v[106:107], v[68:69] op_sel_hi:[1,0] neg_lo:[0,1] neg_hi:[0,1]
	v_pk_add_f32 v[124:125], v[124:125], v[68:69] op_sel_hi:[1,0] neg_lo:[0,1] neg_hi:[0,1]
	v_pk_add_f32 v[108:109], v[108:109], v[68:69] op_sel_hi:[1,0] neg_lo:[0,1] neg_hi:[0,1]
	v_pk_add_f32 v[126:127], v[126:127], v[68:69] op_sel_hi:[1,0] neg_lo:[0,1] neg_hi:[0,1]
	v_pk_add_f32 v[110:111], v[110:111], v[68:69] op_sel_hi:[1,0] neg_lo:[0,1] neg_hi:[0,1]
	v_pk_add_f32 v[128:129], v[128:129], v[68:69] op_sel_hi:[1,0] neg_lo:[0,1] neg_hi:[0,1]
	v_pk_add_f32 v[112:113], v[112:113], v[68:69] op_sel_hi:[1,0] neg_lo:[0,1] neg_hi:[0,1]
	v_pk_add_f32 v[130:131], v[130:131], v[68:69] op_sel_hi:[1,0] neg_lo:[0,1] neg_hi:[0,1]
	v_pk_add_f32 v[114:115], v[114:115], v[68:69] op_sel_hi:[1,0] neg_lo:[0,1] neg_hi:[0,1]
	v_pk_add_f32 v[132:133], v[132:133], v[68:69] op_sel_hi:[1,0] neg_lo:[0,1] neg_hi:[0,1]
	v_pk_add_f32 v[116:117], v[116:117], v[68:69] op_sel_hi:[1,0] neg_lo:[0,1] neg_hi:[0,1]
	v_pk_add_f32 v[134:135], v[134:135], v[68:69] op_sel_hi:[1,0] neg_lo:[0,1] neg_hi:[0,1]
	v_pk_add_f32 v[118:119], v[118:119], v[68:69] op_sel_hi:[1,0] neg_lo:[0,1] neg_hi:[0,1]
	v_pk_add_f32 v[136:137], v[136:137], v[68:69] op_sel_hi:[1,0] neg_lo:[0,1] neg_hi:[0,1]
	v_pk_add_f32 v[120:121], v[120:121], v[68:69] op_sel_hi:[1,0] neg_lo:[0,1] neg_hi:[0,1]
	v_exp_f32_e64 v68, -v68
	v_mov_b32_e32 v35, v34
	v_mov_b32_e32 v36, v34
	v_mov_b32_e32 v37, v34
	v_mov_b32_e32 v38, v34
	v_mov_b32_e32 v39, v34
	v_mov_b32_e32 v40, v34
	v_mov_b32_e32 v41, v34
	v_mov_b32_e32 v42, v34
	v_mov_b32_e32 v43, v34
	v_mov_b32_e32 v44, v34
	v_mov_b32_e32 v45, v34
	v_mov_b32_e32 v46, v34
	v_mov_b32_e32 v47, v34
	v_mov_b32_e32 v48, v34
	v_mov_b32_e32 v49, v34
	s_nop 11
	v_pk_mul_f32 v[32:33], v[32:33], v[68:69] op_sel_hi:[1,0]
	v_pk_mul_f32 v[30:31], v[30:31], v[68:69] op_sel_hi:[1,0]
	v_pk_mul_f32 v[28:29], v[28:29], v[68:69] op_sel_hi:[1,0]
	v_pk_mul_f32 v[26:27], v[26:27], v[68:69] op_sel_hi:[1,0]
	v_pk_mul_f32 v[24:25], v[24:25], v[68:69] op_sel_hi:[1,0]
	v_pk_mul_f32 v[22:23], v[22:23], v[68:69] op_sel_hi:[1,0]
	v_pk_mul_f32 v[20:21], v[20:21], v[68:69] op_sel_hi:[1,0]
	v_pk_mul_f32 v[18:19], v[18:19], v[68:69] op_sel_hi:[1,0]
	v_pk_mul_f32 v[16:17], v[16:17], v[68:69] op_sel_hi:[1,0]
	v_pk_mul_f32 v[14:15], v[14:15], v[68:69] op_sel_hi:[1,0]
	v_pk_mul_f32 v[12:13], v[12:13], v[68:69] op_sel_hi:[1,0]
	v_pk_mul_f32 v[10:11], v[10:11], v[68:69] op_sel_hi:[1,0]
	v_pk_mul_f32 v[8:9], v[8:9], v[68:69] op_sel_hi:[1,0]
	v_pk_mul_f32 v[6:7], v[6:7], v[68:69] op_sel_hi:[1,0]
	v_pk_mul_f32 v[4:5], v[4:5], v[68:69] op_sel_hi:[1,0]
	v_pk_mul_f32 v[2:3], v[2:3], v[68:69] op_sel_hi:[1,0]
	v_mul_f32_e32 v50, v50, v68

.LBB0_661:
	v_lshl_add_u64 v[164:165], v[204:205], 0, v[200:201]
	s_mov_b32 s26, 0x1da8a000
	v_add_co_u32_e32 v2, vcc, s26, v164
	v_lshl_add_u64 v[6:7], v[202:203], 0, v[200:201]
	s_nop 0
	v_addc_co_u32_e32 v3, vcc, 0, v165, vcc
	s_mov_b32 s26, 0x1e2a0000
	v_add_co_u32_e32 v14, vcc, s26, v6
	s_nop 0
	v_addc_co_u32_e32 v15, vcc, 0, v7, vcc
	global_load_dwordx4 v[2:5], v[2:3], off
	s_mul_i32 s28, s27, 0x2400
	global_load_dwordx4 v[6:9], v[14:15], off offset:512
	s_add_i32 s26, s13, -7
	s_add_i32 s29, s28, 0xffffdc00
	s_cmp_lg_u32 s27, 0
	s_cselect_b32 s29, s29, 0x9000
	v_add_u32_e32 v1, s29, v195
	ds_read_b128 v[10:13], v1 offset:36864
	ds_read_b128 v[66:69], v1 offset:36896
	ds_read_b128 v[70:73], v1 offset:41472
	ds_read_b128 v[74:77], v1 offset:41504
	ds_read_b128 v[128:131], v1 offset:36928
	ds_read_b128 v[132:135], v1 offset:36960
	ds_read_b128 v[148:151], v1 offset:41536
	ds_read_b128 v[160:163], v1 offset:41568
	s_setprio 3
	v_mov_b32_e32 v1, 0
	v_cvt_pk_bf16_f32 v210, v116, v117
	v_cvt_pk_bf16_f32 v211, v118, v119
	v_cvt_pk_bf16_f32 v212, v112, v113
	v_cvt_pk_bf16_f32 v213, v114, v115
	s_waitcnt lgkmcnt(7)
	s_nop 0
	v_mfma_f32_32x32x16_bf16 v[16:31], v[10:13], v[210:213], v[16:31]
	v_add_f32_e32 v1, v1, v116
	v_add_f32_e32 v1, v1, v117
	v_add_f32_e32 v1, v1, v118
	v_add_f32_e32 v1, v1, v119
	s_waitcnt lgkmcnt(5)
	v_mfma_f32_32x32x16_bf16 v[32:47], v[70:73], v[210:213], v[32:47]
	v_cvt_pk_bf16_f32 v10, v187, v186
	v_cvt_pk_bf16_f32 v11, v185, v184
	v_cvt_pk_bf16_f32 v12, v147, v146
	v_cvt_pk_bf16_f32 v13, v145, v144
	v_add_f32_e32 v1, v1, v112
	v_add_f32_e32 v1, v1, v113
	v_add_f32_e32 v1, v1, v114
	v_add_f32_e32 v1, v1, v115
	s_nop 0
	v_mfma_f32_32x32x16_bf16 v[16:31], v[66:69], v[10:13], v[16:31]
	v_add_f32_e32 v1, v1, v187
	v_add_f32_e32 v1, v1, v186
	v_add_f32_e32 v1, v1, v185
	v_add_f32_e32 v1, v1, v184
	s_waitcnt lgkmcnt(4)
	v_mfma_f32_32x32x16_bf16 v[32:47], v[74:77], v[10:13], v[32:47]
	v_cvt_pk_bf16_f32 v66, v143, v142
	v_cvt_pk_bf16_f32 v67, v141, v140
	v_cvt_pk_bf16_f32 v68, v139, v138
	v_cvt_pk_bf16_f32 v69, v137, v136
	v_add_f32_e32 v1, v1, v147
	v_add_f32_e32 v1, v1, v146
	v_add_f32_e32 v1, v1, v145
	v_add_f32_e32 v1, v1, v144
	s_waitcnt lgkmcnt(3)
	v_mfma_f32_32x32x16_bf16 v[16:31], v[128:131], v[66:69], v[16:31]
	v_add_f32_e32 v1, v1, v143
	v_add_f32_e32 v1, v1, v142
	v_add_f32_e32 v1, v1, v141
	v_add_f32_e32 v1, v1, v140
	s_waitcnt lgkmcnt(1)
	v_mfma_f32_32x32x16_bf16 v[32:47], v[148:151], v[66:69], v[32:47]
	v_cvt_pk_bf16_f32 v10, v123, v122
	v_cvt_pk_bf16_f32 v11, v121, v120
	v_cvt_pk_bf16_f32 v12, v127, v126
	v_cvt_pk_bf16_f32 v13, v125, v124
	v_add_f32_e32 v1, v1, v139
	v_add_f32_e32 v1, v1, v138
	v_add_f32_e32 v1, v1, v137
	v_add_f32_e32 v1, v1, v136
	s_nop 0
	v_mfma_f32_32x32x16_bf16 v[16:31], v[132:135], v[10:13], v[16:31]
	v_add_f32_e32 v1, v1, v123
	v_add_f32_e32 v1, v1, v122
	v_add_f32_e32 v1, v1, v121
	v_add_f32_e32 v1, v1, v120
	s_waitcnt lgkmcnt(0)
	v_mfma_f32_32x32x16_bf16 v[32:47], v[160:163], v[10:13], v[32:47]
	v_add_f32_e32 v1, v1, v127
	v_add_f32_e32 v1, v1, v126
	v_add_f32_e32 v1, v1, v125
	v_add_f32_e32 v1, v1, v124
	s_setprio 2
	s_waitcnt lgkmcnt(0)
	s_barrier
	ds_read_b128 v[240:243], v195 offset:18432
	ds_read_b128 v[244:247], v195 offset:23040
	ds_read_b128 v[66:69], v195 offset:18464
	ds_read_b128 v[74:77], v195 offset:23072
	ds_read_b128 v[144:147], v195 offset:18496
	ds_read_b128 v[148:151], v195 offset:18528
	ds_read_b128 v[160:163], v195 offset:23104
	ds_read_b128 v[184:187], v195 offset:23136
	s_waitcnt lgkmcnt(6)
	v_mfma_f32_32x32x16_bf16 v[128:143], v[240:243], v[180:183], v[48:63]
	v_exp_f32_e32 v166, v96
	v_exp_f32_e32 v167, v97
	v_exp_f32_e32 v210, v98
	v_exp_f32_e32 v211, v99
	s_waitcnt lgkmcnt(5)
	v_mfma_f32_32x32x16_bf16 v[112:127], v[244:247], v[180:183], v[48:63]
	v_exp_f32_e32 v212, v100
	v_exp_f32_e32 v213, v101
	v_exp_f32_e32 v214, v102
	v_exp_f32_e32 v215, v103
	v_mfma_f32_32x32x16_bf16 v[128:143], v[66:69], v[176:179], v[128:143]
	v_exp_f32_e32 v100, v104
	v_exp_f32_e32 v101, v105
	v_exp_f32_e32 v102, v106
	v_exp_f32_e32 v103, v107
	s_waitcnt lgkmcnt(4)
	v_mfma_f32_32x32x16_bf16 v[112:127], v[74:77], v[176:179], v[112:127]
	v_exp_f32_e32 v104, v108
	v_exp_f32_e32 v105, v109
	v_exp_f32_e32 v106, v110
	v_exp_f32_e32 v107, v111
	s_waitcnt lgkmcnt(3)
	v_mfma_f32_32x32x16_bf16 v[128:143], v[144:147], v[172:175], v[128:143]
	v_exp_f32_e32 v108, v80
	v_exp_f32_e32 v109, v81
	v_exp_f32_e32 v110, v82
	v_exp_f32_e32 v111, v83
	s_waitcnt lgkmcnt(1)
	v_mfma_f32_32x32x16_bf16 v[112:127], v[160:163], v[172:175], v[112:127]
	v_exp_f32_e32 v144, v84
	v_exp_f32_e32 v145, v85
	v_exp_f32_e32 v146, v86
	v_exp_f32_e32 v147, v87
	v_mfma_f32_32x32x16_bf16 v[128:143], v[148:151], v[168:171], v[128:143]
	v_exp_f32_e32 v216, v88
	v_exp_f32_e32 v217, v89
	v_exp_f32_e32 v218, v90
	v_exp_f32_e32 v219, v91
	s_waitcnt lgkmcnt(0)
	v_mfma_f32_32x32x16_bf16 v[112:127], v[184:187], v[168:171], v[112:127]
	v_exp_f32_e32 v148, v92
	v_exp_f32_e32 v149, v93
	v_exp_f32_e32 v150, v94
	v_exp_f32_e32 v151, v95
	s_cmp_gt_i32 s27, 2
	s_cselect_b32 s29, -3, 2
	s_add_i32 s29, s29, s27
	v_add_u32_e32 v92, s28, v195
	s_add_i32 s28, s13, -6
	s_mulk_i32 s29, 0x2400
	s_min_u32 s28, s28, s12
	v_add_u32_e32 v10, s29, v208
	s_min_u32 s26, s26, s12
	s_lshl_b32 s92, s28, 13
	s_waitcnt vmcnt(3)
	ds_write_b128 v208, v[152:155]
	s_waitcnt vmcnt(2)
	ds_write_b128 v10, v[156:159] offset:36864
	v_lshl_add_u64 v[10:11], v[198:199], 0, s[92:93]
	s_lshl_b32 s92, s26, 7
	v_add_f32_e32 v1, v64, v1
	v_lshl_add_u64 v[64:65], v[196:197], 0, s[92:93]
	global_load_dwordx4 v[10:13], v[10:11], off
	s_add_i32 s29, s27, 1
	global_load_dwordx4 v[160:163], v[64:65], off
	ds_read_b128 v[240:243], v195 offset:27648
	ds_read_b128 v[244:247], v195 offset:32256
	ds_read_b128 v[64:67], v92 offset:41472
	ds_read_b128 v[68:71], v92 offset:36864
	ds_read_b128 v[72:75], v92 offset:36896
	ds_read_b128 v[76:79], v92 offset:41504
	ds_read_b128 v[80:83], v92 offset:36928
	ds_read_b128 v[84:87], v92 offset:41536
	ds_read_b128 v[88:91], v92 offset:36960
	ds_read_b128 v[92:95], v92 offset:41568
	s_setprio 1
	v_mov_b32_e32 v184, 0
	v_cvt_pk_bf16_f32 v96, v166, v167
	v_cvt_pk_bf16_f32 v97, v210, v211
	v_cvt_pk_bf16_f32 v98, v212, v213
	v_cvt_pk_bf16_f32 v99, v214, v215
	s_waitcnt lgkmcnt(6)
	s_nop 0
	v_mfma_f32_32x32x16_bf16 v[16:31], v[68:71], v[96:99], v[16:31]
	v_add_f32_e32 v184, v184, v166
	v_add_f32_e32 v184, v184, v167
	v_add_f32_e32 v184, v184, v210
	v_add_f32_e32 v184, v184, v211
	s_nop 0
	v_mfma_f32_32x32x16_bf16 v[32:47], v[64:67], v[96:99], v[32:47]
	v_cvt_pk_bf16_f32 v68, v100, v101
	v_cvt_pk_bf16_f32 v69, v102, v103
	v_cvt_pk_bf16_f32 v70, v104, v105
	v_cvt_pk_bf16_f32 v71, v106, v107
	v_add_f32_e32 v184, v184, v212
	v_add_f32_e32 v184, v184, v213
	v_add_f32_e32 v184, v184, v214
	v_add_f32_e32 v184, v184, v215
	s_waitcnt lgkmcnt(5)
	v_mfma_f32_32x32x16_bf16 v[16:31], v[72:75], v[68:71], v[16:31]
	v_add_f32_e32 v184, v184, v100
	v_add_f32_e32 v184, v184, v101
	v_add_f32_e32 v184, v184, v102
	v_add_f32_e32 v184, v184, v103
	s_waitcnt lgkmcnt(4)
	v_mfma_f32_32x32x16_bf16 v[32:47], v[76:79], v[68:71], v[32:47]
	v_cvt_pk_bf16_f32 v64, v108, v109
	v_cvt_pk_bf16_f32 v65, v110, v111
	v_cvt_pk_bf16_f32 v66, v144, v145
	v_cvt_pk_bf16_f32 v67, v146, v147
	v_add_f32_e32 v184, v184, v104
	v_add_f32_e32 v184, v184, v105
	v_add_f32_e32 v184, v184, v106
	v_add_f32_e32 v184, v184, v107
	s_waitcnt lgkmcnt(3)
	v_mfma_f32_32x32x16_bf16 v[16:31], v[80:83], v[64:67], v[16:31]
	v_add_f32_e32 v184, v184, v108
	v_add_f32_e32 v184, v184, v109
	v_add_f32_e32 v184, v184, v110
	v_add_f32_e32 v184, v184, v111
	s_waitcnt lgkmcnt(2)
	v_mfma_f32_32x32x16_bf16 v[32:47], v[84:87], v[64:67], v[32:47]
	v_cvt_pk_bf16_f32 v68, v216, v217
	v_cvt_pk_bf16_f32 v69, v218, v219
	v_cvt_pk_bf16_f32 v70, v148, v149
	v_cvt_pk_bf16_f32 v71, v150, v151
	v_add_f32_e32 v184, v184, v144
	v_add_f32_e32 v184, v184, v145
	v_add_f32_e32 v184, v184, v146
	v_add_f32_e32 v184, v184, v147
	s_waitcnt lgkmcnt(1)
	v_mfma_f32_32x32x16_bf16 v[16:31], v[88:91], v[68:71], v[16:31]
	v_add_f32_e32 v184, v184, v216
	v_add_f32_e32 v184, v184, v217
	v_add_f32_e32 v184, v184, v218
	v_add_f32_e32 v184, v184, v219
	s_waitcnt lgkmcnt(0)
	v_mfma_f32_32x32x16_bf16 v[32:47], v[92:95], v[68:71], v[32:47]
	v_add_f32_e32 v184, v184, v148
	v_add_f32_e32 v184, v184, v149
	v_add_f32_e32 v184, v184, v150
	v_add_f32_e32 v184, v184, v151
	s_setprio 0
	ds_read_b128 v[68:71], v195 offset:27680
	ds_read_b128 v[76:79], v195 offset:32288
	ds_read_b128 v[80:83], v195 offset:27712
	ds_read_b128 v[84:87], v195 offset:27744
	ds_read_b128 v[88:91], v195 offset:32320
	ds_read_b128 v[92:95], v195 offset:32352
	s_cmp_lg_u32 s27, 4
	s_cselect_b32 s26, s29, 0
	s_waitcnt lgkmcnt(6)
	v_mfma_f32_32x32x16_bf16 v[144:159], v[240:243], v[180:183], v[48:63]
	v_exp_f32_e32 v166, v128
	v_exp_f32_e32 v167, v129
	v_exp_f32_e32 v185, v130
	v_exp_f32_e32 v186, v131
	s_waitcnt lgkmcnt(5)
	v_mfma_f32_32x32x16_bf16 v[96:111], v[244:247], v[180:183], v[48:63]
	v_exp_f32_e32 v128, v132
	v_exp_f32_e32 v129, v133
	v_exp_f32_e32 v130, v134
	v_exp_f32_e32 v131, v135
	v_mfma_f32_32x32x16_bf16 v[144:159], v[68:71], v[176:179], v[144:159]
	v_exp_f32_e32 v132, v136
	v_exp_f32_e32 v133, v137
	v_exp_f32_e32 v134, v138
	v_exp_f32_e32 v135, v139
	s_waitcnt lgkmcnt(4)
	v_mfma_f32_32x32x16_bf16 v[96:111], v[76:79], v[176:179], v[96:111]
	v_exp_f32_e32 v136, v140
	v_exp_f32_e32 v137, v141
	v_exp_f32_e32 v138, v142
	v_exp_f32_e32 v139, v143
	s_waitcnt lgkmcnt(3)
	v_mfma_f32_32x32x16_bf16 v[144:159], v[80:83], v[172:175], v[144:159]
	v_exp_f32_e32 v140, v112
	v_exp_f32_e32 v141, v113
	v_exp_f32_e32 v142, v114
	v_exp_f32_e32 v143, v115
	s_waitcnt lgkmcnt(1)
	v_mfma_f32_32x32x16_bf16 v[96:111], v[88:91], v[172:175], v[96:111]
	v_exp_f32_e32 v187, v116
	v_exp_f32_e32 v210, v117
	v_exp_f32_e32 v211, v118
	v_exp_f32_e32 v212, v119
	v_mfma_f32_32x32x16_bf16 v[144:159], v[84:87], v[168:171], v[144:159]
	v_exp_f32_e32 v116, v120
	v_exp_f32_e32 v117, v121
	v_exp_f32_e32 v118, v122
	v_exp_f32_e32 v119, v123
	s_waitcnt lgkmcnt(0)
	v_mfma_f32_32x32x16_bf16 v[96:111], v[92:95], v[168:171], v[96:111]
	v_exp_f32_e32 v120, v124
	v_exp_f32_e32 v121, v125
	v_exp_f32_e32 v122, v126
	v_exp_f32_e32 v123, v127
	s_cmp_gt_i32 s26, 2
	s_cselect_b32 s27, -3, 2
	s_add_i32 s27, s27, s26
	s_mulk_i32 s27, 0x2400
	s_waitcnt vmcnt(3)
	ds_write_b128 v208, v[2:5] offset:9216
	v_add_u32_e32 v2, s27, v208
	s_add_i32 s27, s26, 1
	s_cmp_lg_u32 s26, 4
	s_cselect_b32 s26, s27, 0
	s_add_i32 s27, s13, -5
	s_min_u32 s27, s27, s12
	s_lshl_b32 s92, s27, 13
	s_waitcnt vmcnt(2)
	ds_write_b128 v2, v[6:9] offset:36864
	v_lshl_add_u64 v[2:3], v[198:199], 0, s[92:93]
	s_lshl_b32 s92, s28, 7
	v_lshl_add_u64 v[4:5], v[196:197], 0, s[92:93]
	global_load_dwordx4 v[6:9], v[2:3], off
	s_nop 0
	global_load_dwordx4 v[2:5], v[4:5], off
	s_mul_i32 s28, s26, 0x2400
	s_add_i32 s29, s28, 0xffffdc00
	s_cmp_lg_u32 s26, 0
	s_cselect_b32 s29, s29, 0x9000
	v_add_u32_e32 v92, s29, v195
	ds_read_b128 v[64:67], v92 offset:36864
	ds_read_b128 v[68:71], v92 offset:36896
	ds_read_b128 v[72:75], v92 offset:41472
	ds_read_b128 v[76:79], v92 offset:41504
	ds_read_b128 v[80:83], v92 offset:36928
	ds_read_b128 v[84:87], v92 offset:36960
	ds_read_b128 v[88:91], v92 offset:41536
	ds_read_b128 v[92:95], v92 offset:41568
	s_setprio 3
	v_mov_b32_e32 v213, 0
	v_cvt_pk_bf16_f32 v112, v166, v167
	v_cvt_pk_bf16_f32 v113, v185, v186
	v_cvt_pk_bf16_f32 v114, v128, v129
	v_cvt_pk_bf16_f32 v115, v130, v131
	s_waitcnt lgkmcnt(7)
	s_nop 0
	v_mfma_f32_32x32x16_bf16 v[16:31], v[64:67], v[112:115], v[16:31]
	v_add_f32_e32 v213, v213, v166
	v_add_f32_e32 v213, v213, v167
	v_add_f32_e32 v213, v213, v185
	v_add_f32_e32 v213, v213, v186
	s_waitcnt lgkmcnt(5)
	v_mfma_f32_32x32x16_bf16 v[32:47], v[72:75], v[112:115], v[32:47]
	v_cvt_pk_bf16_f32 v64, v132, v133
	v_cvt_pk_bf16_f32 v65, v134, v135
	v_cvt_pk_bf16_f32 v66, v136, v137
	v_cvt_pk_bf16_f32 v67, v138, v139
	v_add_f32_e32 v213, v213, v128
	v_add_f32_e32 v213, v213, v129
	v_add_f32_e32 v213, v213, v130
	v_add_f32_e32 v213, v213, v131
	s_nop 0
	v_mfma_f32_32x32x16_bf16 v[16:31], v[68:71], v[64:67], v[16:31]
	v_add_f32_e32 v213, v213, v132
	v_add_f32_e32 v213, v213, v133
	v_add_f32_e32 v213, v213, v134
	v_add_f32_e32 v213, v213, v135
	s_waitcnt lgkmcnt(4)
	v_mfma_f32_32x32x16_bf16 v[32:47], v[76:79], v[64:67], v[32:47]
	v_cvt_pk_bf16_f32 v68, v140, v141
	v_cvt_pk_bf16_f32 v69, v142, v143
	v_cvt_pk_bf16_f32 v70, v187, v210
	v_cvt_pk_bf16_f32 v71, v211, v212
	v_add_f32_e32 v213, v213, v136
	v_add_f32_e32 v213, v213, v137
	v_add_f32_e32 v213, v213, v138
	v_add_f32_e32 v213, v213, v139
	s_waitcnt lgkmcnt(3)
	v_mfma_f32_32x32x16_bf16 v[16:31], v[80:83], v[68:71], v[16:31]
	v_add_f32_e32 v213, v213, v140
	v_add_f32_e32 v213, v213, v141
	v_add_f32_e32 v213, v213, v142
	v_add_f32_e32 v213, v213, v143
	s_waitcnt lgkmcnt(1)
	v_mfma_f32_32x32x16_bf16 v[32:47], v[88:91], v[68:71], v[32:47]
	v_cvt_pk_bf16_f32 v64, v116, v117
	v_cvt_pk_bf16_f32 v65, v118, v119
	v_cvt_pk_bf16_f32 v66, v120, v121
	v_cvt_pk_bf16_f32 v67, v122, v123
	v_add_f32_e32 v213, v213, v187
	v_add_f32_e32 v213, v213, v210
	v_add_f32_e32 v213, v213, v211
	v_add_f32_e32 v213, v213, v212
	s_nop 0
	v_mfma_f32_32x32x16_bf16 v[16:31], v[84:87], v[64:67], v[16:31]
	v_add_f32_e32 v213, v213, v116
	v_add_f32_e32 v213, v213, v117
	v_add_f32_e32 v213, v213, v118
	v_add_f32_e32 v213, v213, v119
	s_waitcnt lgkmcnt(0)
	v_mfma_f32_32x32x16_bf16 v[32:47], v[92:95], v[64:67], v[32:47]
	v_add_f32_e32 v213, v213, v120
	v_add_f32_e32 v213, v213, v121
	v_add_f32_e32 v213, v213, v122
	v_add_f32_e32 v213, v213, v123
	s_setprio 2
	s_waitcnt lgkmcnt(0)
	s_barrier
	ds_read_b128 v[240:243], v195
	ds_read_b128 v[244:247], v195 offset:4608
	ds_read_b128 v[116:119], v195 offset:32
	ds_read_b128 v[120:123], v195 offset:4640
	ds_read_b128 v[124:127], v195 offset:64
	ds_read_b128 v[128:131], v195 offset:4672
	ds_read_b128 v[132:135], v195 offset:96
	ds_read_b128 v[136:139], v195 offset:4704
	v_add_f32_e32 v1, v1, v184
	s_waitcnt lgkmcnt(6)
	v_mfma_f32_32x32x16_bf16 v[80:95], v[240:243], v[180:183], v[48:63]
	v_exp_f32_e32 v140, v144
	v_exp_f32_e32 v141, v145
	v_exp_f32_e32 v142, v146
	v_exp_f32_e32 v143, v147
	v_mfma_f32_32x32x16_bf16 v[64:79], v[244:247], v[180:183], v[48:63]
	v_exp_f32_e32 v144, v148
	v_exp_f32_e32 v145, v149
	v_exp_f32_e32 v146, v150
	v_exp_f32_e32 v147, v151
	s_waitcnt lgkmcnt(5)
	v_mfma_f32_32x32x16_bf16 v[80:95], v[116:119], v[176:179], v[80:95]
	v_exp_f32_e32 v148, v152
	v_exp_f32_e32 v149, v153
	v_exp_f32_e32 v150, v154
	v_exp_f32_e32 v151, v155
	s_waitcnt lgkmcnt(4)
	v_mfma_f32_32x32x16_bf16 v[64:79], v[120:123], v[176:179], v[64:79]
	v_exp_f32_e32 v152, v156
	v_exp_f32_e32 v153, v157
	v_exp_f32_e32 v154, v158
	v_exp_f32_e32 v155, v159
	s_waitcnt lgkmcnt(3)
	v_mfma_f32_32x32x16_bf16 v[80:95], v[124:127], v[172:175], v[80:95]
	v_exp_f32_e32 v156, v96
	v_exp_f32_e32 v157, v97
	v_exp_f32_e32 v158, v98
	v_exp_f32_e32 v159, v99
	s_waitcnt lgkmcnt(2)
	v_mfma_f32_32x32x16_bf16 v[64:79], v[128:131], v[172:175], v[64:79]
	v_exp_f32_e32 v166, v100
	v_exp_f32_e32 v167, v101
	v_exp_f32_e32 v184, v102
	v_exp_f32_e32 v185, v103
	s_waitcnt lgkmcnt(1)
	v_mfma_f32_32x32x16_bf16 v[80:95], v[132:135], v[168:171], v[80:95]
	v_exp_f32_e32 v186, v104
	v_exp_f32_e32 v187, v105
	v_exp_f32_e32 v210, v106
	v_exp_f32_e32 v211, v107
	s_waitcnt lgkmcnt(0)
	v_mfma_f32_32x32x16_bf16 v[64:79], v[136:139], v[168:171], v[64:79]
	v_exp_f32_e32 v212, v108
	v_exp_f32_e32 v214, v109
	v_exp_f32_e32 v215, v110
	v_exp_f32_e32 v216, v111
	s_cmp_gt_i32 s26, 2
	s_cselect_b32 s29, -3, 2
	s_add_i32 s29, s29, s26
	s_mulk_i32 s29, 0x2400
	s_waitcnt vmcnt(3)
	ds_write_b128 v208, v[10:13] offset:18432
	v_add_u32_e32 v10, s29, v208
	s_mov_b32 s29, 0x1da90000
	s_waitcnt vmcnt(2)
	ds_write_b128 v10, v[160:163] offset:36864
	v_add_co_u32_e32 v10, vcc, s29, v164
	s_lshl_b32 s92, s27, 7
	s_nop 0
	v_addc_co_u32_e32 v11, vcc, 0, v165, vcc
	global_load_dwordx4 v[128:131], v[10:11], off
	v_lshl_add_u64 v[10:11], v[196:197], 0, s[92:93]
	global_load_dwordx4 v[10:13], v[10:11], off
	v_add_u32_e32 v124, s28, v195
	ds_read_b128 v[240:243], v195 offset:9216
	ds_read_b128 v[244:247], v195 offset:13824
	ds_read_b128 v[96:99], v124 offset:41472
	ds_read_b128 v[100:103], v124 offset:36864
	ds_read_b128 v[104:107], v124 offset:36896
	ds_read_b128 v[108:111], v124 offset:41504
	ds_read_b128 v[112:115], v124 offset:36928
	ds_read_b128 v[116:119], v124 offset:41536
	ds_read_b128 v[120:123], v124 offset:36960
	ds_read_b128 v[124:127], v124 offset:41568
	v_add_f32_e32 v1, v1, v213
	s_add_i32 s28, s26, 1
	s_setprio 1
	v_mov_b32_e32 v160, 0
	v_cvt_pk_bf16_f32 v132, v140, v141
	v_cvt_pk_bf16_f32 v133, v142, v143
	v_cvt_pk_bf16_f32 v134, v144, v145
	v_cvt_pk_bf16_f32 v135, v146, v147
	s_waitcnt lgkmcnt(6)
	s_nop 0
	v_mfma_f32_32x32x16_bf16 v[16:31], v[100:103], v[132:135], v[16:31]
	v_add_f32_e32 v160, v160, v140
	v_add_f32_e32 v160, v160, v141
	v_add_f32_e32 v160, v160, v142
	v_add_f32_e32 v160, v160, v143
	s_nop 0
	v_mfma_f32_32x32x16_bf16 v[32:47], v[96:99], v[132:135], v[32:47]
	v_cvt_pk_bf16_f32 v100, v148, v149
	v_cvt_pk_bf16_f32 v101, v150, v151
	v_cvt_pk_bf16_f32 v102, v152, v153
	v_cvt_pk_bf16_f32 v103, v154, v155
	v_add_f32_e32 v160, v160, v144
	v_add_f32_e32 v160, v160, v145
	v_add_f32_e32 v160, v160, v146
	v_add_f32_e32 v160, v160, v147
	s_waitcnt lgkmcnt(5)
	v_mfma_f32_32x32x16_bf16 v[16:31], v[104:107], v[100:103], v[16:31]
	v_add_f32_e32 v160, v160, v148
	v_add_f32_e32 v160, v160, v149
	v_add_f32_e32 v160, v160, v150
	v_add_f32_e32 v160, v160, v151
	s_waitcnt lgkmcnt(4)
	v_mfma_f32_32x32x16_bf16 v[32:47], v[108:111], v[100:103], v[32:47]
	v_cvt_pk_bf16_f32 v96, v156, v157
	v_cvt_pk_bf16_f32 v97, v158, v159
	v_cvt_pk_bf16_f32 v98, v166, v167
	v_cvt_pk_bf16_f32 v99, v184, v185
	v_add_f32_e32 v160, v160, v152
	v_add_f32_e32 v160, v160, v153
	v_add_f32_e32 v160, v160, v154
	v_add_f32_e32 v160, v160, v155
	s_waitcnt lgkmcnt(3)
	v_mfma_f32_32x32x16_bf16 v[16:31], v[112:115], v[96:99], v[16:31]
	v_add_f32_e32 v160, v160, v156
	v_add_f32_e32 v160, v160, v157
	v_add_f32_e32 v160, v160, v158
	v_add_f32_e32 v160, v160, v159
	s_waitcnt lgkmcnt(2)
	v_mfma_f32_32x32x16_bf16 v[32:47], v[116:119], v[96:99], v[32:47]
	v_cvt_pk_bf16_f32 v100, v186, v187
	v_cvt_pk_bf16_f32 v101, v210, v211
	v_cvt_pk_bf16_f32 v102, v212, v214
	v_cvt_pk_bf16_f32 v103, v215, v216
	v_add_f32_e32 v160, v160, v166
	v_add_f32_e32 v160, v160, v167
	v_add_f32_e32 v160, v160, v184
	v_add_f32_e32 v160, v160, v185
	s_waitcnt lgkmcnt(1)
	v_mfma_f32_32x32x16_bf16 v[16:31], v[120:123], v[100:103], v[16:31]
	v_add_f32_e32 v160, v160, v186
	v_add_f32_e32 v160, v160, v187
	v_add_f32_e32 v160, v160, v210
	v_add_f32_e32 v160, v160, v211
	s_waitcnt lgkmcnt(0)
	v_mfma_f32_32x32x16_bf16 v[32:47], v[124:127], v[100:103], v[32:47]
	v_add_f32_e32 v160, v160, v212
	v_add_f32_e32 v160, v160, v214
	v_add_f32_e32 v160, v160, v215
	v_add_f32_e32 v160, v160, v216
	s_setprio 0
	ds_read_b128 v[132:135], v195 offset:9248
	ds_read_b128 v[140:143], v195 offset:13856
	ds_read_b128 v[144:147], v195 offset:9280
	ds_read_b128 v[148:151], v195 offset:9312
	ds_read_b128 v[152:155], v195 offset:13888
	ds_read_b128 v[156:159], v195 offset:13920
	s_cmp_lg_u32 s26, 4
	s_cselect_b32 s26, s28, 0
	s_waitcnt lgkmcnt(6)
	v_mfma_f32_32x32x16_bf16 v[112:127], v[240:243], v[180:183], v[48:63]
	v_exp_f32_e32 v161, v80
	v_exp_f32_e32 v162, v81
	v_exp_f32_e32 v163, v82
	v_exp_f32_e32 v164, v83
	s_waitcnt lgkmcnt(5)
	v_mfma_f32_32x32x16_bf16 v[96:111], v[244:247], v[180:183], v[48:63]
	v_exp_f32_e32 v165, v84
	v_exp_f32_e32 v166, v85
	v_exp_f32_e32 v167, v86
	v_exp_f32_e32 v184, v87
	v_mfma_f32_32x32x16_bf16 v[112:127], v[132:135], v[176:179], v[112:127]
	v_exp_f32_e32 v136, v88
	v_exp_f32_e32 v137, v89
	v_exp_f32_e32 v138, v90
	v_exp_f32_e32 v139, v91
	s_waitcnt lgkmcnt(4)
	v_mfma_f32_32x32x16_bf16 v[96:111], v[140:143], v[176:179], v[96:111]
	v_exp_f32_e32 v185, v92
	v_exp_f32_e32 v186, v93
	v_exp_f32_e32 v187, v94
	v_exp_f32_e32 v210, v95
	s_waitcnt lgkmcnt(3)
	v_mfma_f32_32x32x16_bf16 v[112:127], v[144:147], v[172:175], v[112:127]
	v_exp_f32_e32 v140, v64
	v_exp_f32_e32 v141, v65
	v_exp_f32_e32 v142, v66
	v_exp_f32_e32 v143, v67
	s_waitcnt lgkmcnt(1)
	v_mfma_f32_32x32x16_bf16 v[96:111], v[152:155], v[172:175], v[96:111]
	v_exp_f32_e32 v144, v68
	v_exp_f32_e32 v145, v69
	v_exp_f32_e32 v146, v70
	v_exp_f32_e32 v147, v71
	v_mfma_f32_32x32x16_bf16 v[112:127], v[148:151], v[168:171], v[112:127]
	v_exp_f32_e32 v152, v72
	v_exp_f32_e32 v153, v73
	v_exp_f32_e32 v154, v74
	v_exp_f32_e32 v155, v75
	s_waitcnt lgkmcnt(0)
	v_mfma_f32_32x32x16_bf16 v[96:111], v[156:159], v[168:171], v[96:111]
	v_exp_f32_e32 v148, v76
	v_exp_f32_e32 v149, v77
	v_exp_f32_e32 v150, v78
	v_exp_f32_e32 v151, v79
	s_cmp_gt_i32 s26, 2
	s_cselect_b32 s27, -3, 2
	s_add_i32 s27, s27, s26
	s_mulk_i32 s27, 0x2400
	s_waitcnt vmcnt(3)
	ds_write_b128 v208, v[6:9] offset:27648
	v_add_u32_e32 v6, s27, v208
	s_add_i32 s27, s26, 1
	s_cmp_lg_u32 s26, 4
	s_cselect_b32 s27, s27, 0
	s_add_i32 s26, s13, -3
	s_min_u32 s28, s26, s12
	s_lshl_b32 s92, s28, 13
	s_waitcnt vmcnt(2)
	ds_write_b128 v6, v[2:5] offset:36864
	v_lshl_add_u64 v[2:3], v[198:199], 0, s[92:93]
	global_load_dwordx4 v[6:9], v[2:3], off
	s_nop 0
	global_load_dwordx4 v[2:5], v[14:15], off offset:1024
	s_mul_i32 s29, s27, 0x2400
	s_add_i32 s34, s29, 0xffffdc00
	s_cmp_lg_u32 s27, 0
	s_cselect_b32 s34, s34, 0x9000
	v_add_u32_e32 v14, s34, v195
	ds_read_b128 v[64:67], v14 offset:36864
	ds_read_b128 v[68:71], v14 offset:36896
	ds_read_b128 v[72:75], v14 offset:41472
	ds_read_b128 v[76:79], v14 offset:41504
	ds_read_b128 v[80:83], v14 offset:36928
	ds_read_b128 v[84:87], v14 offset:36960
	ds_read_b128 v[88:91], v14 offset:41536
	ds_read_b128 v[92:95], v14 offset:41568
	s_setprio 3
	v_mov_b32_e32 v14, 0
	v_cvt_pk_bf16_f32 v132, v161, v162
	v_cvt_pk_bf16_f32 v133, v163, v164
	v_cvt_pk_bf16_f32 v134, v165, v166
	v_cvt_pk_bf16_f32 v135, v167, v184
	s_waitcnt lgkmcnt(7)
	s_nop 0
	v_mfma_f32_32x32x16_bf16 v[16:31], v[64:67], v[132:135], v[16:31]
	v_add_f32_e32 v14, v14, v161
	v_add_f32_e32 v14, v14, v162
	v_add_f32_e32 v14, v14, v163
	v_add_f32_e32 v14, v14, v164
	s_waitcnt lgkmcnt(5)
	v_mfma_f32_32x32x16_bf16 v[32:47], v[72:75], v[132:135], v[32:47]
	v_cvt_pk_bf16_f32 v64, v136, v137
	v_cvt_pk_bf16_f32 v65, v138, v139
	v_cvt_pk_bf16_f32 v66, v185, v186
	v_cvt_pk_bf16_f32 v67, v187, v210
	v_add_f32_e32 v14, v14, v165
	v_add_f32_e32 v14, v14, v166
	v_add_f32_e32 v14, v14, v167
	v_add_f32_e32 v14, v14, v184
	s_nop 0
	v_mfma_f32_32x32x16_bf16 v[16:31], v[68:71], v[64:67], v[16:31]
	v_add_f32_e32 v14, v14, v136
	v_add_f32_e32 v14, v14, v137
	v_add_f32_e32 v14, v14, v138
	v_add_f32_e32 v14, v14, v139
	s_waitcnt lgkmcnt(4)
	v_mfma_f32_32x32x16_bf16 v[32:47], v[76:79], v[64:67], v[32:47]
	v_cvt_pk_bf16_f32 v68, v140, v141
	v_cvt_pk_bf16_f32 v69, v142, v143
	v_cvt_pk_bf16_f32 v70, v144, v145
	v_cvt_pk_bf16_f32 v71, v146, v147
	v_add_f32_e32 v14, v14, v185
	v_add_f32_e32 v14, v14, v186
	v_add_f32_e32 v14, v14, v187
	v_add_f32_e32 v14, v14, v210
	s_waitcnt lgkmcnt(3)
	v_mfma_f32_32x32x16_bf16 v[16:31], v[80:83], v[68:71], v[16:31]
	v_add_f32_e32 v14, v14, v140
	v_add_f32_e32 v14, v14, v141
	v_add_f32_e32 v14, v14, v142
	v_add_f32_e32 v14, v14, v143
	s_waitcnt lgkmcnt(1)
	v_mfma_f32_32x32x16_bf16 v[32:47], v[88:91], v[68:71], v[32:47]
	v_cvt_pk_bf16_f32 v64, v152, v153
	v_cvt_pk_bf16_f32 v65, v154, v155
	v_cvt_pk_bf16_f32 v66, v148, v149
	v_cvt_pk_bf16_f32 v67, v150, v151
	v_add_f32_e32 v14, v14, v144
	v_add_f32_e32 v14, v14, v145
	v_add_f32_e32 v14, v14, v146
	v_add_f32_e32 v14, v14, v147
	s_nop 0
	v_mfma_f32_32x32x16_bf16 v[16:31], v[84:87], v[64:67], v[16:31]
	v_add_f32_e32 v14, v14, v152
	v_add_f32_e32 v14, v14, v153
	v_add_f32_e32 v14, v14, v154
	v_add_f32_e32 v14, v14, v155
	s_waitcnt lgkmcnt(0)
	v_mfma_f32_32x32x16_bf16 v[32:47], v[92:95], v[64:67], v[32:47]
	v_add_f32_e32 v14, v14, v148
	v_add_f32_e32 v14, v14, v149
	v_add_f32_e32 v14, v14, v150
	v_add_f32_e32 v14, v14, v151
	s_setprio 2
	s_waitcnt lgkmcnt(0)
	s_barrier
	ds_read_b128 v[240:243], v195 offset:18432
	ds_read_b128 v[244:247], v195 offset:23040
	ds_read_b128 v[136:139], v195 offset:18464
	ds_read_b128 v[140:143], v195 offset:23072
	ds_read_b128 v[144:147], v195 offset:18496
	ds_read_b128 v[148:151], v195 offset:23104
	ds_read_b128 v[152:155], v195 offset:18528
	ds_read_b128 v[156:159], v195 offset:23136
	v_add_f32_e32 v1, v1, v160
	s_waitcnt lgkmcnt(6)
	v_mfma_f32_32x32x16_bf16 v[80:95], v[240:243], v[180:183], v[48:63]
	v_exp_f32_e32 v160, v112
	v_exp_f32_e32 v161, v113
	v_exp_f32_e32 v162, v114
	v_exp_f32_e32 v163, v115
	v_mfma_f32_32x32x16_bf16 v[64:79], v[244:247], v[180:183], v[48:63]
	v_exp_f32_e32 v164, v116
	v_exp_f32_e32 v165, v117
	v_exp_f32_e32 v166, v118
	v_exp_f32_e32 v167, v119
	s_waitcnt lgkmcnt(5)
	v_mfma_f32_32x32x16_bf16 v[80:95], v[136:139], v[176:179], v[80:95]
	v_exp_f32_e32 v184, v120
	v_exp_f32_e32 v185, v121
	v_exp_f32_e32 v186, v122
	v_exp_f32_e32 v187, v123
	s_waitcnt lgkmcnt(4)
	v_mfma_f32_32x32x16_bf16 v[64:79], v[140:143], v[176:179], v[64:79]
	v_exp_f32_e32 v136, v124
	v_exp_f32_e32 v137, v125
	v_exp_f32_e32 v138, v126
	v_exp_f32_e32 v139, v127
	s_waitcnt lgkmcnt(3)
	v_mfma_f32_32x32x16_bf16 v[80:95], v[144:147], v[172:175], v[80:95]
	v_exp_f32_e32 v140, v96
	v_exp_f32_e32 v141, v97
	v_exp_f32_e32 v142, v98
	v_exp_f32_e32 v143, v99
	s_waitcnt lgkmcnt(2)
	v_mfma_f32_32x32x16_bf16 v[64:79], v[148:151], v[172:175], v[64:79]
	v_exp_f32_e32 v144, v100
	v_exp_f32_e32 v145, v101
	v_exp_f32_e32 v146, v102
	v_exp_f32_e32 v147, v103
	s_waitcnt lgkmcnt(1)
	v_mfma_f32_32x32x16_bf16 v[80:95], v[152:155], v[168:171], v[80:95]
	v_exp_f32_e32 v148, v104
	v_exp_f32_e32 v149, v105
	v_exp_f32_e32 v150, v106
	v_exp_f32_e32 v151, v107
	s_waitcnt lgkmcnt(0)
	v_mfma_f32_32x32x16_bf16 v[64:79], v[156:159], v[168:171], v[64:79]
	v_exp_f32_e32 v152, v108
	v_exp_f32_e32 v153, v109
	v_exp_f32_e32 v154, v110
	v_exp_f32_e32 v155, v111
	s_cmp_gt_i32 s27, 2
	s_cselect_b32 s34, -3, 2
	s_waitcnt vmcnt(3)
	ds_write_b128 v208, v[128:131]
	s_add_i32 s34, s34, s27
	v_add_u32_e32 v128, s29, v195
	s_add_i32 s29, s13, -2
	s_mulk_i32 s34, 0x2400
	s_min_u32 s29, s29, s12
	v_add_u32_e32 v15, s34, v208
	s_lshl_b32 s92, s29, 13
	s_waitcnt vmcnt(2)
	ds_write_b128 v15, v[10:13] offset:36864
	v_lshl_add_u64 v[10:11], v[198:199], 0, s[92:93]
	s_lshl_b32 s92, s28, 7
	v_add_f32_e32 v1, v1, v14
	global_load_dwordx4 v[10:13], v[10:11], off
	v_lshl_add_u64 v[14:15], v[196:197], 0, s[92:93]
	global_load_dwordx4 v[112:115], v[14:15], off
	ds_read_b128 v[240:243], v195 offset:27648
	ds_read_b128 v[244:247], v195 offset:32256
	ds_read_b128 v[96:99], v128 offset:41472
	ds_read_b128 v[100:103], v128 offset:36864
	ds_read_b128 v[104:107], v128 offset:36896
	ds_read_b128 v[108:111], v128 offset:41504
	ds_read_b128 v[116:119], v128 offset:36928
	ds_read_b128 v[120:123], v128 offset:41536
	ds_read_b128 v[124:127], v128 offset:36960
	ds_read_b128 v[128:131], v128 offset:41568
	s_add_i32 s34, s27, 1
	s_setprio 1
	v_mov_b32_e32 v14, 0
	v_cvt_pk_bf16_f32 v132, v160, v161
	v_cvt_pk_bf16_f32 v133, v162, v163
	v_cvt_pk_bf16_f32 v134, v164, v165
	v_cvt_pk_bf16_f32 v135, v166, v167
	s_waitcnt lgkmcnt(6)
	s_nop 0
	v_mfma_f32_32x32x16_bf16 v[16:31], v[100:103], v[132:135], v[16:31]
	v_add_f32_e32 v14, v14, v160
	v_add_f32_e32 v14, v14, v161
	v_add_f32_e32 v14, v14, v162
	v_add_f32_e32 v14, v14, v163
	s_nop 0
	v_mfma_f32_32x32x16_bf16 v[32:47], v[96:99], v[132:135], v[32:47]
	v_cvt_pk_bf16_f32 v100, v184, v185
	v_cvt_pk_bf16_f32 v101, v186, v187
	v_cvt_pk_bf16_f32 v102, v136, v137
	v_cvt_pk_bf16_f32 v103, v138, v139
	v_add_f32_e32 v14, v14, v164
	v_add_f32_e32 v14, v14, v165
	v_add_f32_e32 v14, v14, v166
	v_add_f32_e32 v14, v14, v167
	s_waitcnt lgkmcnt(5)
	v_mfma_f32_32x32x16_bf16 v[16:31], v[104:107], v[100:103], v[16:31]
	v_add_f32_e32 v14, v14, v184
	v_add_f32_e32 v14, v14, v185
	v_add_f32_e32 v14, v14, v186
	v_add_f32_e32 v14, v14, v187
	s_waitcnt lgkmcnt(4)
	v_mfma_f32_32x32x16_bf16 v[32:47], v[108:111], v[100:103], v[32:47]
	v_cvt_pk_bf16_f32 v96, v140, v141
	v_cvt_pk_bf16_f32 v97, v142, v143
	v_cvt_pk_bf16_f32 v98, v144, v145
	v_cvt_pk_bf16_f32 v99, v146, v147
	v_add_f32_e32 v14, v14, v136
	v_add_f32_e32 v14, v14, v137
	v_add_f32_e32 v14, v14, v138
	v_add_f32_e32 v14, v14, v139
	s_waitcnt lgkmcnt(3)
	v_mfma_f32_32x32x16_bf16 v[16:31], v[116:119], v[96:99], v[16:31]
	v_add_f32_e32 v14, v14, v140
	v_add_f32_e32 v14, v14, v141
	v_add_f32_e32 v14, v14, v142
	v_add_f32_e32 v14, v14, v143
	s_waitcnt lgkmcnt(2)
	v_mfma_f32_32x32x16_bf16 v[32:47], v[120:123], v[96:99], v[32:47]
	v_cvt_pk_bf16_f32 v100, v148, v149
	v_cvt_pk_bf16_f32 v101, v150, v151
	v_cvt_pk_bf16_f32 v102, v152, v153
	v_cvt_pk_bf16_f32 v103, v154, v155
	v_add_f32_e32 v14, v14, v144
	v_add_f32_e32 v14, v14, v145
	v_add_f32_e32 v14, v14, v146
	v_add_f32_e32 v14, v14, v147
	s_waitcnt lgkmcnt(1)
	v_mfma_f32_32x32x16_bf16 v[16:31], v[124:127], v[100:103], v[16:31]
	v_add_f32_e32 v14, v14, v148
	v_add_f32_e32 v14, v14, v149
	v_add_f32_e32 v14, v14, v150
	v_add_f32_e32 v14, v14, v151
	s_waitcnt lgkmcnt(0)
	v_mfma_f32_32x32x16_bf16 v[32:47], v[128:131], v[100:103], v[32:47]
	v_add_f32_e32 v14, v14, v152
	v_add_f32_e32 v14, v14, v153
	v_add_f32_e32 v14, v14, v154
	v_add_f32_e32 v14, v14, v155
	s_setprio 0
	ds_read_b128 v[116:119], v195 offset:27680
	ds_read_b128 v[124:127], v195 offset:32288
	ds_read_b128 v[128:131], v195 offset:27712
	ds_read_b128 v[132:135], v195 offset:27744
	ds_read_b128 v[136:139], v195 offset:32320
	ds_read_b128 v[140:143], v195 offset:32352
	s_cmp_lg_u32 s27, 4
	s_cselect_b32 s27, s34, 0
	s_waitcnt lgkmcnt(6)
	v_mfma_f32_32x32x16_bf16 v[152:167], v[240:243], v[180:183], v[48:63]
	v_exp_f32_e32 v15, v80
	v_exp_f32_e32 v144, v81
	v_exp_f32_e32 v145, v82
	v_exp_f32_e32 v146, v83
	s_waitcnt lgkmcnt(5)
	v_mfma_f32_32x32x16_bf16 v[96:111], v[244:247], v[180:183], v[48:63]
	v_exp_f32_e32 v147, v84
	v_exp_f32_e32 v148, v85
	v_exp_f32_e32 v149, v86
	v_exp_f32_e32 v150, v87
	v_mfma_f32_32x32x16_bf16 v[152:167], v[116:119], v[176:179], v[152:167]
	v_exp_f32_e32 v120, v88
	v_exp_f32_e32 v121, v89
	v_exp_f32_e32 v122, v90
	v_exp_f32_e32 v123, v91
	s_waitcnt lgkmcnt(4)
	v_mfma_f32_32x32x16_bf16 v[96:111], v[124:127], v[176:179], v[96:111]
	v_exp_f32_e32 v151, v92
	v_exp_f32_e32 v184, v93
	v_exp_f32_e32 v185, v94
	v_exp_f32_e32 v186, v95
	s_waitcnt lgkmcnt(3)
	v_mfma_f32_32x32x16_bf16 v[152:167], v[128:131], v[172:175], v[152:167]
	v_exp_f32_e32 v124, v64
	v_exp_f32_e32 v125, v65
	v_exp_f32_e32 v126, v66
	v_exp_f32_e32 v127, v67
	s_waitcnt lgkmcnt(1)
	v_mfma_f32_32x32x16_bf16 v[96:111], v[136:139], v[172:175], v[96:111]
	v_exp_f32_e32 v128, v68
	v_exp_f32_e32 v129, v69
	v_exp_f32_e32 v130, v70
	v_exp_f32_e32 v131, v71
	v_mfma_f32_32x32x16_bf16 v[152:167], v[132:135], v[168:171], v[152:167]
	v_exp_f32_e32 v136, v72
	v_exp_f32_e32 v137, v73
	v_exp_f32_e32 v138, v74
	v_exp_f32_e32 v139, v75
	s_waitcnt lgkmcnt(0)
	v_mfma_f32_32x32x16_bf16 v[96:111], v[140:143], v[168:171], v[96:111]
	v_exp_f32_e32 v132, v76
	v_exp_f32_e32 v133, v77
	v_exp_f32_e32 v134, v78
	v_exp_f32_e32 v135, v79
	s_cmp_gt_i32 s27, 2
	s_cselect_b32 s28, -3, 2
	s_add_i32 s28, s28, s27
	s_mulk_i32 s28, 0x2400
	s_waitcnt vmcnt(3)
	ds_write_b128 v208, v[6:9] offset:9216
	v_add_u32_e32 v6, s28, v208
	s_add_i32 s28, s27, 1
	s_cmp_lg_u32 s27, 4
	s_cselect_b32 s27, s28, 0
	s_add_i32 s28, s13, -1
	s_min_u32 s28, s28, s12
	s_lshl_b32 s92, s28, 13
	s_waitcnt vmcnt(2)
	ds_write_b128 v6, v[2:5] offset:36864
	v_lshl_add_u64 v[2:3], v[198:199], 0, s[92:93]
	s_lshl_b32 s92, s29, 7
	v_lshl_add_u64 v[4:5], v[196:197], 0, s[92:93]
	global_load_dwordx4 v[6:9], v[2:3], off
	s_nop 0
	global_load_dwordx4 v[2:5], v[4:5], off
	s_mul_i32 s29, s27, 0x2400
	s_add_i32 s34, s29, 0xffffdc00
	s_cmp_lg_u32 s27, 0
	s_cselect_b32 s34, s34, 0x9000
	v_add_u32_e32 v92, s34, v195
	ds_read_b128 v[64:67], v92 offset:36864
	ds_read_b128 v[68:71], v92 offset:36896
	ds_read_b128 v[72:75], v92 offset:41472
	ds_read_b128 v[76:79], v92 offset:41504
	ds_read_b128 v[80:83], v92 offset:36928
	ds_read_b128 v[84:87], v92 offset:36960
	ds_read_b128 v[88:91], v92 offset:41536
	ds_read_b128 v[92:95], v92 offset:41568
	s_setprio 3
	v_mov_b32_e32 v187, 0
	v_cvt_pk_bf16_f32 v116, v15, v144
	v_cvt_pk_bf16_f32 v117, v145, v146
	v_cvt_pk_bf16_f32 v118, v147, v148
	v_cvt_pk_bf16_f32 v119, v149, v150
	s_waitcnt lgkmcnt(7)
	s_nop 0
	v_mfma_f32_32x32x16_bf16 v[16:31], v[64:67], v[116:119], v[16:31]
	v_add_f32_e32 v187, v187, v15
	v_add_f32_e32 v187, v187, v144
	v_add_f32_e32 v187, v187, v145
	v_add_f32_e32 v187, v187, v146
	s_waitcnt lgkmcnt(5)
	v_mfma_f32_32x32x16_bf16 v[32:47], v[72:75], v[116:119], v[32:47]
	v_cvt_pk_bf16_f32 v64, v120, v121
	v_cvt_pk_bf16_f32 v65, v122, v123
	v_cvt_pk_bf16_f32 v66, v151, v184
	v_cvt_pk_bf16_f32 v67, v185, v186
	v_add_f32_e32 v187, v187, v147
	v_add_f32_e32 v187, v187, v148
	v_add_f32_e32 v187, v187, v149
	v_add_f32_e32 v187, v187, v150
	s_nop 0
	v_mfma_f32_32x32x16_bf16 v[16:31], v[68:71], v[64:67], v[16:31]
	v_add_f32_e32 v187, v187, v120
	v_add_f32_e32 v187, v187, v121
	v_add_f32_e32 v187, v187, v122
	v_add_f32_e32 v187, v187, v123
	s_waitcnt lgkmcnt(4)
	v_mfma_f32_32x32x16_bf16 v[32:47], v[76:79], v[64:67], v[32:47]
	v_cvt_pk_bf16_f32 v68, v124, v125
	v_cvt_pk_bf16_f32 v69, v126, v127
	v_cvt_pk_bf16_f32 v70, v128, v129
	v_cvt_pk_bf16_f32 v71, v130, v131
	v_add_f32_e32 v187, v187, v151
	v_add_f32_e32 v187, v187, v184
	v_add_f32_e32 v187, v187, v185
	v_add_f32_e32 v187, v187, v186
	s_waitcnt lgkmcnt(3)
	v_mfma_f32_32x32x16_bf16 v[16:31], v[80:83], v[68:71], v[16:31]
	v_add_f32_e32 v187, v187, v124
	v_add_f32_e32 v187, v187, v125
	v_add_f32_e32 v187, v187, v126
	v_add_f32_e32 v187, v187, v127
	s_waitcnt lgkmcnt(1)
	v_mfma_f32_32x32x16_bf16 v[32:47], v[88:91], v[68:71], v[32:47]
	v_cvt_pk_bf16_f32 v64, v136, v137
	v_cvt_pk_bf16_f32 v65, v138, v139
	v_cvt_pk_bf16_f32 v66, v132, v133
	v_cvt_pk_bf16_f32 v67, v134, v135
	v_add_f32_e32 v187, v187, v128
	v_add_f32_e32 v187, v187, v129
	v_add_f32_e32 v187, v187, v130
	v_add_f32_e32 v187, v187, v131
	s_nop 0
	v_mfma_f32_32x32x16_bf16 v[16:31], v[84:87], v[64:67], v[16:31]
	v_add_f32_e32 v187, v187, v136
	v_add_f32_e32 v187, v187, v137
	v_add_f32_e32 v187, v187, v138
	v_add_f32_e32 v187, v187, v139
	s_waitcnt lgkmcnt(0)
	v_mfma_f32_32x32x16_bf16 v[32:47], v[92:95], v[64:67], v[32:47]
	v_add_f32_e32 v187, v187, v132
	v_add_f32_e32 v187, v187, v133
	v_add_f32_e32 v187, v187, v134
	v_add_f32_e32 v187, v187, v135
	s_setprio 2
	s_waitcnt lgkmcnt(0)
	s_barrier
	ds_read_b128 v[240:243], v195
	ds_read_b128 v[244:247], v195 offset:4608
	ds_read_b128 v[72:75], v195 offset:32
	ds_read_b128 v[76:79], v195 offset:4640
	ds_read_b128 v[80:83], v195 offset:64
	ds_read_b128 v[84:87], v195 offset:4672
	ds_read_b128 v[88:91], v195 offset:96
	ds_read_b128 v[92:95], v195 offset:4704
	v_add_f32_e32 v1, v1, v14
	s_waitcnt lgkmcnt(6)
	v_mfma_f32_32x32x16_bf16 v[136:151], v[240:243], v[180:183], v[48:63]
	v_exp_f32_e32 v14, v152
	v_exp_f32_e32 v15, v153
	v_exp_f32_e32 v116, v154
	v_exp_f32_e32 v117, v155
	v_mfma_f32_32x32x16_bf16 v[120:135], v[244:247], v[180:183], v[48:63]
	v_exp_f32_e32 v118, v156
	v_exp_f32_e32 v119, v157
	v_exp_f32_e32 v184, v158
	v_exp_f32_e32 v185, v159
	s_waitcnt lgkmcnt(5)
	v_mfma_f32_32x32x16_bf16 v[136:151], v[72:75], v[176:179], v[136:151]
	v_exp_f32_e32 v186, v160
	v_exp_f32_e32 v210, v161
	v_exp_f32_e32 v211, v162
	v_exp_f32_e32 v212, v163
	s_waitcnt lgkmcnt(4)
	v_mfma_f32_32x32x16_bf16 v[120:135], v[76:79], v[176:179], v[120:135]
	v_exp_f32_e32 v160, v164
	v_exp_f32_e32 v161, v165
	v_exp_f32_e32 v162, v166
	v_exp_f32_e32 v163, v167
	s_waitcnt lgkmcnt(3)
	v_mfma_f32_32x32x16_bf16 v[136:151], v[80:83], v[172:175], v[136:151]
	v_exp_f32_e32 v164, v96
	v_exp_f32_e32 v165, v97
	v_exp_f32_e32 v166, v98
	v_exp_f32_e32 v167, v99
	s_waitcnt lgkmcnt(2)
	v_mfma_f32_32x32x16_bf16 v[120:135], v[84:87], v[172:175], v[120:135]
	v_exp_f32_e32 v96, v100
	v_exp_f32_e32 v97, v101
	v_exp_f32_e32 v98, v102
	v_exp_f32_e32 v99, v103
	s_waitcnt lgkmcnt(1)
	v_mfma_f32_32x32x16_bf16 v[136:151], v[88:91], v[168:171], v[136:151]
	v_exp_f32_e32 v100, v104
	v_exp_f32_e32 v101, v105
	v_exp_f32_e32 v102, v106
	v_exp_f32_e32 v103, v107
	s_waitcnt lgkmcnt(0)
	v_mfma_f32_32x32x16_bf16 v[120:135], v[92:95], v[168:171], v[120:135]
	v_exp_f32_e32 v104, v108
	v_exp_f32_e32 v105, v109
	v_exp_f32_e32 v106, v110
	v_exp_f32_e32 v107, v111
	s_cmp_gt_i32 s27, 2
	s_cselect_b32 s34, -3, 2
	s_add_i32 s34, s34, s27
	s_mulk_i32 s34, 0x2400
	v_add_u32_e32 v88, s29, v195
	s_min_u32 s29, s13, s12
	s_waitcnt vmcnt(3)
	ds_write_b128 v208, v[10:13] offset:18432
	v_add_u32_e32 v10, s34, v208
	s_lshl_b32 s92, s29, 13
	s_waitcnt vmcnt(2)
	ds_write_b128 v10, v[112:115] offset:36864
	v_lshl_add_u64 v[10:11], v[198:199], 0, s[92:93]
	s_lshl_b32 s92, s28, 7
	global_load_dwordx4 v[152:155], v[10:11], off
	v_lshl_add_u64 v[10:11], v[196:197], 0, s[92:93]
	global_load_dwordx4 v[156:159], v[10:11], off
	ds_read_b128 v[240:243], v195 offset:9216
	ds_read_b128 v[244:247], v195 offset:13824
	ds_read_b128 v[10:13], v88 offset:41472
	ds_read_b128 v[64:67], v88 offset:36864
	ds_read_b128 v[68:71], v88 offset:36896
	ds_read_b128 v[72:75], v88 offset:41504
	ds_read_b128 v[76:79], v88 offset:36928
	ds_read_b128 v[80:83], v88 offset:41536
	ds_read_b128 v[84:87], v88 offset:36960
	ds_read_b128 v[88:91], v88 offset:41568
	v_add_f32_e32 v1, v1, v187
	s_setprio 1
	v_mov_b32_e32 v108, 0
	v_mov_b32_e32 v109, v136
	v_cvt_pk_bf16_f32 v92, v14, v15
	v_cvt_pk_bf16_f32 v93, v116, v117
	v_cvt_pk_bf16_f32 v94, v118, v119
	v_cvt_pk_bf16_f32 v95, v184, v185
	s_waitcnt lgkmcnt(6)
	s_nop 0
	v_mfma_f32_32x32x16_bf16 v[16:31], v[64:67], v[92:95], v[16:31]
	v_max3_f32 v109, v109, v137, v138
	v_max3_f32 v109, v109, v139, v140
	v_add_f32_e32 v108, v108, v14
	v_add_f32_e32 v108, v108, v15
	v_add_f32_e32 v108, v108, v116
	v_add_f32_e32 v108, v108, v117
	s_nop 0
	v_mfma_f32_32x32x16_bf16 v[32:47], v[10:13], v[92:95], v[32:47]
	v_cvt_pk_bf16_f32 v64, v186, v210
	v_cvt_pk_bf16_f32 v65, v211, v212
	v_cvt_pk_bf16_f32 v66, v160, v161
	v_cvt_pk_bf16_f32 v67, v162, v163
	v_max3_f32 v109, v109, v141, v142
	v_max3_f32 v109, v109, v143, v144
	v_add_f32_e32 v108, v108, v118
	v_add_f32_e32 v108, v108, v119
	v_add_f32_e32 v108, v108, v184
	v_add_f32_e32 v108, v108, v185
	s_waitcnt lgkmcnt(5)
	v_mfma_f32_32x32x16_bf16 v[16:31], v[68:71], v[64:67], v[16:31]
	v_max3_f32 v109, v109, v145, v146
	v_max3_f32 v109, v109, v147, v148
	v_add_f32_e32 v108, v108, v186
	v_add_f32_e32 v108, v108, v210
	v_add_f32_e32 v108, v108, v211
	v_add_f32_e32 v108, v108, v212
	s_waitcnt lgkmcnt(4)
	v_mfma_f32_32x32x16_bf16 v[32:47], v[72:75], v[64:67], v[32:47]
	v_cvt_pk_bf16_f32 v10, v164, v165
	v_cvt_pk_bf16_f32 v11, v166, v167
	v_cvt_pk_bf16_f32 v12, v96, v97
	v_cvt_pk_bf16_f32 v13, v98, v99
	v_max3_f32 v109, v109, v149, v150
	v_max3_f32 v109, v109, v151, v120
	v_add_f32_e32 v108, v108, v160
	v_add_f32_e32 v108, v108, v161
	v_add_f32_e32 v108, v108, v162
	v_add_f32_e32 v108, v108, v163
	s_waitcnt lgkmcnt(3)
	v_mfma_f32_32x32x16_bf16 v[16:31], v[76:79], v[10:13], v[16:31]
	v_max3_f32 v109, v109, v121, v122
	v_max3_f32 v109, v109, v123, v124
	v_add_f32_e32 v108, v108, v164
	v_add_f32_e32 v108, v108, v165
	v_add_f32_e32 v108, v108, v166
	v_add_f32_e32 v108, v108, v167
	s_waitcnt lgkmcnt(2)
	v_mfma_f32_32x32x16_bf16 v[32:47], v[80:83], v[10:13], v[32:47]
	v_cvt_pk_bf16_f32 v64, v100, v101
	v_cvt_pk_bf16_f32 v65, v102, v103
	v_cvt_pk_bf16_f32 v66, v104, v105
	v_cvt_pk_bf16_f32 v67, v106, v107
	v_max3_f32 v109, v109, v125, v126
	v_max3_f32 v109, v109, v127, v128
	v_add_f32_e32 v108, v108, v96
	v_add_f32_e32 v108, v108, v97
	v_add_f32_e32 v108, v108, v98
	v_add_f32_e32 v108, v108, v99
	s_waitcnt lgkmcnt(1)
	v_mfma_f32_32x32x16_bf16 v[16:31], v[84:87], v[64:67], v[16:31]
	v_max3_f32 v109, v109, v129, v130
	v_max3_f32 v109, v109, v131, v132
	v_add_f32_e32 v108, v108, v100
	v_add_f32_e32 v108, v108, v101
	v_add_f32_e32 v108, v108, v102
	v_add_f32_e32 v108, v108, v103
	s_waitcnt lgkmcnt(0)
	v_mfma_f32_32x32x16_bf16 v[32:47], v[88:91], v[64:67], v[32:47]
	v_max3_f32 v109, v109, v133, v134
	v_max3_f32 v109, v109, v135, v135
	v_add_f32_e32 v108, v108, v104
	v_add_f32_e32 v108, v108, v105
	v_add_f32_e32 v108, v108, v106
	v_add_f32_e32 v108, v108, v107
	s_setprio 0
	ds_read_b128 v[164:167], v195 offset:9248
	ds_read_b128 v[160:163], v195 offset:13856
	ds_read_b128 v[74:77], v195 offset:9280
	ds_read_b128 v[66:69], v195 offset:9312
	ds_read_b128 v[70:73], v195 offset:13888
	ds_read_b128 v[10:13], v195 offset:13920
	v_add_f32_e32 v64, v1, v108
	v_mov_b32_e32 v1, v109
	s_nop 1
	v_permlane32_swap_b32_e32 v109, v1
	v_max_f32_e32 v1, v1, v1
	v_max_f32_e32 v14, v109, v109
	v_max_f32_e32 v1, v14, v1
	v_cmp_lt_f32_e32 vcc, s52, v1
	s_cbranch_vccz .LBB0_663
	v_max_f32_e32 v1, v1, v1
	v_max_f32_e32 v14, 0, v1
	v_add_f32_e32 v209, v209, v14
	v_xor_b32_e32 v48, 0x80000000, v209
	v_pk_add_f32 v[136:137], v[136:137], v[14:15] op_sel_hi:[1,0] neg_lo:[0,1] neg_hi:[0,1]
	v_pk_add_f32 v[120:121], v[120:121], v[14:15] op_sel_hi:[1,0] neg_lo:[0,1] neg_hi:[0,1]
	v_pk_add_f32 v[138:139], v[138:139], v[14:15] op_sel_hi:[1,0] neg_lo:[0,1] neg_hi:[0,1]
	v_pk_add_f32 v[122:123], v[122:123], v[14:15] op_sel_hi:[1,0] neg_lo:[0,1] neg_hi:[0,1]
	v_pk_add_f32 v[140:141], v[140:141], v[14:15] op_sel_hi:[1,0] neg_lo:[0,1] neg_hi:[0,1]
	v_pk_add_f32 v[124:125], v[124:125], v[14:15] op_sel_hi:[1,0] neg_lo:[0,1] neg_hi:[0,1]
	v_pk_add_f32 v[142:143], v[142:143], v[14:15] op_sel_hi:[1,0] neg_lo:[0,1] neg_hi:[0,1]
	v_pk_add_f32 v[126:127], v[126:127], v[14:15] op_sel_hi:[1,0] neg_lo:[0,1] neg_hi:[0,1]
	v_pk_add_f32 v[144:145], v[144:145], v[14:15] op_sel_hi:[1,0] neg_lo:[0,1] neg_hi:[0,1]
	v_pk_add_f32 v[128:129], v[128:129], v[14:15] op_sel_hi:[1,0] neg_lo:[0,1] neg_hi:[0,1]
	v_pk_add_f32 v[146:147], v[146:147], v[14:15] op_sel_hi:[1,0] neg_lo:[0,1] neg_hi:[0,1]
	v_pk_add_f32 v[130:131], v[130:131], v[14:15] op_sel_hi:[1,0] neg_lo:[0,1] neg_hi:[0,1]
	v_pk_add_f32 v[148:149], v[148:149], v[14:15] op_sel_hi:[1,0] neg_lo:[0,1] neg_hi:[0,1]
	v_pk_add_f32 v[132:133], v[132:133], v[14:15] op_sel_hi:[1,0] neg_lo:[0,1] neg_hi:[0,1]
	v_pk_add_f32 v[150:151], v[150:151], v[14:15] op_sel_hi:[1,0] neg_lo:[0,1] neg_hi:[0,1]
	v_pk_add_f32 v[134:135], v[134:135], v[14:15] op_sel_hi:[1,0] neg_lo:[0,1] neg_hi:[0,1]
	v_exp_f32_e64 v14, -v14
	v_mov_b32_e32 v49, v48
	v_mov_b32_e32 v50, v48
	v_mov_b32_e32 v51, v48
	v_mov_b32_e32 v52, v48
	v_mov_b32_e32 v53, v48
	v_mov_b32_e32 v54, v48
	v_mov_b32_e32 v55, v48
	v_mov_b32_e32 v56, v48
	v_mov_b32_e32 v57, v48
	v_mov_b32_e32 v58, v48
	v_mov_b32_e32 v59, v48
	v_mov_b32_e32 v60, v48
	v_mov_b32_e32 v61, v48
	v_mov_b32_e32 v62, v48
	v_mov_b32_e32 v63, v48
	s_nop 11
	v_pk_mul_f32 v[30:31], v[30:31], v[14:15] op_sel_hi:[1,0]
	v_pk_mul_f32 v[28:29], v[28:29], v[14:15] op_sel_hi:[1,0]
	v_pk_mul_f32 v[26:27], v[26:27], v[14:15] op_sel_hi:[1,0]
	v_pk_mul_f32 v[24:25], v[24:25], v[14:15] op_sel_hi:[1,0]
	v_pk_mul_f32 v[22:23], v[22:23], v[14:15] op_sel_hi:[1,0]
	v_pk_mul_f32 v[20:21], v[20:21], v[14:15] op_sel_hi:[1,0]
	v_pk_mul_f32 v[18:19], v[18:19], v[14:15] op_sel_hi:[1,0]
	v_pk_mul_f32 v[16:17], v[16:17], v[14:15] op_sel_hi:[1,0]
	v_pk_mul_f32 v[46:47], v[46:47], v[14:15] op_sel_hi:[1,0]
	v_pk_mul_f32 v[44:45], v[44:45], v[14:15] op_sel_hi:[1,0]
	v_pk_mul_f32 v[42:43], v[42:43], v[14:15] op_sel_hi:[1,0]
	v_pk_mul_f32 v[40:41], v[40:41], v[14:15] op_sel_hi:[1,0]
	v_pk_mul_f32 v[38:39], v[38:39], v[14:15] op_sel_hi:[1,0]
	v_pk_mul_f32 v[36:37], v[36:37], v[14:15] op_sel_hi:[1,0]
	v_pk_mul_f32 v[34:35], v[34:35], v[14:15] op_sel_hi:[1,0]
	v_pk_mul_f32 v[32:33], v[32:33], v[14:15] op_sel_hi:[1,0]
	v_mul_f32_e32 v64, v64, v14

.LBB0_697:
	s_add_i32 s22, s45, s18
	s_ashr_i32 s23, s22, 31
	s_lshl_b64 s[24:25], s[22:23], 13
	s_lshl_b32 s22, s22, 6
	v_lshl_add_u64 v[2:3], v[198:199], 0, s[24:25]
	s_sub_i32 s24, s22, 64
	s_ashr_i32 s25, s24, 31
	v_lshl_add_u64 v[4:5], s[24:25], 1, v[196:197]
	global_load_dwordx4 v[6:9], v[2:3], off
	s_nop 0
	global_load_dwordx4 v[2:5], v[4:5], off
	s_mul_i32 s2, s34, 0x2400
	s_add_i32 s23, s2, 0xffffdc00
	s_cmp_lg_u32 s34, 0
	s_cselect_b32 s23, s23, 0x9000
	v_add_u32_e32 v1, s23, v201
	ds_read_b128 v[10:13], v1 offset:36864
	ds_read_b128 v[66:69], v1 offset:36896
	ds_read_b128 v[70:73], v1 offset:41472
	ds_read_b128 v[74:77], v1 offset:41504
	ds_read_b128 v[128:131], v1 offset:36928
	ds_read_b128 v[132:135], v1 offset:36960
	ds_read_b128 v[136:139], v1 offset:41536
	ds_read_b128 v[142:145], v1 offset:41568
	s_setprio 3
	v_mov_b32_e32 v1, 0
	v_cvt_pk_bf16_f32 v178, v116, v117
	v_cvt_pk_bf16_f32 v179, v118, v119
	v_cvt_pk_bf16_f32 v180, v112, v113
	v_cvt_pk_bf16_f32 v181, v114, v115
	s_waitcnt lgkmcnt(7)
	s_nop 0
	v_mfma_f32_32x32x16_bf16 v[16:31], v[10:13], v[178:181], v[16:31]
	v_add_f32_e32 v1, v1, v116
	v_add_f32_e32 v1, v1, v117
	v_add_f32_e32 v1, v1, v118
	v_add_f32_e32 v1, v1, v119
	s_waitcnt lgkmcnt(5)
	v_mfma_f32_32x32x16_bf16 v[32:47], v[70:73], v[178:181], v[32:47]
	v_cvt_pk_bf16_f32 v10, v208, v207
	v_cvt_pk_bf16_f32 v11, v206, v205
	v_cvt_pk_bf16_f32 v12, v204, v187
	v_cvt_pk_bf16_f32 v13, v186, v185
	v_add_f32_e32 v1, v1, v112
	v_add_f32_e32 v1, v1, v113
	v_add_f32_e32 v1, v1, v114
	v_add_f32_e32 v1, v1, v115
	s_nop 0
	v_mfma_f32_32x32x16_bf16 v[16:31], v[66:69], v[10:13], v[16:31]
	v_add_f32_e32 v1, v1, v208
	v_add_f32_e32 v1, v1, v207
	v_add_f32_e32 v1, v1, v206
	v_add_f32_e32 v1, v1, v205
	s_waitcnt lgkmcnt(4)
	v_mfma_f32_32x32x16_bf16 v[32:47], v[74:77], v[10:13], v[32:47]
	v_cvt_pk_bf16_f32 v66, v177, v176
	v_cvt_pk_bf16_f32 v67, v149, v148
	v_cvt_pk_bf16_f32 v68, v147, v146
	v_cvt_pk_bf16_f32 v69, v141, v140
	v_add_f32_e32 v1, v1, v204
	v_add_f32_e32 v1, v1, v187
	v_add_f32_e32 v1, v1, v186
	v_add_f32_e32 v1, v1, v185
	s_waitcnt lgkmcnt(3)
	v_mfma_f32_32x32x16_bf16 v[16:31], v[128:131], v[66:69], v[16:31]
	v_add_f32_e32 v1, v1, v177
	v_add_f32_e32 v1, v1, v176
	v_add_f32_e32 v1, v1, v149
	v_add_f32_e32 v1, v1, v148
	s_waitcnt lgkmcnt(1)
	v_mfma_f32_32x32x16_bf16 v[32:47], v[136:139], v[66:69], v[32:47]
	v_cvt_pk_bf16_f32 v10, v123, v122
	v_cvt_pk_bf16_f32 v11, v121, v120
	v_cvt_pk_bf16_f32 v12, v127, v126
	v_cvt_pk_bf16_f32 v13, v125, v124
	v_add_f32_e32 v1, v1, v147
	v_add_f32_e32 v1, v1, v146
	v_add_f32_e32 v1, v1, v141
	v_add_f32_e32 v1, v1, v140
	s_nop 0
	v_mfma_f32_32x32x16_bf16 v[16:31], v[132:135], v[10:13], v[16:31]
	v_add_f32_e32 v1, v1, v123
	v_add_f32_e32 v1, v1, v122
	v_add_f32_e32 v1, v1, v121
	v_add_f32_e32 v1, v1, v120
	s_waitcnt lgkmcnt(0)
	v_mfma_f32_32x32x16_bf16 v[32:47], v[142:145], v[10:13], v[32:47]
	v_add_f32_e32 v1, v1, v127
	v_add_f32_e32 v1, v1, v126
	v_add_f32_e32 v1, v1, v125
	v_add_f32_e32 v1, v1, v124
	s_setprio 2
	s_waitcnt lgkmcnt(0)
	s_barrier
	ds_read_b128 v[240:243], v201 offset:18432
	ds_read_b128 v[244:247], v201 offset:23040
	ds_read_b128 v[66:69], v201 offset:18464
	ds_read_b128 v[76:79], v201 offset:23072
	ds_read_b128 v[144:147], v201 offset:18496
	ds_read_b128 v[176:179], v201 offset:18528
	ds_read_b128 v[204:207], v201 offset:23104
	ds_read_b128 v[208:211], v201 offset:23136
	s_waitcnt lgkmcnt(6)
	v_mfma_f32_32x32x16_bf16 v[128:143], v[240:243], v[164:167], v[48:63]
	v_exp_f32_e32 v148, v96
	v_exp_f32_e32 v149, v97
	v_exp_f32_e32 v150, v98
	v_exp_f32_e32 v151, v99
	s_waitcnt lgkmcnt(5)
	v_mfma_f32_32x32x16_bf16 v[112:127], v[244:247], v[164:167], v[48:63]
	v_exp_f32_e32 v96, v100
	v_exp_f32_e32 v97, v101
	v_exp_f32_e32 v98, v102
	v_exp_f32_e32 v99, v103
	v_mfma_f32_32x32x16_bf16 v[128:143], v[66:69], v[160:163], v[128:143]
	v_exp_f32_e32 v100, v104
	v_exp_f32_e32 v101, v105
	v_exp_f32_e32 v102, v106
	v_exp_f32_e32 v103, v107
	s_waitcnt lgkmcnt(4)
	v_mfma_f32_32x32x16_bf16 v[112:127], v[76:79], v[160:163], v[112:127]
	v_exp_f32_e32 v71, v108
	v_exp_f32_e32 v72, v109
	v_exp_f32_e32 v73, v110
	v_exp_f32_e32 v74, v111
	s_waitcnt lgkmcnt(3)
	v_mfma_f32_32x32x16_bf16 v[128:143], v[144:147], v[156:159], v[128:143]
	v_exp_f32_e32 v75, v80
	v_exp_f32_e32 v76, v81
	v_exp_f32_e32 v77, v82
	v_exp_f32_e32 v78, v83
	s_waitcnt lgkmcnt(1)
	v_mfma_f32_32x32x16_bf16 v[112:127], v[204:207], v[156:159], v[112:127]
	v_exp_f32_e32 v14, v84
	v_exp_f32_e32 v15, v85
	v_exp_f32_e32 v65, v86
	v_exp_f32_e32 v66, v87
	v_mfma_f32_32x32x16_bf16 v[128:143], v[176:179], v[152:155], v[128:143]
	v_exp_f32_e32 v67, v88
	v_exp_f32_e32 v68, v89
	v_exp_f32_e32 v69, v90
	v_exp_f32_e32 v70, v91
	s_waitcnt lgkmcnt(0)
	v_mfma_f32_32x32x16_bf16 v[112:127], v[208:211], v[152:155], v[112:127]
	v_exp_f32_e32 v79, v92
	v_exp_f32_e32 v80, v93
	v_exp_f32_e32 v81, v94
	v_exp_f32_e32 v82, v95
	s_cmp_lt_u32 s45, 3
	s_cbranch_scc1 .LBB0_699
	s_add_i32 s23, s19, s45
	v_lshl_add_u32 v10, s23, 6, v184
	v_add_u32_e32 v11, 0xffffff7f, v10
	v_cmp_lt_u32_e32 vcc, s53, v11
	v_add_u32_e32 v11, 0xffffff9f, v10
	s_nop 7
	s_nop 3
	s_nop 0
	v_cndmask_b32_e32 v128, v233, v128, vcc
	v_cmp_lt_u32_e32 vcc, s53, v11
	v_add_u32_e32 v11, 0xffffff80, v10
	s_nop 0
	v_cndmask_b32_e32 v112, v233, v112, vcc
	v_cmp_lt_u32_e32 vcc, s53, v11
	v_add_u32_e32 v11, 0xffffffa0, v10
	s_nop 0
	v_cndmask_b32_e32 v129, v233, v129, vcc
	v_cmp_lt_u32_e32 vcc, s53, v11
	v_add_u32_e32 v11, 0xffffff81, v10
	s_nop 0
	v_cndmask_b32_e32 v113, v233, v113, vcc
	v_cmp_lt_u32_e32 vcc, s53, v11
	v_add_u32_e32 v11, 0xffffffa1, v10
	s_nop 0
	v_cndmask_b32_e32 v130, v233, v130, vcc
	v_cmp_lt_u32_e32 vcc, s53, v11
	v_add_u32_e32 v11, 0xffffff82, v10
	s_nop 0
	v_cndmask_b32_e32 v114, v233, v114, vcc
	v_cmp_lt_u32_e32 vcc, s53, v11
	v_add_u32_e32 v11, 0xffffffa2, v10
	s_nop 0
	v_cndmask_b32_e32 v131, v233, v131, vcc
	v_cmp_lt_u32_e32 vcc, s53, v11
	v_add_u32_e32 v11, 0xffffff87, v10
	s_nop 0
	v_cndmask_b32_e32 v115, v233, v115, vcc
	v_cmp_lt_u32_e32 vcc, s53, v11
	v_add_u32_e32 v11, 0xffffffa7, v10
	s_nop 0
	v_cndmask_b32_e32 v132, v233, v132, vcc
	v_cmp_lt_u32_e32 vcc, s53, v11
	v_add_u32_e32 v11, 0xffffff88, v10
	s_nop 0
	v_cndmask_b32_e32 v116, v233, v116, vcc
	v_cmp_lt_u32_e32 vcc, s53, v11
	v_add_u32_e32 v11, 0xffffffa8, v10
	s_nop 0
	v_cndmask_b32_e32 v133, v233, v133, vcc
	v_cmp_lt_u32_e32 vcc, s53, v11
	v_add_u32_e32 v11, 0xffffff89, v10
	s_nop 0
	v_cndmask_b32_e32 v117, v233, v117, vcc
	v_cmp_lt_u32_e32 vcc, s53, v11
	v_add_u32_e32 v11, 0xffffffa9, v10
	s_nop 0
	v_cndmask_b32_e32 v134, v233, v134, vcc
	v_cmp_lt_u32_e32 vcc, s53, v11
	v_add_u32_e32 v11, 0xffffff8a, v10
	s_nop 0
	v_cndmask_b32_e32 v118, v233, v118, vcc
	v_cmp_lt_u32_e32 vcc, s53, v11
	v_add_u32_e32 v11, 0xffffffaa, v10
	s_nop 0
	v_cndmask_b32_e32 v135, v233, v135, vcc
	v_cmp_lt_u32_e32 vcc, s53, v11
	v_add_u32_e32 v11, 0xffffff8f, v10
	s_nop 0
	v_cndmask_b32_e32 v119, v233, v119, vcc
	v_cmp_lt_u32_e32 vcc, s53, v11
	v_add_u32_e32 v11, 0xffffffaf, v10
	s_nop 0
	v_cndmask_b32_e32 v136, v233, v136, vcc
	v_cmp_lt_u32_e32 vcc, s53, v11
	v_add_u32_e32 v11, 0xffffff90, v10
	s_nop 0
	v_cndmask_b32_e32 v120, v233, v120, vcc
	v_cmp_lt_u32_e32 vcc, s53, v11
	v_add_u32_e32 v11, 0xffffffb0, v10
	s_nop 0
	v_cndmask_b32_e32 v137, v233, v137, vcc
	v_cmp_lt_u32_e32 vcc, s53, v11
	v_add_u32_e32 v11, 0xffffff91, v10
	s_nop 0
	v_cndmask_b32_e32 v121, v233, v121, vcc
	v_cmp_lt_u32_e32 vcc, s53, v11
	v_add_u32_e32 v11, 0xffffffb1, v10
	s_nop 0
	v_cndmask_b32_e32 v138, v233, v138, vcc
	v_cmp_lt_u32_e32 vcc, s53, v11
	v_add_u32_e32 v11, 0xffffff92, v10
	s_nop 0
	v_cndmask_b32_e32 v122, v233, v122, vcc
	v_cmp_lt_u32_e32 vcc, s53, v11
	v_add_u32_e32 v11, 0xffffffb2, v10
	s_nop 0
	v_cndmask_b32_e32 v139, v233, v139, vcc
	v_cmp_lt_u32_e32 vcc, s53, v11
	v_add_u32_e32 v11, 0xffffff97, v10
	s_nop 0
	v_cndmask_b32_e32 v123, v233, v123, vcc
	v_cmp_lt_u32_e32 vcc, s53, v11
	v_add_u32_e32 v11, 0xffffffb7, v10
	s_nop 0
	v_cndmask_b32_e32 v140, v233, v140, vcc
	v_cmp_lt_u32_e32 vcc, s53, v11
	v_add_u32_e32 v11, 0xffffff98, v10
	s_nop 0
	v_cndmask_b32_e32 v124, v233, v124, vcc
	v_cmp_lt_u32_e32 vcc, s53, v11
	v_add_u32_e32 v11, 0xffffffb8, v10
	s_nop 0
	v_cndmask_b32_e32 v141, v233, v141, vcc
	v_cmp_lt_u32_e32 vcc, s53, v11
	v_add_u32_e32 v11, 0xffffff99, v10
	s_nop 0
	v_cndmask_b32_e32 v125, v233, v125, vcc
	v_cmp_lt_u32_e32 vcc, s53, v11
	v_add_u32_e32 v11, 0xffffffb9, v10
	s_nop 0
	v_cndmask_b32_e32 v142, v233, v142, vcc
	v_cmp_lt_u32_e32 vcc, s53, v11
	v_add_u32_e32 v11, 0xffffff9a, v10
	v_add_u32_e32 v10, 0xffffffba, v10
	v_cndmask_b32_e32 v126, v233, v126, vcc
	v_cmp_lt_u32_e32 vcc, s53, v11
	s_nop 1
	v_cndmask_b32_e32 v143, v233, v143, vcc
	v_cmp_lt_u32_e32 vcc, s53, v10
	s_nop 1
	v_cndmask_b32_e32 v127, v233, v127, vcc

.LBB0_701:
	s_add_i32 s2, s34, 1
	s_cmp_lg_u32 s34, 4
	s_cselect_b32 s2, s2, 0
	s_cmp_gt_i32 s2, 2
	s_cselect_b32 s23, -3, 2
	s_add_i32 s23, s23, s2
	s_mulk_i32 s23, 0x2400
	s_waitcnt vmcnt(3)
	ds_write_b128 v203, v[6:9] offset:9216
	v_add_u32_e32 v6, s23, v203
	s_add_i32 s23, s2, 1
	s_cmp_lg_u32 s2, 4
	s_cselect_b32 s23, s23, 0
	s_add_i32 s2, s45, 6
	s_add_i32 s34, s2, s13
	s_ashr_i32 s35, s34, 31
	s_lshl_b32 s26, s26, 6
	s_lshl_b64 vcc, s[34:35], 13
	s_ashr_i32 s27, s26, 31
	s_waitcnt vmcnt(2)
	ds_write_b128 v6, v[2:5] offset:36864
	v_lshl_add_u64 v[2:3], v[198:199], 0, vcc
	v_lshl_add_u64 v[6:7], s[26:27], 1, v[196:197]
	global_load_dwordx4 v[2:5], v[2:3], off
	s_mul_i32 s25, s23, 0x2400
	global_load_dwordx4 v[6:9], v[6:7], off
	s_add_i32 s26, s25, 0xffffdc00
	s_cmp_lg_u32 s23, 0
	s_cselect_b32 s26, s26, 0x9000
	v_add_f32_e32 v1, v64, v1
	v_add_u32_e32 v64, s26, v201
	v_add_f32_e32 v1, v1, v168
	ds_read_b128 v[116:119], v64 offset:41472
	ds_read_b128 v[120:123], v64 offset:36864
	ds_read_b128 v[124:127], v64 offset:36896
	ds_read_b128 v[136:139], v64 offset:41504
	ds_read_b128 v[140:143], v64 offset:36928
	ds_read_b128 v[168:171], v64 offset:41536
	ds_read_b128 v[172:175], v64 offset:36960
	ds_read_b128 v[176:179], v64 offset:41568
	s_setprio 3
	v_mov_b32_e32 v180, 0
	v_cvt_pk_bf16_f32 v204, v148, v149
	v_cvt_pk_bf16_f32 v205, v150, v151
	v_cvt_pk_bf16_f32 v206, v128, v129
	v_cvt_pk_bf16_f32 v207, v130, v131
	s_waitcnt lgkmcnt(6)
	s_nop 0
	v_mfma_f32_32x32x16_bf16 v[16:31], v[120:123], v[204:207], v[16:31]
	v_add_f32_e32 v180, v180, v148
	v_add_f32_e32 v180, v180, v149
	v_add_f32_e32 v180, v180, v150
	v_add_f32_e32 v180, v180, v151
	s_nop 0
	v_mfma_f32_32x32x16_bf16 v[32:47], v[116:119], v[204:207], v[32:47]
	v_cvt_pk_bf16_f32 v120, v132, v133
	v_cvt_pk_bf16_f32 v121, v134, v135
	v_cvt_pk_bf16_f32 v122, v71, v72
	v_cvt_pk_bf16_f32 v123, v73, v74
	v_add_f32_e32 v180, v180, v128
	v_add_f32_e32 v180, v180, v129
	v_add_f32_e32 v180, v180, v130
	v_add_f32_e32 v180, v180, v131
	s_waitcnt lgkmcnt(5)
	v_mfma_f32_32x32x16_bf16 v[16:31], v[124:127], v[120:123], v[16:31]
	v_add_f32_e32 v180, v180, v132
	v_add_f32_e32 v180, v180, v133
	v_add_f32_e32 v180, v180, v134
	v_add_f32_e32 v180, v180, v135
	s_waitcnt lgkmcnt(4)
	v_mfma_f32_32x32x16_bf16 v[32:47], v[136:139], v[120:123], v[32:47]
	v_cvt_pk_bf16_f32 v116, v75, v76
	v_cvt_pk_bf16_f32 v117, v77, v78
	v_cvt_pk_bf16_f32 v118, v14, v15
	v_cvt_pk_bf16_f32 v119, v65, v66
	v_add_f32_e32 v180, v180, v71
	v_add_f32_e32 v180, v180, v72
	v_add_f32_e32 v180, v180, v73
	v_add_f32_e32 v180, v180, v74
	s_waitcnt lgkmcnt(3)
	v_mfma_f32_32x32x16_bf16 v[16:31], v[140:143], v[116:119], v[16:31]
	v_add_f32_e32 v180, v180, v75
	v_add_f32_e32 v180, v180, v76
	v_add_f32_e32 v180, v180, v77
	v_add_f32_e32 v180, v180, v78
	s_waitcnt lgkmcnt(2)
	v_mfma_f32_32x32x16_bf16 v[32:47], v[168:171], v[116:119], v[32:47]
	v_cvt_pk_bf16_f32 v72, v67, v68
	v_cvt_pk_bf16_f32 v73, v69, v70
	v_cvt_pk_bf16_f32 v74, v79, v112
	v_cvt_pk_bf16_f32 v75, v113, v114
	v_add_f32_e32 v180, v180, v14
	v_add_f32_e32 v180, v180, v15
	v_add_f32_e32 v180, v180, v65
	v_add_f32_e32 v180, v180, v66
	s_waitcnt lgkmcnt(1)
	v_mfma_f32_32x32x16_bf16 v[16:31], v[172:175], v[72:75], v[16:31]
	v_add_f32_e32 v180, v180, v67
	v_add_f32_e32 v180, v180, v68
	v_add_f32_e32 v180, v180, v69
	v_add_f32_e32 v180, v180, v70
	s_waitcnt lgkmcnt(0)
	v_mfma_f32_32x32x16_bf16 v[32:47], v[176:179], v[72:75], v[32:47]
	v_add_f32_e32 v180, v180, v79
	v_add_f32_e32 v180, v180, v112
	v_add_f32_e32 v180, v180, v113
	v_add_f32_e32 v180, v180, v114
	s_setprio 2
	s_waitcnt lgkmcnt(0)
	s_barrier
	ds_read_b128 v[240:243], v201
	ds_read_b128 v[244:247], v201 offset:4608
	ds_read_b128 v[128:131], v201 offset:32
	ds_read_b128 v[136:139], v201 offset:4640
	ds_read_b128 v[172:175], v201 offset:64
	ds_read_b128 v[176:179], v201 offset:96
	ds_read_b128 v[204:207], v201 offset:4672
	ds_read_b128 v[208:211], v201 offset:4704
	s_waitcnt lgkmcnt(6)
	v_mfma_f32_32x32x16_bf16 v[64:79], v[240:243], v[164:167], v[48:63]
	v_exp_f32_e32 v168, v96
	v_exp_f32_e32 v169, v97
	v_exp_f32_e32 v170, v98
	v_exp_f32_e32 v171, v99
	s_waitcnt lgkmcnt(5)
	v_mfma_f32_32x32x16_bf16 v[112:127], v[244:247], v[164:167], v[48:63]
	v_exp_f32_e32 v140, v100
	v_exp_f32_e32 v141, v101
	v_exp_f32_e32 v142, v102
	v_exp_f32_e32 v143, v103
	v_mfma_f32_32x32x16_bf16 v[64:79], v[128:131], v[160:163], v[64:79]
	v_exp_f32_e32 v148, v104
	v_exp_f32_e32 v149, v105
	v_exp_f32_e32 v150, v106
	v_exp_f32_e32 v151, v107
	s_waitcnt lgkmcnt(4)
	v_mfma_f32_32x32x16_bf16 v[112:127], v[136:139], v[160:163], v[112:127]
	v_exp_f32_e32 v132, v108
	v_exp_f32_e32 v133, v109
	v_exp_f32_e32 v134, v110
	v_exp_f32_e32 v135, v111
	s_waitcnt lgkmcnt(3)
	v_mfma_f32_32x32x16_bf16 v[64:79], v[172:175], v[156:159], v[64:79]
	v_exp_f32_e32 v136, v80
	v_exp_f32_e32 v137, v81
	v_exp_f32_e32 v138, v82
	v_exp_f32_e32 v139, v83
	s_waitcnt lgkmcnt(1)
	v_mfma_f32_32x32x16_bf16 v[112:127], v[204:207], v[156:159], v[112:127]
	v_exp_f32_e32 v128, v84
	v_exp_f32_e32 v129, v85
	v_exp_f32_e32 v130, v86
	v_exp_f32_e32 v131, v87
	v_mfma_f32_32x32x16_bf16 v[64:79], v[176:179], v[152:155], v[64:79]
	v_exp_f32_e32 v84, v88
	v_exp_f32_e32 v85, v89
	v_exp_f32_e32 v86, v90
	v_exp_f32_e32 v87, v91
	s_waitcnt lgkmcnt(0)
	v_mfma_f32_32x32x16_bf16 v[112:127], v[208:211], v[152:155], v[112:127]
	v_exp_f32_e32 v88, v92
	v_exp_f32_e32 v89, v93
	v_exp_f32_e32 v90, v94
	v_exp_f32_e32 v91, v95
	v_sub_u32_e32 v14, s24, v202
	v_add_u32_e32 v14, v14, v183
	v_add_u32_e32 v15, 0xffffff7f, v14
	v_cmp_lt_u32_e32 vcc, s53, v15
	v_add_u32_e32 v15, 0xffffff9f, v14
	s_cmp_gt_i32 s23, 2
	v_cndmask_b32_e32 v80, v233, v64, vcc
	v_cmp_lt_u32_e32 vcc, s53, v15
	v_add_u32_e32 v64, 0xffffff80, v14
	s_cselect_b32 s24, -3, 2
	v_cndmask_b32_e32 v15, v233, v112, vcc
	v_cmp_lt_u32_e32 vcc, s53, v64
	v_add_u32_e32 v64, 0xffffffa0, v14
	s_add_i32 s24, s24, s23
	v_cndmask_b32_e32 v81, v233, v65, vcc
	v_cmp_lt_u32_e32 vcc, s53, v64
	v_add_u32_e32 v64, 0xffffff81, v14
	s_mulk_i32 s24, 0x2400
	v_cndmask_b32_e32 v100, v233, v113, vcc
	v_cmp_lt_u32_e32 vcc, s53, v64
	v_add_u32_e32 v64, 0xffffffa1, v14
	s_add_i32 s27, s77, s18
	v_cndmask_b32_e32 v82, v233, v66, vcc
	v_cmp_lt_u32_e32 vcc, s53, v64
	v_add_u32_e32 v64, 0xffffff82, v14
	s_nop 7
	s_nop 3
	s_waitcnt vmcnt(3)
	ds_write_b128 v203, v[144:147] offset:18432
	v_cndmask_b32_e32 v101, v233, v114, vcc
	v_cmp_lt_u32_e32 vcc, s53, v64
	v_add_u32_e32 v64, 0xffffffa2, v14
	s_lshl_b32 s34, s34, 6
	v_cndmask_b32_e32 v83, v233, v67, vcc
	v_cmp_lt_u32_e32 vcc, s53, v64
	v_add_u32_e32 v64, 0xffffff87, v14
	s_ashr_i32 s35, s34, 31
	v_cndmask_b32_e32 v102, v233, v115, vcc
	v_cmp_lt_u32_e32 vcc, s53, v64
	v_add_u32_e32 v64, 0xffffffa7, v14
	v_add_f32_e32 v1, v1, v180
	v_cndmask_b32_e32 v105, v233, v68, vcc
	v_cmp_lt_u32_e32 vcc, s53, v64
	v_add_u32_e32 v64, 0xffffff88, v14
	v_add_u32_e32 v68, 0xffffff9a, v14
	v_cndmask_b32_e32 v103, v233, v116, vcc
	v_cmp_lt_u32_e32 vcc, s53, v64
	v_add_u32_e32 v64, 0xffffffa8, v14
	s_add_i32 s26, s23, 1
	v_cndmask_b32_e32 v107, v233, v69, vcc
	v_cmp_lt_u32_e32 vcc, s53, v64
	v_add_u32_e32 v64, 0xffffff89, v14
	s_nop 0
	v_cndmask_b32_e32 v104, v233, v117, vcc
	v_cmp_lt_u32_e32 vcc, s53, v64
	v_add_u32_e32 v64, 0xffffffa9, v14
	s_nop 0
	v_cndmask_b32_e32 v109, v233, v70, vcc
	v_cmp_lt_u32_e32 vcc, s53, v64
	v_add_u32_e32 v64, 0xffffff8a, v14
	s_nop 0
	v_cndmask_b32_e32 v106, v233, v118, vcc
	v_cmp_lt_u32_e32 vcc, s53, v64
	v_add_u32_e32 v64, 0xffffffaa, v14
	s_nop 0
	v_cndmask_b32_e32 v111, v233, v71, vcc
	v_cmp_lt_u32_e32 vcc, s53, v64
	v_add_u32_e32 v64, 0xffffff8f, v14
	s_nop 0
	v_cndmask_b32_e32 v108, v233, v119, vcc
	v_cmp_lt_u32_e32 vcc, s53, v64
	v_add_u32_e32 v64, 0xffffffaf, v14
	s_nop 0
	v_cndmask_b32_e32 v113, v233, v72, vcc
	v_cmp_lt_u32_e32 vcc, s53, v64
	v_add_u32_e32 v64, 0xffffff90, v14
	s_nop 0
	v_cndmask_b32_e32 v110, v233, v120, vcc
	v_cmp_lt_u32_e32 vcc, s53, v64
	v_add_u32_e32 v64, 0xffffffb0, v14
	s_nop 0
	v_cndmask_b32_e32 v115, v233, v73, vcc
	v_cmp_lt_u32_e32 vcc, s53, v64
	v_add_u32_e32 v64, 0xffffff91, v14
	s_nop 0
	v_cndmask_b32_e32 v112, v233, v121, vcc
	v_cmp_lt_u32_e32 vcc, s53, v64
	v_add_u32_e32 v64, 0xffffffb1, v14
	s_nop 0
	v_cndmask_b32_e32 v117, v233, v74, vcc
	v_cmp_lt_u32_e32 vcc, s53, v64
	v_add_u32_e32 v64, 0xffffff92, v14
	s_nop 0
	v_cndmask_b32_e32 v114, v233, v122, vcc
	v_cmp_lt_u32_e32 vcc, s53, v64
	v_add_u32_e32 v64, 0xffffffb2, v14
	s_nop 0
	v_cndmask_b32_e32 v119, v233, v75, vcc
	v_cmp_lt_u32_e32 vcc, s53, v64
	v_add_u32_e32 v64, 0xffffff97, v14
	s_nop 0
	v_cndmask_b32_e32 v116, v233, v123, vcc
	v_cmp_lt_u32_e32 vcc, s53, v64
	v_add_u32_e32 v64, 0xffffffb7, v14
	s_nop 0
	v_cndmask_b32_e32 v121, v233, v76, vcc
	v_cmp_lt_u32_e32 vcc, s53, v64
	v_add_u32_e32 v64, 0xffffff98, v14
	s_nop 0
	v_cndmask_b32_e32 v118, v233, v124, vcc
	v_cmp_lt_u32_e32 vcc, s53, v64
	v_add_u32_e32 v64, 0xffffffb8, v14
	s_nop 0
	v_cndmask_b32_e32 v123, v233, v77, vcc
	v_cmp_lt_u32_e32 vcc, s53, v64
	v_add_u32_e32 v64, 0xffffff99, v14
	s_nop 0
	v_cndmask_b32_e32 v120, v233, v125, vcc
	v_cmp_lt_u32_e32 vcc, s53, v64
	v_add_u32_e32 v64, 0xffffffb9, v14
	v_add_u32_e32 v14, 0xffffffba, v14
	v_cndmask_b32_e32 v125, v233, v78, vcc
	v_cmp_lt_u32_e32 vcc, s53, v64
	s_nop 1
	v_cndmask_b32_e32 v122, v233, v126, vcc
	v_cmp_lt_u32_e32 vcc, s53, v14
	v_add_u32_e32 v14, s24, v203
	s_add_i32 s24, s27, -4
	s_waitcnt vmcnt(2)
	ds_write_b128 v14, v[10:13] offset:36864
	v_add_u32_e32 v14, s25, v201
	s_ashr_i32 s25, s24, 31
	v_cndmask_b32_e32 v124, v233, v127, vcc
	s_lshl_b64 vcc, s[24:25], 13
	v_lshl_add_u64 v[10:11], v[198:199], 0, vcc
	global_load_dwordx4 v[96:99], v[10:11], off
	v_lshl_add_u64 v[10:11], s[34:35], 1, v[196:197]
	global_load_dwordx4 v[10:13], v[10:11], off
	ds_read_b128 v[240:243], v201 offset:9216
	ds_read_b128 v[244:247], v201 offset:13824
	ds_read_b128 v[64:67], v14 offset:41472
	ds_read_b128 v[70:73], v14 offset:36864
	ds_read_b128 v[74:77], v14 offset:36896
	ds_read_b128 v[92:95], v14 offset:41504
	ds_read_b128 v[144:147], v14 offset:36928
	ds_read_b128 v[172:175], v14 offset:41536
	ds_read_b128 v[176:179], v14 offset:36960
	ds_read_b128 v[204:207], v14 offset:41568
	s_setprio 1
	v_mov_b32_e32 v14, 0
	v_cvt_pk_bf16_f32 v208, v168, v169
	v_cvt_pk_bf16_f32 v209, v170, v171
	v_cvt_pk_bf16_f32 v210, v140, v141
	v_cvt_pk_bf16_f32 v211, v142, v143
	s_waitcnt lgkmcnt(6)
	s_nop 0
	v_mfma_f32_32x32x16_bf16 v[16:31], v[70:73], v[208:211], v[16:31]
	v_add_f32_e32 v14, v14, v168
	v_add_f32_e32 v14, v14, v169
	v_add_f32_e32 v14, v14, v170
	v_add_f32_e32 v14, v14, v171
	s_nop 0
	v_mfma_f32_32x32x16_bf16 v[32:47], v[64:67], v[208:211], v[32:47]
	v_cvt_pk_bf16_f32 v70, v148, v149
	v_cvt_pk_bf16_f32 v71, v150, v151
	v_cvt_pk_bf16_f32 v72, v132, v133
	v_cvt_pk_bf16_f32 v73, v134, v135
	v_add_f32_e32 v14, v14, v140
	v_add_f32_e32 v14, v14, v141
	v_add_f32_e32 v14, v14, v142
	v_add_f32_e32 v14, v14, v143
	s_waitcnt lgkmcnt(5)
	v_mfma_f32_32x32x16_bf16 v[16:31], v[74:77], v[70:73], v[16:31]
	v_add_f32_e32 v14, v14, v148
	v_add_f32_e32 v14, v14, v149
	v_add_f32_e32 v14, v14, v150
	v_add_f32_e32 v14, v14, v151
	s_waitcnt lgkmcnt(4)
	v_mfma_f32_32x32x16_bf16 v[32:47], v[92:95], v[70:73], v[32:47]
	v_cvt_pk_bf16_f32 v64, v136, v137
	v_cvt_pk_bf16_f32 v65, v138, v139
	v_cvt_pk_bf16_f32 v66, v128, v129
	v_cvt_pk_bf16_f32 v67, v130, v131
	v_add_f32_e32 v14, v14, v132
	v_add_f32_e32 v14, v14, v133
	v_add_f32_e32 v14, v14, v134
	v_add_f32_e32 v14, v14, v135
	s_waitcnt lgkmcnt(3)
	v_mfma_f32_32x32x16_bf16 v[16:31], v[144:147], v[64:67], v[16:31]
	v_add_f32_e32 v14, v14, v136
	v_add_f32_e32 v14, v14, v137
	v_add_f32_e32 v14, v14, v138
	v_add_f32_e32 v14, v14, v139
	s_waitcnt lgkmcnt(2)
	v_mfma_f32_32x32x16_bf16 v[32:47], v[172:175], v[64:67], v[32:47]
	v_cvt_pk_bf16_f32 v70, v84, v85
	v_cvt_pk_bf16_f32 v71, v86, v87
	v_cvt_pk_bf16_f32 v72, v88, v89
	v_cvt_pk_bf16_f32 v73, v90, v91
	v_add_f32_e32 v14, v14, v128
	v_add_f32_e32 v14, v14, v129
	v_add_f32_e32 v14, v14, v130
	v_add_f32_e32 v14, v14, v131
	s_waitcnt lgkmcnt(1)
	v_mfma_f32_32x32x16_bf16 v[16:31], v[176:179], v[70:73], v[16:31]
	v_add_f32_e32 v14, v14, v84
	v_add_f32_e32 v14, v14, v85
	v_add_f32_e32 v14, v14, v86
	v_add_f32_e32 v14, v14, v87
	s_waitcnt lgkmcnt(0)
	v_mfma_f32_32x32x16_bf16 v[32:47], v[204:207], v[70:73], v[32:47]
	v_add_f32_e32 v14, v14, v88
	v_add_f32_e32 v14, v14, v89
	v_add_f32_e32 v14, v14, v90
	v_add_f32_e32 v14, v14, v91
	s_setprio 0
	ds_read_b128 v[130:133], v201 offset:9248
	ds_read_b128 v[168:171], v201 offset:13856
	ds_read_b128 v[172:175], v201 offset:9280
	ds_read_b128 v[176:179], v201 offset:13888
	ds_read_b128 v[204:207], v201 offset:9312
	ds_read_b128 v[208:211], v201 offset:13920
	v_cmp_lt_u32_e32 vcc, s53, v68
	s_cmp_lg_u32 s23, 4
	s_cselect_b32 s23, s26, 0
	v_cndmask_b32_e32 v135, v233, v79, vcc
	s_waitcnt lgkmcnt(6)
	v_mfma_f32_32x32x16_bf16 v[64:79], v[240:243], v[164:167], v[48:63]
	v_exp_f32_e32 v148, v80
	v_exp_f32_e32 v149, v81
	v_exp_f32_e32 v150, v82
	v_exp_f32_e32 v151, v83
	v_mfma_f32_32x32x16_bf16 v[80:95], v[244:247], v[164:167], v[48:63]
	v_exp_f32_e32 v142, v105
	v_exp_f32_e32 v143, v107
	v_exp_f32_e32 v144, v109
	v_exp_f32_e32 v147, v111
	s_waitcnt lgkmcnt(5)
	v_mfma_f32_32x32x16_bf16 v[64:79], v[130:133], v[160:163], v[64:79]
	v_exp_f32_e32 v136, v113
	v_exp_f32_e32 v137, v115
	v_exp_f32_e32 v138, v117
	v_exp_f32_e32 v140, v119
	s_waitcnt lgkmcnt(4)
	v_mfma_f32_32x32x16_bf16 v[80:95], v[168:171], v[160:163], v[80:95]
	v_exp_f32_e32 v130, v121
	v_exp_f32_e32 v131, v123
	v_exp_f32_e32 v133, v125
	v_exp_f32_e32 v134, v135
	s_waitcnt lgkmcnt(3)
	v_mfma_f32_32x32x16_bf16 v[64:79], v[172:175], v[156:159], v[64:79]
	v_exp_f32_e32 v125, v15
	v_exp_f32_e32 v126, v100
	v_exp_f32_e32 v127, v101
	v_exp_f32_e32 v128, v102
	s_waitcnt lgkmcnt(2)
	v_mfma_f32_32x32x16_bf16 v[80:95], v[176:179], v[156:159], v[80:95]
	v_exp_f32_e32 v117, v103
	v_exp_f32_e32 v119, v104
	v_exp_f32_e32 v121, v106
	v_exp_f32_e32 v123, v108
	s_waitcnt lgkmcnt(1)
	v_mfma_f32_32x32x16_bf16 v[64:79], v[204:207], v[152:155], v[64:79]
	v_exp_f32_e32 v108, v110
	v_exp_f32_e32 v109, v112
	v_exp_f32_e32 v111, v114
	v_exp_f32_e32 v113, v116
	s_waitcnt lgkmcnt(0)
	v_mfma_f32_32x32x16_bf16 v[80:95], v[208:211], v[152:155], v[80:95]
	v_exp_f32_e32 v110, v118
	v_exp_f32_e32 v112, v120
	v_exp_f32_e32 v114, v122
	v_exp_f32_e32 v115, v124
	s_cmp_gt_i32 s23, 2
	v_sub_u32_e32 v15, s22, v202
	s_cselect_b32 s22, -3, 2
	s_add_i32 s22, s22, s23
	s_mulk_i32 s22, 0x2400
	s_nop 7
	s_nop 3
	s_waitcnt vmcnt(3)
	ds_write_b128 v203, v[2:5] offset:27648
	v_add_u32_e32 v2, s22, v203
	s_add_i32 s22, s23, 1
	s_cmp_lg_u32 s23, 4
	s_cselect_b32 s25, s22, 0
	s_add_i32 s26, s45, 8
	s_min_i32 s22, s26, s92
	s_cmp_gt_i32 s22, 3
	s_cselect_b32 s23, s13, 0
	s_add_i32 s34, s23, s22
	s_ashr_i32 s35, s34, 31
	s_lshl_b64 s[22:23], s[34:35], 13
	s_waitcnt vmcnt(2)
	ds_write_b128 v2, v[6:9] offset:36864
	v_lshl_add_u64 v[2:3], v[198:199], 0, s[22:23]
	s_lshl_b32 s22, s24, 6
	s_ashr_i32 s23, s22, 31
	v_lshl_add_u64 v[6:7], s[22:23], 1, v[196:197]
	global_load_dwordx4 v[2:5], v[2:3], off
	v_add_u32_e32 v168, v15, v183
	global_load_dwordx4 v[6:9], v[6:7], off
	v_add_u32_e32 v15, 0xffffff7f, v168
	v_cmp_lt_u32_e32 vcc, s53, v15
	v_add_u32_e32 v15, 0xffffff9f, v168
	s_mul_i32 s22, s25, 0x2400
	v_cndmask_b32_e32 v101, v233, v64, vcc
	v_cmp_lt_u32_e32 vcc, s53, v15
	v_add_u32_e32 v64, 0xffffff80, v168
	s_add_i32 s23, s22, 0xffffdc00
	v_cndmask_b32_e32 v15, v233, v80, vcc
	v_cmp_lt_u32_e32 vcc, s53, v64
	v_add_u32_e32 v64, 0xffffffa0, v168
	s_cmp_lg_u32 s25, 0
	v_cndmask_b32_e32 v80, v233, v65, vcc
	v_cmp_lt_u32_e32 vcc, s53, v64
	v_add_u32_e32 v64, 0xffffff81, v168
	v_add_u32_e32 v65, 0xffffffba, v168
	v_cndmask_b32_e32 v100, v233, v81, vcc
	v_cmp_lt_u32_e32 vcc, s53, v64
	v_add_u32_e32 v64, 0xffffffa1, v168
	s_cselect_b32 s23, s23, 0x9000
	v_cndmask_b32_e32 v81, v233, v66, vcc
	v_cmp_lt_u32_e32 vcc, s53, v64
	v_add_u32_e32 v64, 0xffffff82, v168
	s_nop 0
	v_cndmask_b32_e32 v102, v233, v82, vcc
	v_cmp_lt_u32_e32 vcc, s53, v64
	v_add_u32_e32 v64, 0xffffffa2, v168
	s_nop 0
	v_cndmask_b32_e32 v82, v233, v67, vcc
	v_cmp_lt_u32_e32 vcc, s53, v64
	v_add_u32_e32 v64, 0xffffff87, v168
	s_nop 0
	v_cndmask_b32_e32 v103, v233, v83, vcc
	v_cmp_lt_u32_e32 vcc, s53, v64
	v_add_u32_e32 v64, 0xffffffa7, v168
	v_add_u32_e32 v83, s23, v201
	v_cndmask_b32_e32 v106, v233, v68, vcc
	v_cmp_lt_u32_e32 vcc, s53, v64
	v_add_u32_e32 v64, 0xffffff88, v168
	s_nop 0
	v_cndmask_b32_e32 v104, v233, v84, vcc
	v_cmp_lt_u32_e32 vcc, s53, v64
	v_add_u32_e32 v64, 0xffffffa8, v168
	s_nop 0
	v_cndmask_b32_e32 v116, v233, v69, vcc
	v_cmp_lt_u32_e32 vcc, s53, v64
	v_add_u32_e32 v64, 0xffffff89, v168
	s_nop 0
	v_cndmask_b32_e32 v105, v233, v85, vcc
	v_cmp_lt_u32_e32 vcc, s53, v64
	v_add_u32_e32 v64, 0xffffffa9, v168
	s_nop 0
	v_cndmask_b32_e32 v120, v233, v70, vcc
	v_cmp_lt_u32_e32 vcc, s53, v64
	v_add_u32_e32 v64, 0xffffff8a, v168
	s_nop 0
	v_cndmask_b32_e32 v107, v233, v86, vcc
	v_cmp_lt_u32_e32 vcc, s53, v64
	v_add_u32_e32 v64, 0xffffffaa, v168
	s_nop 0
	v_cndmask_b32_e32 v124, v233, v71, vcc
	v_cmp_lt_u32_e32 vcc, s53, v64
	v_add_u32_e32 v64, 0xffffff8f, v168
	s_nop 0
	v_cndmask_b32_e32 v118, v233, v87, vcc
	v_cmp_lt_u32_e32 vcc, s53, v64
	v_add_u32_e32 v64, 0xffffffaf, v168
	s_nop 0
	v_cndmask_b32_e32 v129, v233, v72, vcc
	v_cmp_lt_u32_e32 vcc, s53, v64
	v_add_u32_e32 v64, 0xffffff90, v168
	s_nop 0
	v_cndmask_b32_e32 v122, v233, v88, vcc
	v_cmp_lt_u32_e32 vcc, s53, v64
	v_add_u32_e32 v64, 0xffffffb0, v168
	s_nop 0
	v_cndmask_b32_e32 v135, v233, v73, vcc
	v_cmp_lt_u32_e32 vcc, s53, v64
	v_add_u32_e32 v64, 0xffffff91, v168
	s_nop 0
	v_cndmask_b32_e32 v132, v233, v89, vcc
	v_cmp_lt_u32_e32 vcc, s53, v64
	v_add_u32_e32 v64, 0xffffffb1, v168
	s_nop 0
	v_cndmask_b32_e32 v141, v233, v74, vcc
	v_cmp_lt_u32_e32 vcc, s53, v64
	v_add_u32_e32 v64, 0xffffff92, v168
	s_nop 0
	v_cndmask_b32_e32 v139, v233, v90, vcc
	v_cmp_lt_u32_e32 vcc, s53, v64
	v_add_u32_e32 v64, 0xffffffb2, v168
	s_nop 0
	v_cndmask_b32_e32 v175, v233, v75, vcc
	v_cmp_lt_u32_e32 vcc, s53, v64
	v_add_u32_e32 v64, 0xffffff97, v168
	s_nop 0
	v_cndmask_b32_e32 v145, v233, v91, vcc
	v_cmp_lt_u32_e32 vcc, s53, v64
	v_add_u32_e32 v64, 0xffffffb7, v168
	s_nop 0
	v_cndmask_b32_e32 v177, v233, v76, vcc
	v_cmp_lt_u32_e32 vcc, s53, v64
	v_add_u32_e32 v64, 0xffffff98, v168
	s_nop 0
	v_cndmask_b32_e32 v146, v233, v92, vcc
	v_cmp_lt_u32_e32 vcc, s53, v64
	v_add_u32_e32 v64, 0xffffffb8, v168
	s_nop 0
	v_cndmask_b32_e32 v179, v233, v77, vcc
	v_cmp_lt_u32_e32 vcc, s53, v64
	v_add_u32_e32 v64, 0xffffff99, v168
	s_nop 0
	v_cndmask_b32_e32 v176, v233, v93, vcc
	v_cmp_lt_u32_e32 vcc, s53, v64
	v_add_u32_e32 v64, 0xffffffb9, v168
	s_nop 0
	v_cndmask_b32_e32 v181, v233, v78, vcc
	v_cmp_lt_u32_e32 vcc, s53, v64
	v_add_u32_e32 v64, 0xffffff9a, v168
	s_nop 0
	v_cndmask_b32_e32 v178, v233, v94, vcc
	v_cmp_lt_u32_e32 vcc, s53, v65
	s_nop 1
	v_cndmask_b32_e32 v180, v233, v95, vcc
	v_cmp_lt_u32_e32 vcc, s53, v64
	s_nop 1
	v_cndmask_b32_e32 v185, v233, v79, vcc
	ds_read_b128 v[64:67], v83 offset:41472
	ds_read_b128 v[68:71], v83 offset:36864
	ds_read_b128 v[72:75], v83 offset:36896
	ds_read_b128 v[76:79], v83 offset:41504
	ds_read_b128 v[84:87], v83 offset:36928
	ds_read_b128 v[88:91], v83 offset:41536
	ds_read_b128 v[92:95], v83 offset:36960
	ds_read_b128 v[168:171], v83 offset:41568
	s_setprio 3
	v_mov_b32_e32 v186, 0
	v_cvt_pk_bf16_f32 v204, v148, v149
	v_cvt_pk_bf16_f32 v205, v150, v151
	v_cvt_pk_bf16_f32 v206, v142, v143
	v_cvt_pk_bf16_f32 v207, v144, v147
	s_waitcnt lgkmcnt(6)
	s_nop 0
	v_mfma_f32_32x32x16_bf16 v[16:31], v[68:71], v[204:207], v[16:31]
	v_add_f32_e32 v186, v186, v148
	v_add_f32_e32 v186, v186, v149
	v_add_f32_e32 v186, v186, v150
	v_add_f32_e32 v186, v186, v151
	s_nop 0
	v_mfma_f32_32x32x16_bf16 v[32:47], v[64:67], v[204:207], v[32:47]
	v_cvt_pk_bf16_f32 v68, v136, v137
	v_cvt_pk_bf16_f32 v69, v138, v140
	v_cvt_pk_bf16_f32 v70, v130, v131
	v_cvt_pk_bf16_f32 v71, v133, v134
	v_add_f32_e32 v186, v186, v142
	v_add_f32_e32 v186, v186, v143
	v_add_f32_e32 v186, v186, v144
	v_add_f32_e32 v186, v186, v147
	s_waitcnt lgkmcnt(5)
	v_mfma_f32_32x32x16_bf16 v[16:31], v[72:75], v[68:71], v[16:31]
	v_add_f32_e32 v186, v186, v136
	v_add_f32_e32 v186, v186, v137
	v_add_f32_e32 v186, v186, v138
	v_add_f32_e32 v186, v186, v140
	s_waitcnt lgkmcnt(4)
	v_mfma_f32_32x32x16_bf16 v[32:47], v[76:79], v[68:71], v[32:47]
	v_cvt_pk_bf16_f32 v64, v125, v126
	v_cvt_pk_bf16_f32 v65, v127, v128
	v_cvt_pk_bf16_f32 v66, v117, v119
	v_cvt_pk_bf16_f32 v67, v121, v123
	v_add_f32_e32 v186, v186, v130
	v_add_f32_e32 v186, v186, v131
	v_add_f32_e32 v186, v186, v133
	v_add_f32_e32 v186, v186, v134
	s_waitcnt lgkmcnt(3)
	v_mfma_f32_32x32x16_bf16 v[16:31], v[84:87], v[64:67], v[16:31]
	v_add_f32_e32 v186, v186, v125
	v_add_f32_e32 v186, v186, v126
	v_add_f32_e32 v186, v186, v127
	v_add_f32_e32 v186, v186, v128
	s_waitcnt lgkmcnt(2)
	v_mfma_f32_32x32x16_bf16 v[32:47], v[88:91], v[64:67], v[32:47]
	v_cvt_pk_bf16_f32 v68, v108, v109
	v_cvt_pk_bf16_f32 v69, v111, v113
	v_cvt_pk_bf16_f32 v70, v110, v112
	v_cvt_pk_bf16_f32 v71, v114, v115
	v_add_f32_e32 v186, v186, v117
	v_add_f32_e32 v186, v186, v119
	v_add_f32_e32 v186, v186, v121
	v_add_f32_e32 v186, v186, v123
	s_waitcnt lgkmcnt(1)
	v_mfma_f32_32x32x16_bf16 v[16:31], v[92:95], v[68:71], v[16:31]
	v_add_f32_e32 v186, v186, v108
	v_add_f32_e32 v186, v186, v109
	v_add_f32_e32 v186, v186, v111
	v_add_f32_e32 v186, v186, v113
	s_waitcnt lgkmcnt(0)
	v_mfma_f32_32x32x16_bf16 v[32:47], v[168:171], v[68:71], v[32:47]
	v_add_f32_e32 v186, v186, v110
	v_add_f32_e32 v186, v186, v112
	v_add_f32_e32 v186, v186, v114
	v_add_f32_e32 v186, v186, v115
	s_setprio 2
	s_waitcnt lgkmcnt(0)
	s_barrier
	ds_read_b128 v[240:243], v201 offset:18432
	ds_read_b128 v[244:247], v201 offset:23040
	ds_read_b128 v[112:115], v201 offset:18464
	ds_read_b128 v[204:207], v201 offset:23072
	ds_read_b128 v[208:211], v201 offset:18496
	ds_read_b128 v[212:215], v201 offset:23104
	ds_read_b128 v[216:219], v201 offset:18528
	ds_read_b128 v[236:239], v201 offset:23136
	v_add_f32_e32 v1, v1, v14
	s_waitcnt lgkmcnt(6)
	v_mfma_f32_32x32x16_bf16 v[64:79], v[240:243], v[164:167], v[48:63]
	v_exp_f32_e32 v171, v101
	v_exp_f32_e32 v172, v80
	v_exp_f32_e32 v173, v81
	v_exp_f32_e32 v174, v82
	v_mfma_f32_32x32x16_bf16 v[80:95], v[244:247], v[164:167], v[48:63]
	v_exp_f32_e32 v151, v106
	v_exp_f32_e32 v168, v116
	v_exp_f32_e32 v169, v120
	v_exp_f32_e32 v170, v124
	s_waitcnt lgkmcnt(5)
	v_mfma_f32_32x32x16_bf16 v[64:79], v[112:115], v[160:163], v[64:79]
	v_exp_f32_e32 v147, v129
	v_exp_f32_e32 v148, v135
	v_exp_f32_e32 v149, v141
	v_exp_f32_e32 v150, v175
	s_waitcnt lgkmcnt(4)
	v_mfma_f32_32x32x16_bf16 v[80:95], v[204:207], v[160:163], v[80:95]
	v_exp_f32_e32 v141, v177
	v_exp_f32_e32 v142, v179
	v_exp_f32_e32 v143, v181
	v_exp_f32_e32 v144, v185
	s_waitcnt lgkmcnt(3)
	v_mfma_f32_32x32x16_bf16 v[64:79], v[208:211], v[156:159], v[64:79]
	v_exp_f32_e32 v135, v15
	v_exp_f32_e32 v136, v100
	v_exp_f32_e32 v137, v102
	v_exp_f32_e32 v138, v103
	s_waitcnt lgkmcnt(2)
	v_mfma_f32_32x32x16_bf16 v[80:95], v[212:215], v[156:159], v[80:95]
	v_exp_f32_e32 v128, v104
	v_exp_f32_e32 v129, v105
	v_exp_f32_e32 v130, v107
	v_exp_f32_e32 v131, v118
	s_waitcnt lgkmcnt(1)
	v_mfma_f32_32x32x16_bf16 v[64:79], v[216:219], v[152:155], v[64:79]
	v_exp_f32_e32 v118, v122
	v_exp_f32_e32 v119, v132
	v_exp_f32_e32 v120, v139
	v_exp_f32_e32 v121, v145
	s_waitcnt lgkmcnt(0)
	v_mfma_f32_32x32x16_bf16 v[80:95], v[236:239], v[152:155], v[80:95]
	v_exp_f32_e32 v122, v146
	v_exp_f32_e32 v123, v176
	v_exp_f32_e32 v124, v178
	v_exp_f32_e32 v125, v180
	s_add_i32 s87, s87, s18
	v_lshl_add_u32 v14, s87, 6, v184
	v_add_u32_e32 v15, 0xffffff7f, v14
	v_cmp_lt_u32_e32 vcc, s53, v15
	v_add_u32_e32 v15, 0xffffff9f, v14
	s_cmp_gt_i32 s25, 2
	v_cndmask_b32_e32 v101, v233, v64, vcc
	v_cmp_lt_u32_e32 vcc, s53, v15
	v_add_u32_e32 v64, 0xffffff80, v14
	s_cselect_b32 s23, -3, 2
	v_cndmask_b32_e32 v15, v233, v80, vcc
	v_cmp_lt_u32_e32 vcc, s53, v64
	v_add_u32_e32 v64, 0xffffffa0, v14
	s_add_i32 s23, s23, s25
	v_cndmask_b32_e32 v80, v233, v65, vcc
	v_cmp_lt_u32_e32 vcc, s53, v64
	v_add_u32_e32 v64, 0xffffff81, v14
	s_mulk_i32 s23, 0x2400
	v_cndmask_b32_e32 v100, v233, v81, vcc
	v_cmp_lt_u32_e32 vcc, s53, v64
	v_add_u32_e32 v64, 0xffffffa1, v14
	s_nop 7
	s_nop 3
	s_waitcnt vmcnt(3)
	ds_write_b128 v203, v[96:99]
	v_cndmask_b32_e32 v81, v233, v66, vcc
	v_cmp_lt_u32_e32 vcc, s53, v64
	v_add_u32_e32 v64, 0xffffff82, v14
	s_add_i32 s24, s25, 1
	v_cndmask_b32_e32 v102, v233, v82, vcc
	v_cmp_lt_u32_e32 vcc, s53, v64
	v_add_u32_e32 v64, 0xffffffa2, v14
	v_add_f32_e32 v1, v1, v186
	v_cndmask_b32_e32 v82, v233, v67, vcc
	v_cmp_lt_u32_e32 vcc, s53, v64
	v_add_u32_e32 v64, 0xffffff87, v14
	s_nop 0
	v_cndmask_b32_e32 v103, v233, v83, vcc
	v_cmp_lt_u32_e32 vcc, s53, v64
	v_add_u32_e32 v64, 0xffffffa7, v14
	s_nop 0
	v_cndmask_b32_e32 v106, v233, v68, vcc
	v_cmp_lt_u32_e32 vcc, s53, v64
	v_add_u32_e32 v64, 0xffffff88, v14
	v_add_u32_e32 v68, 0xffffff9a, v14
	v_cndmask_b32_e32 v104, v233, v84, vcc
	v_cmp_lt_u32_e32 vcc, s53, v64
	v_add_u32_e32 v64, 0xffffffa8, v14
	s_nop 0
	v_cndmask_b32_e32 v108, v233, v69, vcc
	v_cmp_lt_u32_e32 vcc, s53, v64
	v_add_u32_e32 v64, 0xffffff89, v14
	s_nop 0
	v_cndmask_b32_e32 v105, v233, v85, vcc
	v_cmp_lt_u32_e32 vcc, s53, v64
	v_add_u32_e32 v64, 0xffffffa9, v14
	s_nop 0
	v_cndmask_b32_e32 v110, v233, v70, vcc
	v_cmp_lt_u32_e32 vcc, s53, v64
	v_add_u32_e32 v64, 0xffffff8a, v14
	s_nop 0
	v_cndmask_b32_e32 v107, v233, v86, vcc
	v_cmp_lt_u32_e32 vcc, s53, v64
	v_add_u32_e32 v64, 0xffffffaa, v14
	s_nop 0
	v_cndmask_b32_e32 v112, v233, v71, vcc
	v_cmp_lt_u32_e32 vcc, s53, v64
	v_add_u32_e32 v64, 0xffffff8f, v14
	s_nop 0
	v_cndmask_b32_e32 v109, v233, v87, vcc
	v_cmp_lt_u32_e32 vcc, s53, v64
	v_add_u32_e32 v64, 0xffffffaf, v14
	s_nop 0
	v_cndmask_b32_e32 v114, v233, v72, vcc
	v_cmp_lt_u32_e32 vcc, s53, v64
	v_add_u32_e32 v64, 0xffffff90, v14
	s_nop 0
	v_cndmask_b32_e32 v111, v233, v88, vcc
	v_cmp_lt_u32_e32 vcc, s53, v64
	v_add_u32_e32 v64, 0xffffffb0, v14
	s_nop 0
	v_cndmask_b32_e32 v116, v233, v73, vcc
	v_cmp_lt_u32_e32 vcc, s53, v64
	v_add_u32_e32 v64, 0xffffff91, v14
	s_nop 0
	v_cndmask_b32_e32 v113, v233, v89, vcc
	v_cmp_lt_u32_e32 vcc, s53, v64
	v_add_u32_e32 v64, 0xffffffb1, v14
	s_nop 0
	v_cndmask_b32_e32 v126, v233, v74, vcc
	v_cmp_lt_u32_e32 vcc, s53, v64
	v_add_u32_e32 v64, 0xffffff92, v14
	s_nop 0
	v_cndmask_b32_e32 v115, v233, v90, vcc
	v_cmp_lt_u32_e32 vcc, s53, v64
	v_add_u32_e32 v64, 0xffffffb2, v14
	s_nop 0
	v_cndmask_b32_e32 v132, v233, v75, vcc
	v_cmp_lt_u32_e32 vcc, s53, v64
	v_add_u32_e32 v64, 0xffffff97, v14
	s_nop 0
	v_cndmask_b32_e32 v117, v233, v91, vcc
	v_cmp_lt_u32_e32 vcc, s53, v64
	v_add_u32_e32 v64, 0xffffffb7, v14
	s_nop 0
	v_cndmask_b32_e32 v134, v233, v76, vcc
	v_cmp_lt_u32_e32 vcc, s53, v64
	v_add_u32_e32 v64, 0xffffff98, v14
	s_nop 0
	v_cndmask_b32_e32 v127, v233, v92, vcc
	v_cmp_lt_u32_e32 vcc, s53, v64
	v_add_u32_e32 v64, 0xffffffb8, v14
	s_nop 0
	v_cndmask_b32_e32 v140, v233, v77, vcc
	v_cmp_lt_u32_e32 vcc, s53, v64
	v_add_u32_e32 v64, 0xffffff99, v14
	s_nop 0
	v_cndmask_b32_e32 v133, v233, v93, vcc
	v_cmp_lt_u32_e32 vcc, s53, v64
	v_add_u32_e32 v64, 0xffffffb9, v14
	v_add_u32_e32 v14, 0xffffffba, v14
	v_cndmask_b32_e32 v146, v233, v78, vcc
	v_cmp_lt_u32_e32 vcc, s53, v64
	s_nop 1
	v_cndmask_b32_e32 v139, v233, v94, vcc
	v_cmp_lt_u32_e32 vcc, s53, v14
	v_add_u32_e32 v14, s23, v203
	s_waitcnt vmcnt(2)
	ds_write_b128 v14, v[10:13] offset:36864
	v_add_u32_e32 v14, s22, v201
	s_add_i32 s22, s45, 9
	s_min_i32 s22, s22, s92
	s_cmp_gt_i32 s22, 3
	s_cselect_b32 s23, s13, 0
	s_add_i32 s22, s23, s22
	s_ashr_i32 s23, s22, 31
	v_cndmask_b32_e32 v145, v233, v95, vcc
	s_lshl_b64 vcc, s[22:23], 13
	s_lshl_b32 s34, s34, 6
	v_lshl_add_u64 v[10:11], v[198:199], 0, vcc
	s_ashr_i32 s35, s34, 31
	global_load_dwordx4 v[96:99], v[10:11], off
	v_lshl_add_u64 v[10:11], s[34:35], 1, v[196:197]
	global_load_dwordx4 v[10:13], v[10:11], off
	ds_read_b128 v[240:243], v201 offset:27648
	ds_read_b128 v[244:247], v201 offset:32256
	ds_read_b128 v[64:67], v14 offset:41472
	ds_read_b128 v[70:73], v14 offset:36864
	ds_read_b128 v[74:77], v14 offset:36896
	ds_read_b128 v[84:87], v14 offset:41504
	ds_read_b128 v[88:91], v14 offset:36928
	ds_read_b128 v[92:95], v14 offset:41536
	ds_read_b128 v[176:179], v14 offset:36960
	ds_read_b128 v[204:207], v14 offset:41568
	s_setprio 1
	v_mov_b32_e32 v14, 0
	v_cvt_pk_bf16_f32 v208, v171, v172
	v_cvt_pk_bf16_f32 v209, v173, v174
	v_cvt_pk_bf16_f32 v210, v151, v168
	v_cvt_pk_bf16_f32 v211, v169, v170
	s_waitcnt lgkmcnt(6)
	s_nop 0
	v_mfma_f32_32x32x16_bf16 v[16:31], v[70:73], v[208:211], v[16:31]
	v_add_f32_e32 v14, v14, v171
	v_add_f32_e32 v14, v14, v172
	v_add_f32_e32 v14, v14, v173
	v_add_f32_e32 v14, v14, v174
	s_nop 0
	v_mfma_f32_32x32x16_bf16 v[32:47], v[64:67], v[208:211], v[32:47]
	v_cvt_pk_bf16_f32 v70, v147, v148
	v_cvt_pk_bf16_f32 v71, v149, v150
	v_cvt_pk_bf16_f32 v72, v141, v142
	v_cvt_pk_bf16_f32 v73, v143, v144
	v_add_f32_e32 v14, v14, v151
	v_add_f32_e32 v14, v14, v168
	v_add_f32_e32 v14, v14, v169
	v_add_f32_e32 v14, v14, v170
	s_waitcnt lgkmcnt(5)
	v_mfma_f32_32x32x16_bf16 v[16:31], v[74:77], v[70:73], v[16:31]
	v_add_f32_e32 v14, v14, v147
	v_add_f32_e32 v14, v14, v148
	v_add_f32_e32 v14, v14, v149
	v_add_f32_e32 v14, v14, v150
	s_waitcnt lgkmcnt(4)
	v_mfma_f32_32x32x16_bf16 v[32:47], v[84:87], v[70:73], v[32:47]
	v_cvt_pk_bf16_f32 v64, v135, v136
	v_cvt_pk_bf16_f32 v65, v137, v138
	v_cvt_pk_bf16_f32 v66, v128, v129
	v_cvt_pk_bf16_f32 v67, v130, v131
	v_add_f32_e32 v14, v14, v141
	v_add_f32_e32 v14, v14, v142
	v_add_f32_e32 v14, v14, v143
	v_add_f32_e32 v14, v14, v144
	s_waitcnt lgkmcnt(3)
	v_mfma_f32_32x32x16_bf16 v[16:31], v[88:91], v[64:67], v[16:31]
	v_add_f32_e32 v14, v14, v135
	v_add_f32_e32 v14, v14, v136
	v_add_f32_e32 v14, v14, v137
	v_add_f32_e32 v14, v14, v138
	s_waitcnt lgkmcnt(2)
	v_mfma_f32_32x32x16_bf16 v[32:47], v[92:95], v[64:67], v[32:47]
	v_cvt_pk_bf16_f32 v70, v118, v119
	v_cvt_pk_bf16_f32 v71, v120, v121
	v_cvt_pk_bf16_f32 v72, v122, v123
	v_cvt_pk_bf16_f32 v73, v124, v125
	v_add_f32_e32 v14, v14, v128
	v_add_f32_e32 v14, v14, v129
	v_add_f32_e32 v14, v14, v130
	v_add_f32_e32 v14, v14, v131
	s_waitcnt lgkmcnt(1)
	v_mfma_f32_32x32x16_bf16 v[16:31], v[176:179], v[70:73], v[16:31]
	v_add_f32_e32 v14, v14, v118
	v_add_f32_e32 v14, v14, v119
	v_add_f32_e32 v14, v14, v120
	v_add_f32_e32 v14, v14, v121
	s_waitcnt lgkmcnt(0)
	v_mfma_f32_32x32x16_bf16 v[32:47], v[204:207], v[70:73], v[32:47]
	v_add_f32_e32 v14, v14, v122
	v_add_f32_e32 v14, v14, v123
	v_add_f32_e32 v14, v14, v124
	v_add_f32_e32 v14, v14, v125
	s_setprio 0
	ds_read_b128 v[122:125], v201 offset:27680
	ds_read_b128 v[174:177], v201 offset:32288
	ds_read_b128 v[178:181], v201 offset:27712
	ds_read_b128 v[204:207], v201 offset:32320
	ds_read_b128 v[208:211], v201 offset:27744
	ds_read_b128 v[212:215], v201 offset:32352
	v_cmp_lt_u32_e32 vcc, s53, v68
	s_cmp_lg_u32 s25, 4
	s_cselect_b32 s23, s24, 0
	v_cndmask_b32_e32 v131, v233, v79, vcc
	s_waitcnt lgkmcnt(6)
	v_mfma_f32_32x32x16_bf16 v[64:79], v[240:243], v[164:167], v[48:63]
	v_exp_f32_e32 v169, v101
	v_exp_f32_e32 v170, v80
	v_exp_f32_e32 v171, v81
	v_exp_f32_e32 v172, v82
	v_mfma_f32_32x32x16_bf16 v[80:95], v[244:247], v[164:167], v[48:63]
	v_exp_f32_e32 v147, v106
	v_exp_f32_e32 v148, v108
	v_exp_f32_e32 v149, v110
	v_exp_f32_e32 v150, v112
	s_waitcnt lgkmcnt(5)
	v_mfma_f32_32x32x16_bf16 v[64:79], v[122:125], v[160:163], v[64:79]
	v_exp_f32_e32 v138, v114
	v_exp_f32_e32 v141, v116
	v_exp_f32_e32 v142, v126
	v_exp_f32_e32 v143, v132
	s_waitcnt lgkmcnt(4)
	v_mfma_f32_32x32x16_bf16 v[80:95], v[174:177], v[160:163], v[80:95]
	v_exp_f32_e32 v128, v134
	v_exp_f32_e32 v129, v140
	v_exp_f32_e32 v130, v146
	v_exp_f32_e32 v135, v131
	s_waitcnt lgkmcnt(3)
	v_mfma_f32_32x32x16_bf16 v[64:79], v[178:181], v[156:159], v[64:79]
	v_exp_f32_e32 v122, v15
	v_exp_f32_e32 v123, v100
	v_exp_f32_e32 v124, v102
	v_exp_f32_e32 v125, v103
	s_waitcnt lgkmcnt(2)
	v_mfma_f32_32x32x16_bf16 v[80:95], v[204:207], v[156:159], v[80:95]
	v_exp_f32_e32 v118, v104
	v_exp_f32_e32 v119, v105
	v_exp_f32_e32 v120, v107
	v_exp_f32_e32 v121, v109
	s_waitcnt lgkmcnt(1)
	v_mfma_f32_32x32x16_bf16 v[64:79], v[208:211], v[152:155], v[64:79]
	v_exp_f32_e32 v107, v111
	v_exp_f32_e32 v108, v113
	v_exp_f32_e32 v109, v115
	v_exp_f32_e32 v110, v117
	s_waitcnt lgkmcnt(0)
	v_mfma_f32_32x32x16_bf16 v[80:95], v[212:215], v[152:155], v[80:95]
	v_exp_f32_e32 v111, v127
	v_exp_f32_e32 v113, v133
	v_exp_f32_e32 v114, v139
	v_exp_f32_e32 v115, v145
	s_add_i32 s2, s2, s18
	s_cmp_gt_i32 s23, 2
	v_lshl_add_u32 v127, s2, 6, v184
	s_cselect_b32 s2, -3, 2
	s_add_i32 s2, s2, s23
	s_mulk_i32 s2, 0x2400
	s_nop 7
	s_nop 3
	s_waitcnt vmcnt(3)
	ds_write_b128 v203, v[2:5] offset:9216
	v_add_u32_e32 v2, s2, v203
	s_add_i32 s2, s23, 1
	s_cmp_lg_u32 s23, 4
	s_cselect_b32 s2, s2, 0
	s_add_i32 s23, s45, 10
	s_min_i32 s23, s23, s92
	s_cmp_gt_i32 s23, 3
	s_cselect_b32 s24, s13, 0
	s_add_i32 s24, s24, s23
	s_ashr_i32 s25, s24, 31
	s_lshl_b32 s22, s22, 6
	s_lshl_b64 s[34:35], s[24:25], 13
	s_ashr_i32 s23, s22, 31
	s_waitcnt vmcnt(2)
	ds_write_b128 v2, v[6:9] offset:36864
	v_lshl_add_u64 v[2:3], v[198:199], 0, s[34:35]
	v_lshl_add_u64 v[6:7], s[22:23], 1, v[196:197]
	global_load_dwordx4 v[2:5], v[2:3], off
	v_add_u32_e32 v15, 0xffffff7f, v127
	global_load_dwordx4 v[6:9], v[6:7], off
	v_cmp_lt_u32_e32 vcc, s53, v15
	v_add_u32_e32 v15, 0xffffff9f, v127
	s_mul_i32 s22, s2, 0x2400
	v_cndmask_b32_e32 v101, v233, v64, vcc
	v_cmp_lt_u32_e32 vcc, s53, v15
	v_add_u32_e32 v64, 0xffffff80, v127
	s_add_i32 s23, s22, 0xffffdc00
	v_cndmask_b32_e32 v15, v233, v80, vcc
	v_cmp_lt_u32_e32 vcc, s53, v64
	v_add_u32_e32 v64, 0xffffffa0, v127
	s_cmp_lg_u32 s2, 0
	v_cndmask_b32_e32 v80, v233, v65, vcc
	v_cmp_lt_u32_e32 vcc, s53, v64
	v_add_u32_e32 v64, 0xffffff81, v127
	v_add_u32_e32 v65, 0xffffffba, v127
	v_cndmask_b32_e32 v100, v233, v81, vcc
	v_cmp_lt_u32_e32 vcc, s53, v64
	v_add_u32_e32 v64, 0xffffffa1, v127
	s_cselect_b32 s23, s23, 0x9000
	v_cndmask_b32_e32 v81, v233, v66, vcc
	v_cmp_lt_u32_e32 vcc, s53, v64
	v_add_u32_e32 v64, 0xffffff82, v127
	s_nop 0
	v_cndmask_b32_e32 v102, v233, v82, vcc
	v_cmp_lt_u32_e32 vcc, s53, v64
	v_add_u32_e32 v64, 0xffffffa2, v127
	s_nop 0
	v_cndmask_b32_e32 v82, v233, v67, vcc
	v_cmp_lt_u32_e32 vcc, s53, v64
	v_add_u32_e32 v64, 0xffffff87, v127
	s_nop 0
	v_cndmask_b32_e32 v103, v233, v83, vcc
	v_cmp_lt_u32_e32 vcc, s53, v64
	v_add_u32_e32 v64, 0xffffffa7, v127
	v_add_u32_e32 v83, s23, v201
	v_cndmask_b32_e32 v106, v233, v68, vcc
	v_cmp_lt_u32_e32 vcc, s53, v64
	v_add_u32_e32 v64, 0xffffff88, v127
	s_nop 0
	v_cndmask_b32_e32 v104, v233, v84, vcc
	v_cmp_lt_u32_e32 vcc, s53, v64
	v_add_u32_e32 v64, 0xffffffa8, v127
	s_nop 0
	v_cndmask_b32_e32 v116, v233, v69, vcc
	v_cmp_lt_u32_e32 vcc, s53, v64
	v_add_u32_e32 v64, 0xffffff89, v127
	s_nop 0
	v_cndmask_b32_e32 v105, v233, v85, vcc
	v_cmp_lt_u32_e32 vcc, s53, v64
	v_add_u32_e32 v64, 0xffffffa9, v127
	s_nop 0
	v_cndmask_b32_e32 v117, v233, v70, vcc
	v_cmp_lt_u32_e32 vcc, s53, v64
	v_add_u32_e32 v64, 0xffffff8a, v127
	s_nop 0
	v_cndmask_b32_e32 v112, v233, v86, vcc
	v_cmp_lt_u32_e32 vcc, s53, v64
	v_add_u32_e32 v64, 0xffffffaa, v127
	s_nop 0
	v_cndmask_b32_e32 v126, v233, v71, vcc
	v_cmp_lt_u32_e32 vcc, s53, v64
	v_add_u32_e32 v64, 0xffffff8f, v127
	s_nop 0
	v_cndmask_b32_e32 v131, v233, v87, vcc
	v_cmp_lt_u32_e32 vcc, s53, v64
	v_add_u32_e32 v64, 0xffffffaf, v127
	s_nop 0
	v_cndmask_b32_e32 v134, v233, v72, vcc
	v_cmp_lt_u32_e32 vcc, s53, v64
	v_add_u32_e32 v64, 0xffffff90, v127
	s_nop 0
	v_cndmask_b32_e32 v132, v233, v88, vcc
	v_cmp_lt_u32_e32 vcc, s53, v64
	v_add_u32_e32 v64, 0xffffffb0, v127
	s_nop 0
	v_cndmask_b32_e32 v137, v233, v73, vcc
	v_cmp_lt_u32_e32 vcc, s53, v64
	v_add_u32_e32 v64, 0xffffff91, v127
	s_nop 0
	v_cndmask_b32_e32 v133, v233, v89, vcc
	v_cmp_lt_u32_e32 vcc, s53, v64
	v_add_u32_e32 v64, 0xffffffb1, v127
	s_nop 0
	v_cndmask_b32_e32 v140, v233, v74, vcc
	v_cmp_lt_u32_e32 vcc, s53, v64
	v_add_u32_e32 v64, 0xffffff92, v127
	s_nop 0
	v_cndmask_b32_e32 v136, v233, v90, vcc
	v_cmp_lt_u32_e32 vcc, s53, v64
	v_add_u32_e32 v64, 0xffffffb2, v127
	s_nop 0
	v_cndmask_b32_e32 v145, v233, v75, vcc
	v_cmp_lt_u32_e32 vcc, s53, v64
	v_add_u32_e32 v64, 0xffffff97, v127
	s_nop 0
	v_cndmask_b32_e32 v139, v233, v91, vcc
	v_cmp_lt_u32_e32 vcc, s53, v64
	v_add_u32_e32 v64, 0xffffffb7, v127
	s_nop 0
	v_cndmask_b32_e32 v151, v233, v76, vcc
	v_cmp_lt_u32_e32 vcc, s53, v64
	v_add_u32_e32 v64, 0xffffff98, v127
	s_nop 0
	v_cndmask_b32_e32 v144, v233, v92, vcc
	v_cmp_lt_u32_e32 vcc, s53, v64
	v_add_u32_e32 v64, 0xffffffb8, v127
	s_nop 0
	v_cndmask_b32_e32 v173, v233, v77, vcc
	v_cmp_lt_u32_e32 vcc, s53, v64
	v_add_u32_e32 v64, 0xffffff99, v127
	s_nop 0
	v_cndmask_b32_e32 v146, v233, v93, vcc
	v_cmp_lt_u32_e32 vcc, s53, v64
	v_add_u32_e32 v64, 0xffffffb9, v127
	s_nop 0
	v_cndmask_b32_e32 v175, v233, v78, vcc
	v_cmp_lt_u32_e32 vcc, s53, v64
	v_add_u32_e32 v64, 0xffffff9a, v127
	s_nop 0
	v_cndmask_b32_e32 v168, v233, v94, vcc
	v_cmp_lt_u32_e32 vcc, s53, v65
	s_nop 1
	v_cndmask_b32_e32 v174, v233, v95, vcc
	v_cmp_lt_u32_e32 vcc, s53, v64
	s_nop 1
	v_cndmask_b32_e32 v180, v233, v79, vcc
	ds_read_b128 v[64:67], v83 offset:41472
	ds_read_b128 v[68:71], v83 offset:36864
	ds_read_b128 v[72:75], v83 offset:36896
	ds_read_b128 v[76:79], v83 offset:41504
	ds_read_b128 v[84:87], v83 offset:36928
	ds_read_b128 v[88:91], v83 offset:41536
	ds_read_b128 v[92:95], v83 offset:36960
	ds_read_b128 v[176:179], v83 offset:41568
	s_setprio 3
	v_mov_b32_e32 v230, 0
	v_cvt_pk_bf16_f32 v204, v169, v170
	v_cvt_pk_bf16_f32 v205, v171, v172
	v_cvt_pk_bf16_f32 v206, v147, v148
	v_cvt_pk_bf16_f32 v207, v149, v150
	s_waitcnt lgkmcnt(6)
	s_nop 0
	v_mfma_f32_32x32x16_bf16 v[16:31], v[68:71], v[204:207], v[16:31]
	v_add_f32_e32 v230, v230, v169
	v_add_f32_e32 v230, v230, v170
	v_add_f32_e32 v230, v230, v171
	v_add_f32_e32 v230, v230, v172
	s_nop 0
	v_mfma_f32_32x32x16_bf16 v[32:47], v[64:67], v[204:207], v[32:47]
	v_cvt_pk_bf16_f32 v68, v138, v141
	v_cvt_pk_bf16_f32 v69, v142, v143
	v_cvt_pk_bf16_f32 v70, v128, v129
	v_cvt_pk_bf16_f32 v71, v130, v135
	v_add_f32_e32 v230, v230, v147
	v_add_f32_e32 v230, v230, v148
	v_add_f32_e32 v230, v230, v149
	v_add_f32_e32 v230, v230, v150
	s_waitcnt lgkmcnt(5)
	v_mfma_f32_32x32x16_bf16 v[16:31], v[72:75], v[68:71], v[16:31]
	v_add_f32_e32 v230, v230, v138
	v_add_f32_e32 v230, v230, v141
	v_add_f32_e32 v230, v230, v142
	v_add_f32_e32 v230, v230, v143
	s_waitcnt lgkmcnt(4)
	v_mfma_f32_32x32x16_bf16 v[32:47], v[76:79], v[68:71], v[32:47]
	v_cvt_pk_bf16_f32 v64, v122, v123
	v_cvt_pk_bf16_f32 v65, v124, v125
	v_cvt_pk_bf16_f32 v66, v118, v119
	v_cvt_pk_bf16_f32 v67, v120, v121
	v_add_f32_e32 v230, v230, v128
	v_add_f32_e32 v230, v230, v129
	v_add_f32_e32 v230, v230, v130
	v_add_f32_e32 v230, v230, v135
	s_waitcnt lgkmcnt(3)
	v_mfma_f32_32x32x16_bf16 v[16:31], v[84:87], v[64:67], v[16:31]
	v_add_f32_e32 v230, v230, v122
	v_add_f32_e32 v230, v230, v123
	v_add_f32_e32 v230, v230, v124
	v_add_f32_e32 v230, v230, v125
	s_waitcnt lgkmcnt(2)
	v_mfma_f32_32x32x16_bf16 v[32:47], v[88:91], v[64:67], v[32:47]
	v_cvt_pk_bf16_f32 v68, v107, v108
	v_cvt_pk_bf16_f32 v69, v109, v110
	v_cvt_pk_bf16_f32 v70, v111, v113
	v_cvt_pk_bf16_f32 v71, v114, v115
	v_add_f32_e32 v230, v230, v118
	v_add_f32_e32 v230, v230, v119
	v_add_f32_e32 v230, v230, v120
	v_add_f32_e32 v230, v230, v121
	s_waitcnt lgkmcnt(1)
	v_mfma_f32_32x32x16_bf16 v[16:31], v[92:95], v[68:71], v[16:31]
	v_add_f32_e32 v230, v230, v107
	v_add_f32_e32 v230, v230, v108
	v_add_f32_e32 v230, v230, v109
	v_add_f32_e32 v230, v230, v110
	s_waitcnt lgkmcnt(0)
	v_mfma_f32_32x32x16_bf16 v[32:47], v[176:179], v[68:71], v[32:47]
	v_add_f32_e32 v230, v230, v111
	v_add_f32_e32 v230, v230, v113
	v_add_f32_e32 v230, v230, v114
	v_add_f32_e32 v230, v230, v115
	s_setprio 2
	s_waitcnt lgkmcnt(0)
	s_barrier
	ds_read_b128 v[240:243], v201
	ds_read_b128 v[244:247], v201 offset:4608
	ds_read_b128 v[118:121], v201 offset:32
	ds_read_b128 v[176:179], v201 offset:4640
	ds_read_b128 v[206:209], v201 offset:64
	ds_read_b128 v[210:213], v201 offset:4672
	ds_read_b128 v[214:217], v201 offset:96
	ds_read_b128 v[218:221], v201 offset:4704
	v_add_f32_e32 v169, v1, v14
	s_waitcnt lgkmcnt(6)
	v_mfma_f32_32x32x16_bf16 v[64:79], v[240:243], v[164:167], v[48:63]
	v_exp_f32_e32 v185, v101
	v_exp_f32_e32 v186, v80
	v_exp_f32_e32 v187, v81
	v_exp_f32_e32 v204, v82
	v_mfma_f32_32x32x16_bf16 v[80:95], v[244:247], v[164:167], v[48:63]
	v_exp_f32_e32 v127, v106
	v_exp_f32_e32 v128, v116
	v_exp_f32_e32 v129, v117
	v_exp_f32_e32 v130, v126
	s_waitcnt lgkmcnt(5)
	v_mfma_f32_32x32x16_bf16 v[64:79], v[118:121], v[160:163], v[64:79]
	v_exp_f32_e32 v123, v134
	v_exp_f32_e32 v124, v137
	v_exp_f32_e32 v125, v140
	v_exp_f32_e32 v126, v145
	s_waitcnt lgkmcnt(4)
	v_mfma_f32_32x32x16_bf16 v[80:95], v[176:179], v[160:163], v[80:95]
	v_exp_f32_e32 v119, v151
	v_exp_f32_e32 v120, v173
	v_exp_f32_e32 v121, v175
	v_exp_f32_e32 v122, v180
	s_waitcnt lgkmcnt(3)
	v_mfma_f32_32x32x16_bf16 v[64:79], v[206:209], v[156:159], v[64:79]
	v_exp_f32_e32 v111, v15
	v_exp_f32_e32 v116, v100
	v_exp_f32_e32 v117, v102
	v_exp_f32_e32 v118, v103
	s_waitcnt lgkmcnt(2)
	v_mfma_f32_32x32x16_bf16 v[80:95], v[210:213], v[156:159], v[80:95]
	v_exp_f32_e32 v107, v104
	v_exp_f32_e32 v108, v105
	v_exp_f32_e32 v109, v112
	v_exp_f32_e32 v110, v131
	s_waitcnt lgkmcnt(1)
	v_mfma_f32_32x32x16_bf16 v[64:79], v[214:217], v[152:155], v[64:79]
	v_exp_f32_e32 v103, v132
	v_exp_f32_e32 v104, v133
	v_exp_f32_e32 v105, v136
	v_exp_f32_e32 v106, v139
	s_waitcnt lgkmcnt(0)
	v_mfma_f32_32x32x16_bf16 v[80:95], v[218:221], v[152:155], v[80:95]
	v_exp_f32_e32 v1, v144
	v_exp_f32_e32 v100, v146
	v_exp_f32_e32 v101, v168
	v_exp_f32_e32 v102, v174
	v_lshl_add_u32 v131, s27, 6, v184
	v_add_u32_e32 v14, 0xffffff7f, v131
	v_cmp_lt_u32_e32 vcc, s53, v14
	v_add_u32_e32 v14, 0xffffff9f, v131
	v_add_u32_e32 v15, 0xffffff80, v131
	v_cndmask_b32_e32 v112, v233, v64, vcc
	v_cmp_lt_u32_e32 vcc, s53, v14
	v_add_u32_e32 v64, 0xffffff81, v131
	s_cmp_gt_i32 s2, 2
	v_cndmask_b32_e32 v14, v233, v80, vcc
	v_cmp_lt_u32_e32 vcc, s53, v15
	v_add_u32_e32 v15, 0xffffffa0, v131
	s_cselect_b32 s23, -3, 2
	v_cndmask_b32_e32 v113, v233, v65, vcc
	v_cmp_lt_u32_e32 vcc, s53, v15
	s_add_i32 s23, s23, s2
	v_add_u32_e32 v65, 0xffffffba, v131
	v_cndmask_b32_e32 v15, v233, v81, vcc
	v_cmp_lt_u32_e32 vcc, s53, v64
	v_add_u32_e32 v64, 0xffffffa1, v131
	s_mulk_i32 s23, 0x2400
	v_cndmask_b32_e32 v114, v233, v66, vcc
	v_cmp_lt_u32_e32 vcc, s53, v64
	v_add_u32_e32 v64, 0xffffff82, v131
	s_nop 7
	s_nop 3
	s_waitcnt vmcnt(3)
	ds_write_b128 v203, v[96:99] offset:18432
	v_cndmask_b32_e32 v132, v233, v82, vcc
	v_cmp_lt_u32_e32 vcc, s53, v64
	v_add_u32_e32 v64, 0xffffffa2, v131
	v_add_f32_e32 v96, v169, v230
	v_cndmask_b32_e32 v115, v233, v67, vcc
	v_cmp_lt_u32_e32 vcc, s53, v64
	v_add_u32_e32 v64, 0xffffff87, v131
	s_nop 0
	v_cndmask_b32_e32 v133, v233, v83, vcc
	v_cmp_lt_u32_e32 vcc, s53, v64
	v_add_u32_e32 v64, 0xffffffa7, v131
	s_nop 0
	v_cndmask_b32_e32 v140, v233, v68, vcc
	v_cmp_lt_u32_e32 vcc, s53, v64
	v_add_u32_e32 v64, 0xffffff88, v131
	s_nop 0
	v_cndmask_b32_e32 v134, v233, v84, vcc
	v_cmp_lt_u32_e32 vcc, s53, v64
	v_add_u32_e32 v64, 0xffffffa8, v131
	s_nop 0
	v_cndmask_b32_e32 v141, v233, v69, vcc
	v_cmp_lt_u32_e32 vcc, s53, v64
	v_add_u32_e32 v64, 0xffffff89, v131
	s_nop 0
	v_cndmask_b32_e32 v135, v233, v85, vcc
	v_cmp_lt_u32_e32 vcc, s53, v64
	v_add_u32_e32 v64, 0xffffffa9, v131
	s_nop 0
	v_cndmask_b32_e32 v146, v233, v70, vcc
	v_cmp_lt_u32_e32 vcc, s53, v64
	v_add_u32_e32 v64, 0xffffff8a, v131
	s_nop 0
	v_cndmask_b32_e32 v136, v233, v86, vcc
	v_cmp_lt_u32_e32 vcc, s53, v64
	v_add_u32_e32 v64, 0xffffffaa, v131
	s_nop 0
	v_cndmask_b32_e32 v147, v233, v71, vcc
	v_cmp_lt_u32_e32 vcc, s53, v64
	v_add_u32_e32 v64, 0xffffff8f, v131
	s_nop 0
	v_cndmask_b32_e32 v137, v233, v87, vcc
	v_cmp_lt_u32_e32 vcc, s53, v64
	v_add_u32_e32 v64, 0xffffffaf, v131
	s_nop 0
	v_cndmask_b32_e32 v148, v233, v72, vcc
	v_cmp_lt_u32_e32 vcc, s53, v64
	v_add_u32_e32 v64, 0xffffff90, v131
	s_nop 0
	v_cndmask_b32_e32 v138, v233, v88, vcc
	v_cmp_lt_u32_e32 vcc, s53, v64
	v_add_u32_e32 v64, 0xffffffb0, v131
	v_add_u32_e32 v88, s22, v201
	v_cndmask_b32_e32 v149, v233, v73, vcc
	v_cmp_lt_u32_e32 vcc, s53, v64
	v_add_u32_e32 v64, 0xffffff91, v131
	s_add_i32 s22, s45, 11
	v_cndmask_b32_e32 v139, v233, v89, vcc
	v_cmp_lt_u32_e32 vcc, s53, v64
	v_add_u32_e32 v64, 0xffffffb1, v131
	s_min_i32 s22, s22, s92
	v_cndmask_b32_e32 v176, v233, v74, vcc
	v_cmp_lt_u32_e32 vcc, s53, v64
	v_add_u32_e32 v64, 0xffffff92, v131
	s_cmp_gt_i32 s22, 3
	v_cndmask_b32_e32 v142, v233, v90, vcc
	v_cmp_lt_u32_e32 vcc, s53, v64
	v_add_u32_e32 v64, 0xffffffb2, v131
	s_nop 0
	v_cndmask_b32_e32 v177, v233, v75, vcc
	v_cmp_lt_u32_e32 vcc, s53, v64
	v_add_u32_e32 v64, 0xffffff97, v131
	s_nop 0
	v_cndmask_b32_e32 v143, v233, v91, vcc
	v_cmp_lt_u32_e32 vcc, s53, v64
	v_add_u32_e32 v64, 0xffffffb7, v131
	s_nop 0
	v_cndmask_b32_e32 v178, v233, v76, vcc
	v_cmp_lt_u32_e32 vcc, s53, v64
	v_add_u32_e32 v64, 0xffffff98, v131
	s_nop 0
	v_cndmask_b32_e32 v144, v233, v92, vcc
	v_cmp_lt_u32_e32 vcc, s53, v64
	v_add_u32_e32 v64, 0xffffffb8, v131
	s_nop 0
	v_cndmask_b32_e32 v179, v233, v77, vcc
	v_cmp_lt_u32_e32 vcc, s53, v64
	v_add_u32_e32 v64, 0xffffff99, v131
	s_nop 0
	v_cndmask_b32_e32 v145, v233, v93, vcc
	v_cmp_lt_u32_e32 vcc, s53, v64
	v_add_u32_e32 v64, 0xffffffb9, v131
	s_nop 0
	v_cndmask_b32_e32 v180, v233, v78, vcc
	v_cmp_lt_u32_e32 vcc, s53, v64
	v_add_u32_e32 v64, 0xffffff9a, v131
	s_nop 0
	v_cndmask_b32_e32 v150, v233, v94, vcc
	v_cmp_lt_u32_e32 vcc, s53, v65
	v_add_u32_e32 v65, s23, v203
	s_cselect_b32 s23, s13, 0
	s_add_i32 s22, s23, s22
	s_ashr_i32 s23, s22, 31
	s_lshl_b64 s[22:23], s[22:23], 13
	s_waitcnt vmcnt(2)
	ds_write_b128 v65, v[10:13] offset:36864
	v_lshl_add_u64 v[10:11], v[198:199], 0, s[22:23]
	s_lshl_b32 s22, s24, 6
	s_ashr_i32 s23, s22, 31
	global_load_dwordx4 v[168:171], v[10:11], off
	v_lshl_add_u64 v[10:11], s[22:23], 1, v[196:197]
	global_load_dwordx4 v[172:175], v[10:11], off
	v_cndmask_b32_e32 v151, v233, v95, vcc
	v_cmp_lt_u32_e32 vcc, s53, v64
	s_nop 1
	v_cndmask_b32_e32 v181, v233, v79, vcc
	ds_read_b128 v[240:243], v201 offset:9216
	ds_read_b128 v[244:247], v201 offset:13824
	ds_read_b128 v[10:13], v88 offset:41472
	ds_read_b128 v[64:67], v88 offset:36864
	ds_read_b128 v[68:71], v88 offset:36896
	ds_read_b128 v[72:75], v88 offset:41504
	ds_read_b128 v[76:79], v88 offset:36928
	ds_read_b128 v[80:83], v88 offset:41536
	ds_read_b128 v[84:87], v88 offset:36960
	ds_read_b128 v[88:91], v88 offset:41568
	s_setprio 1
	v_mov_b32_e32 v97, 0
	v_mov_b32_e32 v98, v112
	v_cvt_pk_bf16_f32 v92, v185, v186
	v_cvt_pk_bf16_f32 v93, v187, v204
	v_cvt_pk_bf16_f32 v94, v127, v128
	v_cvt_pk_bf16_f32 v95, v129, v130
	s_waitcnt lgkmcnt(6)
	s_nop 0
	v_mfma_f32_32x32x16_bf16 v[16:31], v[64:67], v[92:95], v[16:31]
	v_max3_f32 v98, v98, v113, v114
	v_max3_f32 v98, v98, v115, v140
	v_add_f32_e32 v97, v97, v185
	v_add_f32_e32 v97, v97, v186
	v_add_f32_e32 v97, v97, v187
	v_add_f32_e32 v97, v97, v204
	s_nop 0
	v_mfma_f32_32x32x16_bf16 v[32:47], v[10:13], v[92:95], v[32:47]
	v_cvt_pk_bf16_f32 v64, v123, v124
	v_cvt_pk_bf16_f32 v65, v125, v126
	v_cvt_pk_bf16_f32 v66, v119, v120
	v_cvt_pk_bf16_f32 v67, v121, v122
	v_max3_f32 v98, v98, v141, v146
	v_max3_f32 v98, v98, v147, v148
	v_add_f32_e32 v97, v97, v127
	v_add_f32_e32 v97, v97, v128
	v_add_f32_e32 v97, v97, v129
	v_add_f32_e32 v97, v97, v130
	s_waitcnt lgkmcnt(5)
	v_mfma_f32_32x32x16_bf16 v[16:31], v[68:71], v[64:67], v[16:31]
	v_max3_f32 v98, v98, v149, v176
	v_max3_f32 v98, v98, v177, v178
	v_add_f32_e32 v97, v97, v123
	v_add_f32_e32 v97, v97, v124
	v_add_f32_e32 v97, v97, v125
	v_add_f32_e32 v97, v97, v126
	s_waitcnt lgkmcnt(4)
	v_mfma_f32_32x32x16_bf16 v[32:47], v[72:75], v[64:67], v[32:47]
	v_cvt_pk_bf16_f32 v10, v111, v116
	v_cvt_pk_bf16_f32 v11, v117, v118
	v_cvt_pk_bf16_f32 v12, v107, v108
	v_cvt_pk_bf16_f32 v13, v109, v110
	v_max3_f32 v98, v98, v179, v180
	v_max3_f32 v98, v98, v181, v14
	v_add_f32_e32 v97, v97, v119
	v_add_f32_e32 v97, v97, v120
	v_add_f32_e32 v97, v97, v121
	v_add_f32_e32 v97, v97, v122
	s_waitcnt lgkmcnt(3)
	v_mfma_f32_32x32x16_bf16 v[16:31], v[76:79], v[10:13], v[16:31]
	v_max3_f32 v98, v98, v15, v132
	v_max3_f32 v98, v98, v133, v134
	v_add_f32_e32 v97, v97, v111
	v_add_f32_e32 v97, v97, v116
	v_add_f32_e32 v97, v97, v117
	v_add_f32_e32 v97, v97, v118
	s_waitcnt lgkmcnt(2)
	v_mfma_f32_32x32x16_bf16 v[32:47], v[80:83], v[10:13], v[32:47]
	v_cvt_pk_bf16_f32 v64, v103, v104
	v_cvt_pk_bf16_f32 v65, v105, v106
	v_cvt_pk_bf16_f32 v66, v1, v100
	v_cvt_pk_bf16_f32 v67, v101, v102
	v_max3_f32 v98, v98, v135, v136
	v_max3_f32 v98, v98, v137, v138
	v_add_f32_e32 v97, v97, v107
	v_add_f32_e32 v97, v97, v108
	v_add_f32_e32 v97, v97, v109
	v_add_f32_e32 v97, v97, v110
	s_waitcnt lgkmcnt(1)
	v_mfma_f32_32x32x16_bf16 v[16:31], v[84:87], v[64:67], v[16:31]
	v_max3_f32 v98, v98, v139, v142
	v_max3_f32 v98, v98, v143, v144
	v_add_f32_e32 v97, v97, v103
	v_add_f32_e32 v97, v97, v104
	v_add_f32_e32 v97, v97, v105
	v_add_f32_e32 v97, v97, v106
	s_waitcnt lgkmcnt(0)
	v_mfma_f32_32x32x16_bf16 v[32:47], v[88:91], v[64:67], v[32:47]
	v_max3_f32 v98, v98, v145, v150
	v_max3_f32 v98, v98, v151, v151
	v_add_f32_e32 v97, v97, v1
	v_add_f32_e32 v97, v97, v100
	v_add_f32_e32 v97, v97, v101
	v_add_f32_e32 v97, v97, v102
	s_setprio 0
	ds_read_b128 v[124:127], v201 offset:9248
	ds_read_b128 v[120:123], v201 offset:13856
	ds_read_b128 v[74:77], v201 offset:9280
	ds_read_b128 v[66:69], v201 offset:9312
	ds_read_b128 v[70:73], v201 offset:13888
	ds_read_b128 v[10:13], v201 offset:13920
	v_add_f32_e32 v64, v96, v97
	v_mov_b32_e32 v1, v98
	s_nop 1
	v_permlane32_swap_b32_e32 v98, v1
	v_max_f32_e32 v1, v1, v1
	v_max_f32_e32 v65, v98, v98
	v_max_f32_e32 v1, v65, v1
	v_cmp_lt_f32_e32 vcc, s52, v1
	s_cbranch_vccz .LBB0_703
	v_max_f32_e32 v1, v1, v1
	v_max_f32_e32 v82, 0, v1
	v_add_f32_e32 v195, v195, v82
	v_xor_b32_e32 v48, 0x80000000, v195
	v_pk_add_f32 v[112:113], v[112:113], v[82:83] op_sel_hi:[1,0] neg_lo:[0,1] neg_hi:[0,1]
	v_pk_add_f32 v[14:15], v[14:15], v[82:83] op_sel_hi:[1,0] neg_lo:[0,1] neg_hi:[0,1]
	v_pk_add_f32 v[114:115], v[114:115], v[82:83] op_sel_hi:[1,0] neg_lo:[0,1] neg_hi:[0,1]
	v_pk_add_f32 v[132:133], v[132:133], v[82:83] op_sel_hi:[1,0] neg_lo:[0,1] neg_hi:[0,1]
	v_pk_add_f32 v[140:141], v[140:141], v[82:83] op_sel_hi:[1,0] neg_lo:[0,1] neg_hi:[0,1]
	v_pk_add_f32 v[134:135], v[134:135], v[82:83] op_sel_hi:[1,0] neg_lo:[0,1] neg_hi:[0,1]
	v_pk_add_f32 v[146:147], v[146:147], v[82:83] op_sel_hi:[1,0] neg_lo:[0,1] neg_hi:[0,1]
	v_pk_add_f32 v[136:137], v[136:137], v[82:83] op_sel_hi:[1,0] neg_lo:[0,1] neg_hi:[0,1]
	v_pk_add_f32 v[148:149], v[148:149], v[82:83] op_sel_hi:[1,0] neg_lo:[0,1] neg_hi:[0,1]
	v_pk_add_f32 v[138:139], v[138:139], v[82:83] op_sel_hi:[1,0] neg_lo:[0,1] neg_hi:[0,1]
	v_pk_add_f32 v[176:177], v[176:177], v[82:83] op_sel_hi:[1,0] neg_lo:[0,1] neg_hi:[0,1]
	v_pk_add_f32 v[142:143], v[142:143], v[82:83] op_sel_hi:[1,0] neg_lo:[0,1] neg_hi:[0,1]
	v_pk_add_f32 v[178:179], v[178:179], v[82:83] op_sel_hi:[1,0] neg_lo:[0,1] neg_hi:[0,1]
	v_pk_add_f32 v[144:145], v[144:145], v[82:83] op_sel_hi:[1,0] neg_lo:[0,1] neg_hi:[0,1]
	v_pk_add_f32 v[180:181], v[180:181], v[82:83] op_sel_hi:[1,0] neg_lo:[0,1] neg_hi:[0,1]
	v_pk_add_f32 v[150:151], v[150:151], v[82:83] op_sel_hi:[1,0] neg_lo:[0,1] neg_hi:[0,1]
	v_exp_f32_e64 v82, -v82
	v_mov_b32_e32 v49, v48
	v_mov_b32_e32 v50, v48
	v_mov_b32_e32 v51, v48
	v_mov_b32_e32 v52, v48
	v_mov_b32_e32 v53, v48
	v_mov_b32_e32 v54, v48
	v_mov_b32_e32 v55, v48
	v_mov_b32_e32 v56, v48
	v_mov_b32_e32 v57, v48
	v_mov_b32_e32 v58, v48
	v_mov_b32_e32 v59, v48
	v_mov_b32_e32 v60, v48
	v_mov_b32_e32 v61, v48
	v_mov_b32_e32 v62, v48
	v_mov_b32_e32 v63, v48
	s_nop 11
	v_pk_mul_f32 v[30:31], v[30:31], v[82:83] op_sel_hi:[1,0]
	v_pk_mul_f32 v[28:29], v[28:29], v[82:83] op_sel_hi:[1,0]
	v_pk_mul_f32 v[26:27], v[26:27], v[82:83] op_sel_hi:[1,0]
	v_pk_mul_f32 v[24:25], v[24:25], v[82:83] op_sel_hi:[1,0]
	v_pk_mul_f32 v[22:23], v[22:23], v[82:83] op_sel_hi:[1,0]
	v_pk_mul_f32 v[20:21], v[20:21], v[82:83] op_sel_hi:[1,0]
	v_pk_mul_f32 v[18:19], v[18:19], v[82:83] op_sel_hi:[1,0]
	v_pk_mul_f32 v[16:17], v[16:17], v[82:83] op_sel_hi:[1,0]
	v_pk_mul_f32 v[46:47], v[46:47], v[82:83] op_sel_hi:[1,0]
	v_pk_mul_f32 v[44:45], v[44:45], v[82:83] op_sel_hi:[1,0]
	v_pk_mul_f32 v[42:43], v[42:43], v[82:83] op_sel_hi:[1,0]
	v_pk_mul_f32 v[40:41], v[40:41], v[82:83] op_sel_hi:[1,0]
	v_pk_mul_f32 v[38:39], v[38:39], v[82:83] op_sel_hi:[1,0]
	v_pk_mul_f32 v[36:37], v[36:37], v[82:83] op_sel_hi:[1,0]
	v_pk_mul_f32 v[34:35], v[34:35], v[82:83] op_sel_hi:[1,0]
	v_pk_mul_f32 v[32:33], v[32:33], v[82:83] op_sel_hi:[1,0]
	v_mul_f32_e32 v64, v64, v82
